# GEMM K-loops: dropped the redundant lgkmcnt(0) wait after each phase barrier and fused the vmcnt+lgkmcnt waits before it (40 sites)
# speedup vs baseline: 1.0060x; 1.0060x over previous
; #define PG8_STAGE(bufoff, gbase, voff) do { _Pragma("unroll") for (int _i = 0; _i < 2; ++_i) \
;         __builtin_amdgcn_global_load_lds((const unsigned*)((const char*)(gbase) + (voff)[_i]), (LAS unsigned*)(lds + (bufoff) + ldsw + _i * 8192), 16, 0, 0); } while (0)
; #define PG8_LDA(dst, b, h) do { _Pragma("unroll") for (int m = 0; m < 4; ++m) _Pragma("unroll") for (int k = 0; k < 2; ++k) dst[m][k] = *(const LAS bf16x8*)(lds + PG8_SA(b, h) + aoff + m * 2048 + k * 1024); } while (0)
; #define PG8_LDB(dst, b, h) do { _Pragma("unroll") for (int n = 0; n < 2; ++n) _Pragma("unroll") for (int k = 0; k < 2; ++k) dst[n][k] = *(const LAS bf16x8*)(lds + PG8_SB(b, h) + boff + n * 2048 + k * 1024); } while (0)
; #define PG8_WAIT_V(n) asm volatile("s_waitcnt vmcnt(" #n ")" ::: "memory")
; template <class Epi, class Sched, bool ALIGN_EPI = true, bool SP2 = true>
; __device__ __forceinline__ void gemm_phase(LAS unsigned char* lds, const Gemm g, const Sched& S, const Epi& E) {
;     ...
;         for (int t = 0; t < nt; t += 2) {
;             const bool last = (t == nt - 2);
;             const char* a1 = cA + (size_t)(t + 1) * kstep;
;             const char* a2 = last ? nA : cA + (size_t)(t + 2) * kstep; const char* b2 = last ? nB : cB + (size_t)(t + 2) * kstep;
;             const char* a3 = a2 + kstep; const char* b3 = b2 + kstep;
;             if constexpr (SP2) {
;             PG8_LDB(B0, 0, 0); PG8_LDB(B1, 0, 1); PG8_SCHED; PG8_LDA(At, 0, 0); PG8_STAGE(PG8_SA(1, 1), a1 + hstep, voffA);
;             PG8_WAIT_V(8); PG8_WAIT_L(0); PG8_BAR; PG8_MMA(0, 0, At, B0); PG8_MMA(0, 1, At, B1); PG8_BAR; PG8_SCHED;
;             PG8_LDA(At, 0, 1); PG8_STAGE(PG8_SB(0, 0), b2, voffB); PG8_STAGE(PG8_SB(0, 1), b2 + hstep, voffB); PG8_STAGE(PG8_SA(0, 0), a2, voffA);
;             PG8_WAIT_V(8); PG8_WAIT_L(0); PG8_BAR; PG8_MMA(1, 0, At, B0); PG8_MMA(1, 1, At, B1); PG8_BAR; PG8_SCHED;
;             PG8_LDB(B0, 1, 0); PG8_LDB(B1, 1, 1); PG8_SCHED; PG8_LDA(At, 1, 0); PG8_STAGE(PG8_SA(0, 1), a2 + hstep, voffA);
;             PG8_WAIT_V(8); PG8_WAIT_L(0); PG8_BAR; PG8_MMA(0, 0, At, B0); PG8_MMA(0, 1, At, B1); PG8_BAR; PG8_SCHED;
;             PG8_LDA(At, 1, 1); PG8_STAGE(PG8_SB(1, 0), b3, voffB); PG8_STAGE(PG8_SB(1, 1), b3 + hstep, voffB); PG8_STAGE(PG8_SA(1, 0), a3, voffA);
;             PG8_WAIT_V(8); PG8_WAIT_L(0); PG8_BAR; PG8_MMA(1, 0, At, B0); PG8_MMA(1, 1, At, B1); PG8_BAR; PG8_SCHED;
.Lprio_skip_40:
.LBB0_40:
	s_add_u32 s24, s90, 0xfffe0080
	s_addc_u32 s25, s91, -1
	s_add_i32 s46, 0, 0x10000
	s_cmp_eq_u32 vcc_hi, 4
	s_cselect_b32 s83, s2, s25
	s_cselect_b32 s82, s3, s24
	v_add_u32_e32 v142, s46, v145
	s_cselect_b32 s25, s45, vcc_lo
	s_cselect_b32 s24, s53, s55
	s_add_i32 s48, 0, 0x14000
	ds_read_b128 v[138:141], v142
	ds_read_b128 v[148:151], v142 offset:1024
	ds_read_b128 v[152:155], v142 offset:2048
	ds_read_b128 v[156:159], v142 offset:3072
	v_add_u32_e32 v142, s48, v145
	ds_read_b128 v[170:173], v142
	ds_read_b128 v[174:177], v142 offset:1024
	ds_read_b128 v[178:181], v142 offset:2048
	ds_read_b128 v[182:185], v142 offset:3072
	s_add_i32 m0, s67, 0xc000
	ds_read_b128 v[186:189], v147
	ds_read_b128 v[190:193], v147 offset:1024
	ds_read_b128 v[194:197], v147 offset:2048
	ds_read_b128 v[198:201], v147 offset:3072
	ds_read_b128 v[202:205], v147 offset:4096
	ds_read_b128 v[206:209], v147 offset:5120
	ds_read_b128 v[210:213], v147 offset:6144
	ds_read_b128 v[214:217], v147 offset:7168
	global_load_lds_dwordx4 v134, s[90:91]
	s_add_i32 m0, s67, 0xe000
	s_nop 0
	global_load_lds_dwordx4 v136, s[90:91]
	s_waitcnt vmcnt(8) lgkmcnt(0)
	s_barrier
	v_mfma_f32_16x16x32_bf16 v[124:127], v[138:141], v[186:189], v[124:127]
	v_mfma_f32_16x16x32_bf16 v[120:123], v[152:155], v[186:189], v[120:123]
	v_mfma_f32_16x16x32_bf16 v[108:111], v[138:141], v[194:197], v[108:111]
	v_mfma_f32_16x16x32_bf16 v[104:107], v[152:155], v[194:197], v[104:107]
	v_mfma_f32_16x16x32_bf16 v[92:95], v[138:141], v[202:205], v[92:95]
	v_mfma_f32_16x16x32_bf16 v[88:91], v[152:155], v[202:205], v[88:91]
	v_mfma_f32_16x16x32_bf16 v[76:79], v[138:141], v[210:213], v[76:79]
	v_mfma_f32_16x16x32_bf16 v[72:75], v[152:155], v[210:213], v[72:75]
	v_mfma_f32_16x16x32_bf16 v[124:127], v[148:151], v[190:193], v[124:127]
	v_mfma_f32_16x16x32_bf16 v[120:123], v[156:159], v[190:193], v[120:123]
	v_mfma_f32_16x16x32_bf16 v[108:111], v[148:151], v[198:201], v[108:111]
	v_mfma_f32_16x16x32_bf16 v[104:107], v[156:159], v[198:201], v[104:107]
	v_mfma_f32_16x16x32_bf16 v[92:95], v[148:151], v[206:209], v[92:95]
	v_mfma_f32_16x16x32_bf16 v[88:91], v[156:159], v[206:209], v[88:91]
	v_mfma_f32_16x16x32_bf16 v[76:79], v[148:151], v[214:217], v[76:79]
	v_mfma_f32_16x16x32_bf16 v[72:75], v[156:159], v[214:217], v[72:75]
	v_mfma_f32_16x16x32_bf16 v[116:119], v[170:173], v[186:189], v[116:119]
	v_mfma_f32_16x16x32_bf16 v[112:115], v[178:181], v[186:189], v[112:115]
	v_mfma_f32_16x16x32_bf16 v[100:103], v[170:173], v[194:197], v[100:103]
	v_mfma_f32_16x16x32_bf16 v[96:99], v[178:181], v[194:197], v[96:99]
	v_mfma_f32_16x16x32_bf16 v[84:87], v[170:173], v[202:205], v[84:87]
	v_mfma_f32_16x16x32_bf16 v[80:83], v[178:181], v[202:205], v[80:83]
	v_mfma_f32_16x16x32_bf16 v[68:71], v[170:173], v[210:213], v[68:71]
	v_mfma_f32_16x16x32_bf16 v[64:67], v[178:181], v[210:213], v[64:67]
	v_mfma_f32_16x16x32_bf16 v[116:119], v[174:177], v[190:193], v[116:119]
	v_mfma_f32_16x16x32_bf16 v[112:115], v[182:185], v[190:193], v[112:115]
	v_mfma_f32_16x16x32_bf16 v[100:103], v[174:177], v[198:201], v[100:103]
	v_mfma_f32_16x16x32_bf16 v[96:99], v[182:185], v[198:201], v[96:99]
	v_mfma_f32_16x16x32_bf16 v[84:87], v[174:177], v[206:209], v[84:87]
	v_mfma_f32_16x16x32_bf16 v[80:83], v[182:185], v[206:209], v[80:83]
	v_mfma_f32_16x16x32_bf16 v[68:71], v[174:177], v[214:217], v[68:71]
	v_mfma_f32_16x16x32_bf16 v[64:67], v[182:185], v[214:217], v[64:67]
	s_barrier
	s_add_i32 s46, s46, s93
	s_mov_b32 m0, s46
	ds_read_b128 v[186:189], v147 offset:16384
	ds_read_b128 v[190:193], v147 offset:17408
	ds_read_b128 v[194:197], v147 offset:18432
	ds_read_b128 v[198:201], v147 offset:19456
	ds_read_b128 v[202:205], v147 offset:20480
	ds_read_b128 v[206:209], v147 offset:21504
	ds_read_b128 v[210:213], v147 offset:22528
	ds_read_b128 v[214:217], v147 offset:23552
	global_load_lds_dwordx4 v160, s[24:25]
	s_add_i32 m0, s46, 0x2000
	s_add_u32 s46, s24, 0x20000
	s_addc_u32 s47, s25, 0
	s_add_i32 s48, s48, s93
	global_load_lds_dwordx4 v132, s[24:25]
	s_mov_b32 m0, s48
	s_nop 0
	global_load_lds_dwordx4 v160, s[46:47]
	s_add_i32 m0, s48, 0x2000
	s_nop 0
	global_load_lds_dwordx4 v132, s[46:47]
	s_mov_b32 m0, s67
	s_nop 0
	global_load_lds_dwordx4 v128, s[82:83]
	s_mov_b32 m0, s73
	s_nop 0
	global_load_lds_dwordx4 v130, s[82:83]
	s_waitcnt vmcnt(8) lgkmcnt(0)
	s_barrier
	v_mfma_f32_16x16x32_bf16 v[60:63], v[138:141], v[186:189], v[60:63]
	v_mfma_f32_16x16x32_bf16 v[56:59], v[152:155], v[186:189], v[56:59]
	v_mfma_f32_16x16x32_bf16 v[44:47], v[138:141], v[194:197], v[44:47]
	v_mfma_f32_16x16x32_bf16 v[40:43], v[152:155], v[194:197], v[40:43]
	v_mfma_f32_16x16x32_bf16 v[28:31], v[138:141], v[202:205], v[28:31]
	v_mfma_f32_16x16x32_bf16 v[24:27], v[152:155], v[202:205], v[24:27]
	v_mfma_f32_16x16x32_bf16 v[12:15], v[138:141], v[210:213], v[12:15]
	v_mfma_f32_16x16x32_bf16 v[8:11], v[152:155], v[210:213], v[8:11]
	v_mfma_f32_16x16x32_bf16 v[60:63], v[148:151], v[190:193], v[60:63]
	v_mfma_f32_16x16x32_bf16 v[56:59], v[156:159], v[190:193], v[56:59]
	v_mfma_f32_16x16x32_bf16 v[44:47], v[148:151], v[198:201], v[44:47]
	v_mfma_f32_16x16x32_bf16 v[40:43], v[156:159], v[198:201], v[40:43]
	v_mfma_f32_16x16x32_bf16 v[28:31], v[148:151], v[206:209], v[28:31]
	v_mfma_f32_16x16x32_bf16 v[24:27], v[156:159], v[206:209], v[24:27]
	v_mfma_f32_16x16x32_bf16 v[12:15], v[148:151], v[214:217], v[12:15]
	v_mfma_f32_16x16x32_bf16 v[8:11], v[156:159], v[214:217], v[8:11]
	v_mfma_f32_16x16x32_bf16 v[52:55], v[170:173], v[186:189], v[52:55]
	v_mfma_f32_16x16x32_bf16 v[48:51], v[178:181], v[186:189], v[48:51]
	v_mfma_f32_16x16x32_bf16 v[36:39], v[170:173], v[194:197], v[36:39]
	v_mfma_f32_16x16x32_bf16 v[32:35], v[178:181], v[194:197], v[32:35]
	v_mfma_f32_16x16x32_bf16 v[20:23], v[170:173], v[202:205], v[20:23]
	v_mfma_f32_16x16x32_bf16 v[16:19], v[178:181], v[202:205], v[16:19]
	v_mfma_f32_16x16x32_bf16 v[4:7], v[170:173], v[210:213], v[4:7]
	v_mfma_f32_16x16x32_bf16 v[0:3], v[178:181], v[210:213], v[0:3]
	v_mfma_f32_16x16x32_bf16 v[52:55], v[174:177], v[190:193], v[52:55]
	v_mfma_f32_16x16x32_bf16 v[48:51], v[182:185], v[190:193], v[48:51]
	v_mfma_f32_16x16x32_bf16 v[36:39], v[174:177], v[198:201], v[36:39]
	v_mfma_f32_16x16x32_bf16 v[32:35], v[182:185], v[198:201], v[32:35]
	v_mfma_f32_16x16x32_bf16 v[20:23], v[174:177], v[206:209], v[20:23]
	v_mfma_f32_16x16x32_bf16 v[16:19], v[182:185], v[206:209], v[16:19]
	v_mfma_f32_16x16x32_bf16 v[4:7], v[174:177], v[214:217], v[4:7]
	v_mfma_f32_16x16x32_bf16 v[0:3], v[182:185], v[214:217], v[0:3]
	s_barrier
; #define PG8_STAGE(bufoff, gbase, voff) do { _Pragma("unroll") for (int _i = 0; _i < 2; ++_i) \
;         __builtin_amdgcn_global_load_lds((const unsigned*)((const char*)(gbase) + (voff)[_i]), (LAS unsigned*)(lds + (bufoff) + ldsw + _i * 8192), 16, 0, 0); } while (0)
; #define PG8_LDA(dst, b, h) do { _Pragma("unroll") for (int m = 0; m < 4; ++m) _Pragma("unroll") for (int k = 0; k < 2; ++k) dst[m][k] = *(const LAS bf16x8*)(lds + PG8_SA(b, h) + aoff + m * 2048 + k * 1024); } while (0)
; #define PG8_LDB(dst, b, h) do { _Pragma("unroll") for (int n = 0; n < 2; ++n) _Pragma("unroll") for (int k = 0; k < 2; ++k) dst[n][k] = *(const LAS bf16x8*)(lds + PG8_SB(b, h) + boff + n * 2048 + k * 1024); } while (0)
; #define PG8_WAIT_V(n) asm volatile("s_waitcnt vmcnt(" #n ")" ::: "memory")
; template <class Epi, class Sched, bool ALIGN_EPI = true, bool SP2 = true>
; __device__ __forceinline__ void gemm_phase(LAS unsigned char* lds, const Gemm g, const Sched& S, const Epi& E) {
;     ...
;         for (int t = 0; t < nt; t += 2) {
;             const bool last = (t == nt - 2);
;             const char* a1 = cA + (size_t)(t + 1) * kstep;
;             const char* a2 = last ? nA : cA + (size_t)(t + 2) * kstep; const char* b2 = last ? nB : cB + (size_t)(t + 2) * kstep;
;             const char* a3 = a2 + kstep; const char* b3 = b2 + kstep;
;             if constexpr (SP2) {
;             PG8_LDB(B0, 0, 0); PG8_LDB(B1, 0, 1); PG8_SCHED; PG8_LDA(At, 0, 0); PG8_STAGE(PG8_SA(1, 1), a1 + hstep, voffA);
;             PG8_WAIT_V(8); PG8_WAIT_L(0); PG8_BAR; PG8_MMA(0, 0, At, B0); PG8_MMA(0, 1, At, B1); PG8_BAR; PG8_SCHED;
;             PG8_LDA(At, 0, 1); PG8_STAGE(PG8_SB(0, 0), b2, voffB); PG8_STAGE(PG8_SB(0, 1), b2 + hstep, voffB); PG8_STAGE(PG8_SA(0, 0), a2, voffA);
;             PG8_WAIT_V(8); PG8_WAIT_L(0); PG8_BAR; PG8_MMA(1, 0, At, B0); PG8_MMA(1, 1, At, B1); PG8_BAR; PG8_SCHED;
;             PG8_LDB(B0, 1, 0); PG8_LDB(B1, 1, 1); PG8_SCHED; PG8_LDA(At, 1, 0); PG8_STAGE(PG8_SA(0, 1), a2 + hstep, voffA);
;             PG8_WAIT_V(8); PG8_WAIT_L(0); PG8_BAR; PG8_MMA(0, 0, At, B0); PG8_MMA(0, 1, At, B1); PG8_BAR; PG8_SCHED;
;             PG8_LDA(At, 1, 1); PG8_STAGE(PG8_SB(1, 0), b3, voffB); PG8_STAGE(PG8_SB(1, 1), b3 + hstep, voffB); PG8_STAGE(PG8_SA(1, 0), a3, voffA);
;             PG8_WAIT_V(8); PG8_WAIT_L(0); PG8_BAR; PG8_MMA(1, 0, At, B0); PG8_MMA(1, 1, At, B1); PG8_BAR; PG8_SCHED;
	s_add_i32 s48, 0, 0x18000
	s_add_i32 s49, 0, 0x1c000
	v_add_u32_e32 v156, s48, v145
	v_add_u32_e32 v182, s49, v145
	ds_read_b128 v[138:141], v156
	ds_read_b128 v[148:151], v156 offset:1024
	ds_read_b128 v[152:155], v156 offset:2048
	ds_read_b128 v[156:159], v156 offset:3072
	ds_read_b128 v[170:173], v182
	ds_read_b128 v[174:177], v182 offset:1024
	ds_read_b128 v[178:181], v182 offset:2048
	ds_read_b128 v[182:185], v182 offset:3072
	s_add_u32 s46, s82, 0x20000
	s_addc_u32 s47, s83, 0
	s_mov_b32 m0, s94
	ds_read_b128 v[186:189], v147 offset:32768
	ds_read_b128 v[190:193], v147 offset:33792
	ds_read_b128 v[194:197], v147 offset:34816
	ds_read_b128 v[198:201], v147 offset:35840
	ds_read_b128 v[202:205], v147 offset:36864
	ds_read_b128 v[206:209], v147 offset:37888
	ds_read_b128 v[210:213], v147 offset:38912
	ds_read_b128 v[214:217], v147 offset:39936
	global_load_lds_dwordx4 v128, s[46:47]
	s_mov_b32 m0, s95
	s_nop 0
	global_load_lds_dwordx4 v130, s[46:47]
	s_waitcnt vmcnt(8) lgkmcnt(0)
	s_barrier
	v_mfma_f32_16x16x32_bf16 v[124:127], v[138:141], v[186:189], v[124:127]
	v_mfma_f32_16x16x32_bf16 v[120:123], v[152:155], v[186:189], v[120:123]
	v_mfma_f32_16x16x32_bf16 v[108:111], v[138:141], v[194:197], v[108:111]
	v_mfma_f32_16x16x32_bf16 v[104:107], v[152:155], v[194:197], v[104:107]
	v_mfma_f32_16x16x32_bf16 v[92:95], v[138:141], v[202:205], v[92:95]
	v_mfma_f32_16x16x32_bf16 v[88:91], v[152:155], v[202:205], v[88:91]
	v_mfma_f32_16x16x32_bf16 v[76:79], v[138:141], v[210:213], v[76:79]
	v_mfma_f32_16x16x32_bf16 v[72:75], v[152:155], v[210:213], v[72:75]
	v_mfma_f32_16x16x32_bf16 v[124:127], v[148:151], v[190:193], v[124:127]
	v_mfma_f32_16x16x32_bf16 v[120:123], v[156:159], v[190:193], v[120:123]
	v_mfma_f32_16x16x32_bf16 v[108:111], v[148:151], v[198:201], v[108:111]
	v_mfma_f32_16x16x32_bf16 v[104:107], v[156:159], v[198:201], v[104:107]
	v_mfma_f32_16x16x32_bf16 v[92:95], v[148:151], v[206:209], v[92:95]
	v_mfma_f32_16x16x32_bf16 v[88:91], v[156:159], v[206:209], v[88:91]
	v_mfma_f32_16x16x32_bf16 v[76:79], v[148:151], v[214:217], v[76:79]
	v_mfma_f32_16x16x32_bf16 v[72:75], v[156:159], v[214:217], v[72:75]
	v_mfma_f32_16x16x32_bf16 v[116:119], v[170:173], v[186:189], v[116:119]
	v_mfma_f32_16x16x32_bf16 v[112:115], v[178:181], v[186:189], v[112:115]
	v_mfma_f32_16x16x32_bf16 v[100:103], v[170:173], v[194:197], v[100:103]
	v_mfma_f32_16x16x32_bf16 v[96:99], v[178:181], v[194:197], v[96:99]
	v_mfma_f32_16x16x32_bf16 v[84:87], v[170:173], v[202:205], v[84:87]
	v_mfma_f32_16x16x32_bf16 v[80:83], v[178:181], v[202:205], v[80:83]
	v_mfma_f32_16x16x32_bf16 v[68:71], v[170:173], v[210:213], v[68:71]
	v_mfma_f32_16x16x32_bf16 v[64:67], v[178:181], v[210:213], v[64:67]
	v_mfma_f32_16x16x32_bf16 v[116:119], v[174:177], v[190:193], v[116:119]
	v_mfma_f32_16x16x32_bf16 v[112:115], v[182:185], v[190:193], v[112:115]
	v_mfma_f32_16x16x32_bf16 v[100:103], v[174:177], v[198:201], v[100:103]
	v_mfma_f32_16x16x32_bf16 v[96:99], v[182:185], v[198:201], v[96:99]
	v_mfma_f32_16x16x32_bf16 v[84:87], v[174:177], v[206:209], v[84:87]
	v_mfma_f32_16x16x32_bf16 v[80:83], v[182:185], v[206:209], v[80:83]
	v_mfma_f32_16x16x32_bf16 v[68:71], v[174:177], v[214:217], v[68:71]
	v_mfma_f32_16x16x32_bf16 v[64:67], v[182:185], v[214:217], v[64:67]
	s_barrier
	s_add_i32 s46, s48, s93
	s_mov_b32 m0, s46
	ds_read_b128 v[186:189], v147 offset:49152
	ds_read_b128 v[190:193], v147 offset:50176
	ds_read_b128 v[194:197], v147 offset:51200
	ds_read_b128 v[198:201], v147 offset:52224
	ds_read_b128 v[202:205], v147 offset:53248
	ds_read_b128 v[206:209], v147 offset:54272
	ds_read_b128 v[210:213], v147 offset:55296
	ds_read_b128 v[214:217], v147 offset:56320
	s_add_u32 s98, s24, 0x80
	s_addc_u32 s99, s25, 0
	global_load_lds_dwordx4 v160, s[98:99]
	s_add_i32 m0, s46, 0x2000
	s_add_u32 s24, s24, 0x20080
	s_addc_u32 s25, s25, 0
	s_add_i32 s46, s49, s93
	global_load_lds_dwordx4 v132, s[98:99]
	s_mov_b32 m0, s46
	s_nop 0
	global_load_lds_dwordx4 v160, s[24:25]
	s_add_i32 m0, s46, 0x2000
	s_nop 0
	global_load_lds_dwordx4 v132, s[24:25]
	s_mov_b32 m0, s96
	s_nop 0
	s_add_u32 s98, s82, 0x80
	s_addc_u32 s99, s83, 0
	global_load_lds_dwordx4 v128, s[98:99]
	s_mov_b32 m0, s97
	s_nop 0
	global_load_lds_dwordx4 v130, s[98:99]
	s_waitcnt vmcnt(8) lgkmcnt(0)
	s_barrier
	v_mfma_f32_16x16x32_bf16 v[60:63], v[138:141], v[186:189], v[60:63]
	v_mfma_f32_16x16x32_bf16 v[56:59], v[152:155], v[186:189], v[56:59]
	v_mfma_f32_16x16x32_bf16 v[44:47], v[138:141], v[194:197], v[44:47]
	v_mfma_f32_16x16x32_bf16 v[40:43], v[152:155], v[194:197], v[40:43]
	v_mfma_f32_16x16x32_bf16 v[28:31], v[138:141], v[202:205], v[28:31]
	v_mfma_f32_16x16x32_bf16 v[24:27], v[152:155], v[202:205], v[24:27]
	v_mfma_f32_16x16x32_bf16 v[12:15], v[138:141], v[210:213], v[12:15]
	v_mfma_f32_16x16x32_bf16 v[8:11], v[152:155], v[210:213], v[8:11]
	v_mfma_f32_16x16x32_bf16 v[60:63], v[148:151], v[190:193], v[60:63]
	v_mfma_f32_16x16x32_bf16 v[56:59], v[156:159], v[190:193], v[56:59]
	v_mfma_f32_16x16x32_bf16 v[44:47], v[148:151], v[198:201], v[44:47]
	v_mfma_f32_16x16x32_bf16 v[40:43], v[156:159], v[198:201], v[40:43]
	v_mfma_f32_16x16x32_bf16 v[28:31], v[148:151], v[206:209], v[28:31]
	v_mfma_f32_16x16x32_bf16 v[24:27], v[156:159], v[206:209], v[24:27]
	v_mfma_f32_16x16x32_bf16 v[12:15], v[148:151], v[214:217], v[12:15]
	v_mfma_f32_16x16x32_bf16 v[8:11], v[156:159], v[214:217], v[8:11]
	v_mfma_f32_16x16x32_bf16 v[52:55], v[170:173], v[186:189], v[52:55]
	v_mfma_f32_16x16x32_bf16 v[48:51], v[178:181], v[186:189], v[48:51]
	v_mfma_f32_16x16x32_bf16 v[36:39], v[170:173], v[194:197], v[36:39]
	v_mfma_f32_16x16x32_bf16 v[32:35], v[178:181], v[194:197], v[32:35]
	v_mfma_f32_16x16x32_bf16 v[20:23], v[170:173], v[202:205], v[20:23]
	v_mfma_f32_16x16x32_bf16 v[16:19], v[178:181], v[202:205], v[16:19]
	v_mfma_f32_16x16x32_bf16 v[4:7], v[170:173], v[210:213], v[4:7]
	v_mfma_f32_16x16x32_bf16 v[0:3], v[178:181], v[210:213], v[0:3]
	v_mfma_f32_16x16x32_bf16 v[52:55], v[174:177], v[190:193], v[52:55]
	v_mfma_f32_16x16x32_bf16 v[48:51], v[182:185], v[190:193], v[48:51]
	v_mfma_f32_16x16x32_bf16 v[36:39], v[174:177], v[198:201], v[36:39]
	v_mfma_f32_16x16x32_bf16 v[32:35], v[182:185], v[198:201], v[32:35]
	v_mfma_f32_16x16x32_bf16 v[20:23], v[174:177], v[206:209], v[20:23]
	v_mfma_f32_16x16x32_bf16 v[16:19], v[182:185], v[206:209], v[16:19]
	v_mfma_f32_16x16x32_bf16 v[4:7], v[174:177], v[214:217], v[4:7]
	v_mfma_f32_16x16x32_bf16 v[0:3], v[182:185], v[214:217], v[0:3]
	s_barrier
	s_add_i32 vcc_hi, vcc_hi, 2
	s_add_u32 s90, s90, 0x100
	s_addc_u32 s91, s91, 0
	s_add_u32 s55, s55, 0x100
	s_addc_u32 vcc_lo, vcc_lo, 0
	s_cmp_gt_u32 vcc_hi, 5
	s_cbranch_scc0 .LBB0_40
	s_setprio 0
	s_and_b64 vcc, exec, s[30:31]
	s_cbranch_vccz .LBB0_43
	s_barrier

; #define PG8_STAGE(bufoff, gbase, voff) do { _Pragma("unroll") for (int _i = 0; _i < 2; ++_i) \
;         __builtin_amdgcn_global_load_lds((const unsigned*)((const char*)(gbase) + (voff)[_i]), (LAS unsigned*)(lds + (bufoff) + ldsw + _i * 8192), 16, 0, 0); } while (0)
; #define PG8_LDA(dst, b, h) do { _Pragma("unroll") for (int m = 0; m < 4; ++m) _Pragma("unroll") for (int k = 0; k < 2; ++k) dst[m][k] = *(const LAS bf16x8*)(lds + PG8_SA(b, h) + aoff + m * 2048 + k * 1024); } while (0)
; #define PG8_LDB(dst, b, h) do { _Pragma("unroll") for (int n = 0; n < 2; ++n) _Pragma("unroll") for (int k = 0; k < 2; ++k) dst[n][k] = *(const LAS bf16x8*)(lds + PG8_SB(b, h) + boff + n * 2048 + k * 1024); } while (0)
; #define PG8_WAIT_V(n) asm volatile("s_waitcnt vmcnt(" #n ")" ::: "memory")
; template <class Epi, class Sched, bool ALIGN_EPI = true, bool SP2 = true>
; __device__ __forceinline__ void gemm_phase(LAS unsigned char* lds, const Gemm g, const Sched& S, const Epi& E) {
;     ...
;         for (int t = 0; t < nt; t += 2) {
;             const bool last = (t == nt - 2);
;             const char* a1 = cA + (size_t)(t + 1) * kstep;
;             const char* a2 = last ? nA : cA + (size_t)(t + 2) * kstep; const char* b2 = last ? nB : cB + (size_t)(t + 2) * kstep;
;             const char* a3 = a2 + kstep; const char* b3 = b2 + kstep;
;             if constexpr (SP2) {
;             PG8_LDB(B0, 0, 0); PG8_LDB(B1, 0, 1); PG8_SCHED; PG8_LDA(At, 0, 0); PG8_STAGE(PG8_SA(1, 1), a1 + hstep, voffA);
;             PG8_WAIT_V(8); PG8_WAIT_L(0); PG8_BAR; PG8_MMA(0, 0, At, B0); PG8_MMA(0, 1, At, B1); PG8_BAR; PG8_SCHED;
;             PG8_LDA(At, 0, 1); PG8_STAGE(PG8_SB(0, 0), b2, voffB); PG8_STAGE(PG8_SB(0, 1), b2 + hstep, voffB); PG8_STAGE(PG8_SA(0, 0), a2, voffA);
;             PG8_WAIT_V(8); PG8_WAIT_L(0); PG8_BAR; PG8_MMA(1, 0, At, B0); PG8_MMA(1, 1, At, B1); PG8_BAR; PG8_SCHED;
;             PG8_LDB(B0, 1, 0); PG8_LDB(B1, 1, 1); PG8_SCHED; PG8_LDA(At, 1, 0); PG8_STAGE(PG8_SA(0, 1), a2 + hstep, voffA);
;             PG8_WAIT_V(8); PG8_WAIT_L(0); PG8_BAR; PG8_MMA(0, 0, At, B0); PG8_MMA(0, 1, At, B1); PG8_BAR; PG8_SCHED;
;             PG8_LDA(At, 1, 1); PG8_STAGE(PG8_SB(1, 0), b3, voffB); PG8_STAGE(PG8_SB(1, 1), b3 + hstep, voffB); PG8_STAGE(PG8_SA(1, 0), a3, voffA);
;             PG8_WAIT_V(8); PG8_WAIT_L(0); PG8_BAR; PG8_MMA(1, 0, At, B0); PG8_MMA(1, 1, At, B1); PG8_BAR; PG8_SCHED;
.Lprio_skip_93:
.LBB0_93:
	s_add_u32 s24, s62, 0xfff80080
	s_addc_u32 s25, s63, -1
	s_add_i32 s46, 0, 0x10000
	s_cmp_eq_u32 s93, 28
	s_cselect_b32 s67, s2, s25
	s_cselect_b32 s66, s3, s24
	s_cselect_b32 s25, s19, s92
	s_cselect_b32 s24, s31, s91
	s_add_i32 s47, 0, 0x14000
	v_add_u32_e32 v154, s46, v143
	v_add_u32_e32 v158, s47, v143
	ds_read_b128 v[138:141], v154
	ds_read_b128 v[146:149], v154 offset:1024
	ds_read_b128 v[150:153], v154 offset:2048
	ds_read_b128 v[154:157], v154 offset:3072
	ds_read_b128 v[170:173], v158
	ds_read_b128 v[174:177], v158 offset:1024
	ds_read_b128 v[178:181], v158 offset:2048
	ds_read_b128 v[182:185], v158 offset:3072
	s_add_i32 m0, s44, 0xc000
	ds_read_b128 v[186:189], v145
	ds_read_b128 v[190:193], v145 offset:1024
	ds_read_b128 v[194:197], v145 offset:2048
	ds_read_b128 v[198:201], v145 offset:3072
	ds_read_b128 v[202:205], v145 offset:4096
	ds_read_b128 v[206:209], v145 offset:5120
	ds_read_b128 v[210:213], v145 offset:6144
	ds_read_b128 v[214:217], v145 offset:7168
	global_load_lds_dwordx4 v134, s[62:63]
	s_add_i32 m0, s44, 0xe000
	s_nop 0
	global_load_lds_dwordx4 v136, s[62:63]
	s_waitcnt vmcnt(8) lgkmcnt(0)
	s_barrier
	v_mfma_f32_16x16x32_bf16 v[124:127], v[138:141], v[186:189], v[124:127]
	v_mfma_f32_16x16x32_bf16 v[120:123], v[150:153], v[186:189], v[120:123]
	v_mfma_f32_16x16x32_bf16 v[108:111], v[138:141], v[194:197], v[108:111]
	v_mfma_f32_16x16x32_bf16 v[104:107], v[150:153], v[194:197], v[104:107]
	v_mfma_f32_16x16x32_bf16 v[92:95], v[138:141], v[202:205], v[92:95]
	v_mfma_f32_16x16x32_bf16 v[88:91], v[150:153], v[202:205], v[88:91]
	v_mfma_f32_16x16x32_bf16 v[76:79], v[138:141], v[210:213], v[76:79]
	v_mfma_f32_16x16x32_bf16 v[72:75], v[150:153], v[210:213], v[72:75]
	v_mfma_f32_16x16x32_bf16 v[124:127], v[146:149], v[190:193], v[124:127]
	v_mfma_f32_16x16x32_bf16 v[120:123], v[154:157], v[190:193], v[120:123]
	v_mfma_f32_16x16x32_bf16 v[108:111], v[146:149], v[198:201], v[108:111]
	v_mfma_f32_16x16x32_bf16 v[104:107], v[154:157], v[198:201], v[104:107]
	v_mfma_f32_16x16x32_bf16 v[92:95], v[146:149], v[206:209], v[92:95]
	v_mfma_f32_16x16x32_bf16 v[88:91], v[154:157], v[206:209], v[88:91]
	v_mfma_f32_16x16x32_bf16 v[76:79], v[146:149], v[214:217], v[76:79]
	v_mfma_f32_16x16x32_bf16 v[72:75], v[154:157], v[214:217], v[72:75]
	v_mfma_f32_16x16x32_bf16 v[116:119], v[170:173], v[186:189], v[116:119]
	v_mfma_f32_16x16x32_bf16 v[112:115], v[178:181], v[186:189], v[112:115]
	v_mfma_f32_16x16x32_bf16 v[100:103], v[170:173], v[194:197], v[100:103]
	v_mfma_f32_16x16x32_bf16 v[96:99], v[178:181], v[194:197], v[96:99]
	v_mfma_f32_16x16x32_bf16 v[84:87], v[170:173], v[202:205], v[84:87]
	v_mfma_f32_16x16x32_bf16 v[80:83], v[178:181], v[202:205], v[80:83]
	v_mfma_f32_16x16x32_bf16 v[68:71], v[170:173], v[210:213], v[68:71]
	v_mfma_f32_16x16x32_bf16 v[64:67], v[178:181], v[210:213], v[64:67]
	v_mfma_f32_16x16x32_bf16 v[116:119], v[174:177], v[190:193], v[116:119]
	v_mfma_f32_16x16x32_bf16 v[112:115], v[182:185], v[190:193], v[112:115]
	v_mfma_f32_16x16x32_bf16 v[100:103], v[174:177], v[198:201], v[100:103]
	v_mfma_f32_16x16x32_bf16 v[96:99], v[182:185], v[198:201], v[96:99]
	v_mfma_f32_16x16x32_bf16 v[84:87], v[174:177], v[206:209], v[84:87]
	v_mfma_f32_16x16x32_bf16 v[80:83], v[182:185], v[206:209], v[80:83]
	v_mfma_f32_16x16x32_bf16 v[68:71], v[174:177], v[214:217], v[68:71]
	v_mfma_f32_16x16x32_bf16 v[64:67], v[182:185], v[214:217], v[64:67]
	s_barrier
	s_add_i32 s46, s46, s43
	s_mov_b32 m0, s46
	ds_read_b128 v[186:189], v145 offset:16384
	ds_read_b128 v[190:193], v145 offset:17408
	ds_read_b128 v[194:197], v145 offset:18432
	ds_read_b128 v[198:201], v145 offset:19456
	ds_read_b128 v[202:205], v145 offset:20480
	ds_read_b128 v[206:209], v145 offset:21504
	ds_read_b128 v[210:213], v145 offset:22528
	ds_read_b128 v[214:217], v145 offset:23552
	global_load_lds_dwordx4 v160, s[24:25]
	s_add_i32 m0, s46, 0x2000
	s_add_u32 s94, s24, 0x80000
	s_addc_u32 s95, s25, 0
	s_add_i32 s46, s47, s43
	global_load_lds_dwordx4 v132, s[24:25]
	s_mov_b32 m0, s46
	s_nop 0
	global_load_lds_dwordx4 v160, s[94:95]
	s_add_i32 m0, s46, 0x2000
	s_nop 0
	global_load_lds_dwordx4 v132, s[94:95]
	s_mov_b32 m0, s44
	s_nop 0
	global_load_lds_dwordx4 v128, s[66:67]
	s_mov_b32 m0, s45
	s_nop 0
	global_load_lds_dwordx4 v130, s[66:67]
	s_waitcnt vmcnt(8) lgkmcnt(0)
	s_barrier
	v_mfma_f32_16x16x32_bf16 v[60:63], v[138:141], v[186:189], v[60:63]
	v_mfma_f32_16x16x32_bf16 v[56:59], v[150:153], v[186:189], v[56:59]
	v_mfma_f32_16x16x32_bf16 v[44:47], v[138:141], v[194:197], v[44:47]
	v_mfma_f32_16x16x32_bf16 v[40:43], v[150:153], v[194:197], v[40:43]
	v_mfma_f32_16x16x32_bf16 v[28:31], v[138:141], v[202:205], v[28:31]
	v_mfma_f32_16x16x32_bf16 v[24:27], v[150:153], v[202:205], v[24:27]
	v_mfma_f32_16x16x32_bf16 v[12:15], v[138:141], v[210:213], v[12:15]
	v_mfma_f32_16x16x32_bf16 v[8:11], v[150:153], v[210:213], v[8:11]
	v_mfma_f32_16x16x32_bf16 v[60:63], v[146:149], v[190:193], v[60:63]
	v_mfma_f32_16x16x32_bf16 v[56:59], v[154:157], v[190:193], v[56:59]
	v_mfma_f32_16x16x32_bf16 v[44:47], v[146:149], v[198:201], v[44:47]
	v_mfma_f32_16x16x32_bf16 v[40:43], v[154:157], v[198:201], v[40:43]
	v_mfma_f32_16x16x32_bf16 v[28:31], v[146:149], v[206:209], v[28:31]
	v_mfma_f32_16x16x32_bf16 v[24:27], v[154:157], v[206:209], v[24:27]
	v_mfma_f32_16x16x32_bf16 v[12:15], v[146:149], v[214:217], v[12:15]
	v_mfma_f32_16x16x32_bf16 v[8:11], v[154:157], v[214:217], v[8:11]
	v_mfma_f32_16x16x32_bf16 v[52:55], v[170:173], v[186:189], v[52:55]
	v_mfma_f32_16x16x32_bf16 v[48:51], v[178:181], v[186:189], v[48:51]
	v_mfma_f32_16x16x32_bf16 v[36:39], v[170:173], v[194:197], v[36:39]
	v_mfma_f32_16x16x32_bf16 v[32:35], v[178:181], v[194:197], v[32:35]
	v_mfma_f32_16x16x32_bf16 v[20:23], v[170:173], v[202:205], v[20:23]
	v_mfma_f32_16x16x32_bf16 v[16:19], v[178:181], v[202:205], v[16:19]
	v_mfma_f32_16x16x32_bf16 v[4:7], v[170:173], v[210:213], v[4:7]
	v_mfma_f32_16x16x32_bf16 v[0:3], v[178:181], v[210:213], v[0:3]
	v_mfma_f32_16x16x32_bf16 v[52:55], v[174:177], v[190:193], v[52:55]
	v_mfma_f32_16x16x32_bf16 v[48:51], v[182:185], v[190:193], v[48:51]
	v_mfma_f32_16x16x32_bf16 v[36:39], v[174:177], v[198:201], v[36:39]
	v_mfma_f32_16x16x32_bf16 v[32:35], v[182:185], v[198:201], v[32:35]
	v_mfma_f32_16x16x32_bf16 v[20:23], v[174:177], v[206:209], v[20:23]
	v_mfma_f32_16x16x32_bf16 v[16:19], v[182:185], v[206:209], v[16:19]
	v_mfma_f32_16x16x32_bf16 v[4:7], v[174:177], v[214:217], v[4:7]
	v_mfma_f32_16x16x32_bf16 v[0:3], v[182:185], v[214:217], v[0:3]
	s_barrier
; #define PG8_STAGE(bufoff, gbase, voff) do { _Pragma("unroll") for (int _i = 0; _i < 2; ++_i) \
;         __builtin_amdgcn_global_load_lds((const unsigned*)((const char*)(gbase) + (voff)[_i]), (LAS unsigned*)(lds + (bufoff) + ldsw + _i * 8192), 16, 0, 0); } while (0)
; #define PG8_LDA(dst, b, h) do { _Pragma("unroll") for (int m = 0; m < 4; ++m) _Pragma("unroll") for (int k = 0; k < 2; ++k) dst[m][k] = *(const LAS bf16x8*)(lds + PG8_SA(b, h) + aoff + m * 2048 + k * 1024); } while (0)
; #define PG8_LDB(dst, b, h) do { _Pragma("unroll") for (int n = 0; n < 2; ++n) _Pragma("unroll") for (int k = 0; k < 2; ++k) dst[n][k] = *(const LAS bf16x8*)(lds + PG8_SB(b, h) + boff + n * 2048 + k * 1024); } while (0)
; #define PG8_WAIT_V(n) asm volatile("s_waitcnt vmcnt(" #n ")" ::: "memory")
; template <class Epi, class Sched, bool ALIGN_EPI = true, bool SP2 = true>
; __device__ __forceinline__ void gemm_phase(LAS unsigned char* lds, const Gemm g, const Sched& S, const Epi& E) {
;     ...
;         for (int t = 0; t < nt; t += 2) {
;             const bool last = (t == nt - 2);
;             const char* a1 = cA + (size_t)(t + 1) * kstep;
;             const char* a2 = last ? nA : cA + (size_t)(t + 2) * kstep; const char* b2 = last ? nB : cB + (size_t)(t + 2) * kstep;
;             const char* a3 = a2 + kstep; const char* b3 = b2 + kstep;
;             if constexpr (SP2) {
;             PG8_LDB(B0, 0, 0); PG8_LDB(B1, 0, 1); PG8_SCHED; PG8_LDA(At, 0, 0); PG8_STAGE(PG8_SA(1, 1), a1 + hstep, voffA);
;             PG8_WAIT_V(8); PG8_WAIT_L(0); PG8_BAR; PG8_MMA(0, 0, At, B0); PG8_MMA(0, 1, At, B1); PG8_BAR; PG8_SCHED;
;             PG8_LDA(At, 0, 1); PG8_STAGE(PG8_SB(0, 0), b2, voffB); PG8_STAGE(PG8_SB(0, 1), b2 + hstep, voffB); PG8_STAGE(PG8_SA(0, 0), a2, voffA);
;             PG8_WAIT_V(8); PG8_WAIT_L(0); PG8_BAR; PG8_MMA(1, 0, At, B0); PG8_MMA(1, 1, At, B1); PG8_BAR; PG8_SCHED;
;             PG8_LDB(B0, 1, 0); PG8_LDB(B1, 1, 1); PG8_SCHED; PG8_LDA(At, 1, 0); PG8_STAGE(PG8_SA(0, 1), a2 + hstep, voffA);
;             PG8_WAIT_V(8); PG8_WAIT_L(0); PG8_BAR; PG8_MMA(0, 0, At, B0); PG8_MMA(0, 1, At, B1); PG8_BAR; PG8_SCHED;
;             PG8_LDA(At, 1, 1); PG8_STAGE(PG8_SB(1, 0), b3, voffB); PG8_STAGE(PG8_SB(1, 1), b3 + hstep, voffB); PG8_STAGE(PG8_SA(1, 0), a3, voffA);
;             PG8_WAIT_V(8); PG8_WAIT_L(0); PG8_BAR; PG8_MMA(1, 0, At, B0); PG8_MMA(1, 1, At, B1); PG8_BAR; PG8_SCHED;
	s_add_i32 s46, 0, 0x18000
	s_add_i32 s47, 0, 0x1c000
	v_add_u32_e32 v154, s46, v143
	v_add_u32_e32 v182, s47, v143
	ds_read_b128 v[138:141], v154
	ds_read_b128 v[146:149], v154 offset:1024
	ds_read_b128 v[150:153], v154 offset:2048
	ds_read_b128 v[154:157], v154 offset:3072
	ds_read_b128 v[170:173], v182
	ds_read_b128 v[174:177], v182 offset:1024
	ds_read_b128 v[178:181], v182 offset:2048
	ds_read_b128 v[182:185], v182 offset:3072
	s_add_u32 s66, s66, 0x80000
	s_addc_u32 s67, s67, 0
	s_mov_b32 m0, s61
	ds_read_b128 v[186:189], v145 offset:32768
	ds_read_b128 v[190:193], v145 offset:33792
	ds_read_b128 v[194:197], v145 offset:34816
	ds_read_b128 v[198:201], v145 offset:35840
	ds_read_b128 v[202:205], v145 offset:36864
	ds_read_b128 v[206:209], v145 offset:37888
	ds_read_b128 v[210:213], v145 offset:38912
	ds_read_b128 v[214:217], v145 offset:39936
	global_load_lds_dwordx4 v128, s[66:67]
	s_mov_b32 m0, s72
	s_nop 0
	global_load_lds_dwordx4 v130, s[66:67]
	s_waitcnt vmcnt(8) lgkmcnt(0)
	s_barrier
	v_mfma_f32_16x16x32_bf16 v[124:127], v[138:141], v[186:189], v[124:127]
	v_mfma_f32_16x16x32_bf16 v[120:123], v[150:153], v[186:189], v[120:123]
	v_mfma_f32_16x16x32_bf16 v[108:111], v[138:141], v[194:197], v[108:111]
	v_mfma_f32_16x16x32_bf16 v[104:107], v[150:153], v[194:197], v[104:107]
	v_mfma_f32_16x16x32_bf16 v[92:95], v[138:141], v[202:205], v[92:95]
	v_mfma_f32_16x16x32_bf16 v[88:91], v[150:153], v[202:205], v[88:91]
	v_mfma_f32_16x16x32_bf16 v[76:79], v[138:141], v[210:213], v[76:79]
	v_mfma_f32_16x16x32_bf16 v[72:75], v[150:153], v[210:213], v[72:75]
	v_mfma_f32_16x16x32_bf16 v[124:127], v[146:149], v[190:193], v[124:127]
	v_mfma_f32_16x16x32_bf16 v[120:123], v[154:157], v[190:193], v[120:123]
	v_mfma_f32_16x16x32_bf16 v[108:111], v[146:149], v[198:201], v[108:111]
	v_mfma_f32_16x16x32_bf16 v[104:107], v[154:157], v[198:201], v[104:107]
	v_mfma_f32_16x16x32_bf16 v[92:95], v[146:149], v[206:209], v[92:95]
	v_mfma_f32_16x16x32_bf16 v[88:91], v[154:157], v[206:209], v[88:91]
	v_mfma_f32_16x16x32_bf16 v[76:79], v[146:149], v[214:217], v[76:79]
	v_mfma_f32_16x16x32_bf16 v[72:75], v[154:157], v[214:217], v[72:75]
	v_mfma_f32_16x16x32_bf16 v[116:119], v[170:173], v[186:189], v[116:119]
	v_mfma_f32_16x16x32_bf16 v[112:115], v[178:181], v[186:189], v[112:115]
	v_mfma_f32_16x16x32_bf16 v[100:103], v[170:173], v[194:197], v[100:103]
	v_mfma_f32_16x16x32_bf16 v[96:99], v[178:181], v[194:197], v[96:99]
	v_mfma_f32_16x16x32_bf16 v[84:87], v[170:173], v[202:205], v[84:87]
	v_mfma_f32_16x16x32_bf16 v[80:83], v[178:181], v[202:205], v[80:83]
	v_mfma_f32_16x16x32_bf16 v[68:71], v[170:173], v[210:213], v[68:71]
	v_mfma_f32_16x16x32_bf16 v[64:67], v[178:181], v[210:213], v[64:67]
	v_mfma_f32_16x16x32_bf16 v[116:119], v[174:177], v[190:193], v[116:119]
	v_mfma_f32_16x16x32_bf16 v[112:115], v[182:185], v[190:193], v[112:115]
	v_mfma_f32_16x16x32_bf16 v[100:103], v[174:177], v[198:201], v[100:103]
	v_mfma_f32_16x16x32_bf16 v[96:99], v[182:185], v[198:201], v[96:99]
	v_mfma_f32_16x16x32_bf16 v[84:87], v[174:177], v[206:209], v[84:87]
	v_mfma_f32_16x16x32_bf16 v[80:83], v[182:185], v[206:209], v[80:83]
	v_mfma_f32_16x16x32_bf16 v[68:71], v[174:177], v[214:217], v[68:71]
	v_mfma_f32_16x16x32_bf16 v[64:67], v[182:185], v[214:217], v[64:67]
	s_barrier
	s_add_i32 s46, s46, s43
	s_mov_b32 m0, s46
	ds_read_b128 v[186:189], v145 offset:49152
	ds_read_b128 v[190:193], v145 offset:50176
	ds_read_b128 v[194:197], v145 offset:51200
	ds_read_b128 v[198:201], v145 offset:52224
	ds_read_b128 v[202:205], v145 offset:53248
	ds_read_b128 v[206:209], v145 offset:54272
	ds_read_b128 v[210:213], v145 offset:55296
	ds_read_b128 v[214:217], v145 offset:56320
	s_add_u32 s98, s24, 0x80
	s_addc_u32 s99, s25, 0
	global_load_lds_dwordx4 v160, s[98:99]
	s_add_i32 m0, s46, 0x2000
	s_add_u32 s24, s24, 0x80080
	s_addc_u32 s25, s25, 0
	s_add_i32 s46, s47, s43
	global_load_lds_dwordx4 v132, s[98:99]
	s_mov_b32 m0, s46
	s_nop 0
	global_load_lds_dwordx4 v160, s[24:25]
	s_add_i32 m0, s46, 0x2000
	s_nop 0
	global_load_lds_dwordx4 v132, s[24:25]
	s_mov_b32 m0, s73
	s_nop 0
	s_add_u32 s98, s66, 0xfff80080
	s_addc_u32 s99, s67, -1
	global_load_lds_dwordx4 v128, s[98:99]
	s_mov_b32 m0, s79
	s_nop 0
	global_load_lds_dwordx4 v130, s[98:99]
	s_waitcnt vmcnt(8) lgkmcnt(0)
	s_barrier
	v_mfma_f32_16x16x32_bf16 v[60:63], v[138:141], v[186:189], v[60:63]
	v_mfma_f32_16x16x32_bf16 v[56:59], v[150:153], v[186:189], v[56:59]
	v_mfma_f32_16x16x32_bf16 v[44:47], v[138:141], v[194:197], v[44:47]
	v_mfma_f32_16x16x32_bf16 v[40:43], v[150:153], v[194:197], v[40:43]
	v_mfma_f32_16x16x32_bf16 v[28:31], v[138:141], v[202:205], v[28:31]
	v_mfma_f32_16x16x32_bf16 v[24:27], v[150:153], v[202:205], v[24:27]
	v_mfma_f32_16x16x32_bf16 v[12:15], v[138:141], v[210:213], v[12:15]
	v_mfma_f32_16x16x32_bf16 v[8:11], v[150:153], v[210:213], v[8:11]
	v_mfma_f32_16x16x32_bf16 v[60:63], v[146:149], v[190:193], v[60:63]
	v_mfma_f32_16x16x32_bf16 v[56:59], v[154:157], v[190:193], v[56:59]
	v_mfma_f32_16x16x32_bf16 v[44:47], v[146:149], v[198:201], v[44:47]
	v_mfma_f32_16x16x32_bf16 v[40:43], v[154:157], v[198:201], v[40:43]
	v_mfma_f32_16x16x32_bf16 v[28:31], v[146:149], v[206:209], v[28:31]
	v_mfma_f32_16x16x32_bf16 v[24:27], v[154:157], v[206:209], v[24:27]
	v_mfma_f32_16x16x32_bf16 v[12:15], v[146:149], v[214:217], v[12:15]
	v_mfma_f32_16x16x32_bf16 v[8:11], v[154:157], v[214:217], v[8:11]
	v_mfma_f32_16x16x32_bf16 v[52:55], v[170:173], v[186:189], v[52:55]
	v_mfma_f32_16x16x32_bf16 v[48:51], v[178:181], v[186:189], v[48:51]
	v_mfma_f32_16x16x32_bf16 v[36:39], v[170:173], v[194:197], v[36:39]
	v_mfma_f32_16x16x32_bf16 v[32:35], v[178:181], v[194:197], v[32:35]
	v_mfma_f32_16x16x32_bf16 v[20:23], v[170:173], v[202:205], v[20:23]
	v_mfma_f32_16x16x32_bf16 v[16:19], v[178:181], v[202:205], v[16:19]
	v_mfma_f32_16x16x32_bf16 v[4:7], v[170:173], v[210:213], v[4:7]
	v_mfma_f32_16x16x32_bf16 v[0:3], v[178:181], v[210:213], v[0:3]
	v_mfma_f32_16x16x32_bf16 v[52:55], v[174:177], v[190:193], v[52:55]
	v_mfma_f32_16x16x32_bf16 v[48:51], v[182:185], v[190:193], v[48:51]
	v_mfma_f32_16x16x32_bf16 v[36:39], v[174:177], v[198:201], v[36:39]
	v_mfma_f32_16x16x32_bf16 v[32:35], v[182:185], v[198:201], v[32:35]
	v_mfma_f32_16x16x32_bf16 v[20:23], v[174:177], v[206:209], v[20:23]
	v_mfma_f32_16x16x32_bf16 v[16:19], v[182:185], v[206:209], v[16:19]
	v_mfma_f32_16x16x32_bf16 v[4:7], v[174:177], v[214:217], v[4:7]
	v_mfma_f32_16x16x32_bf16 v[0:3], v[182:185], v[214:217], v[0:3]
	s_barrier
	s_add_i32 s93, s93, 2
	s_add_u32 s62, s62, 0x100
	s_addc_u32 s63, s63, 0
	s_add_u32 s91, s91, 0x100
	s_addc_u32 s92, s92, 0
	s_cmp_gt_u32 s93, 29
	s_cbranch_scc0 .LBB0_93
	s_setprio 0
	s_and_b64 vcc, exec, s[16:17]
	s_movk_i32 s91, 0x161
	s_movk_i32 s92, 0x7ff
	s_cbranch_vccz .LBB0_96
	s_barrier

; #define PG8_STAGE(bufoff, gbase, voff) do { _Pragma("unroll") for (int _i = 0; _i < 2; ++_i) \
;         __builtin_amdgcn_global_load_lds((const unsigned*)((const char*)(gbase) + (voff)[_i]), (LAS unsigned*)(lds + (bufoff) + ldsw + _i * 8192), 16, 0, 0); } while (0)
; #define PG8_LDA(dst, b, h) do { _Pragma("unroll") for (int m = 0; m < 4; ++m) _Pragma("unroll") for (int k = 0; k < 2; ++k) dst[m][k] = *(const LAS bf16x8*)(lds + PG8_SA(b, h) + aoff + m * 2048 + k * 1024); } while (0)
; #define PG8_LDB(dst, b, h) do { _Pragma("unroll") for (int n = 0; n < 2; ++n) _Pragma("unroll") for (int k = 0; k < 2; ++k) dst[n][k] = *(const LAS bf16x8*)(lds + PG8_SB(b, h) + boff + n * 2048 + k * 1024); } while (0)
; #define PG8_WAIT_V(n) asm volatile("s_waitcnt vmcnt(" #n ")" ::: "memory")
; template <class Epi, class Sched, bool ALIGN_EPI = true, bool SP2 = true>
; __device__ __forceinline__ void gemm_phase(LAS unsigned char* lds, const Gemm g, const Sched& S, const Epi& E) {
;     ...
;         for (int t = 0; t < nt; t += 2) {
;             const bool last = (t == nt - 2);
;             const char* a1 = cA + (size_t)(t + 1) * kstep;
;             const char* a2 = last ? nA : cA + (size_t)(t + 2) * kstep; const char* b2 = last ? nB : cB + (size_t)(t + 2) * kstep;
;             const char* a3 = a2 + kstep; const char* b3 = b2 + kstep;
;             if constexpr (SP2) {
;             PG8_LDB(B0, 0, 0); PG8_LDB(B1, 0, 1); PG8_SCHED; PG8_LDA(At, 0, 0); PG8_STAGE(PG8_SA(1, 1), a1 + hstep, voffA);
;             PG8_WAIT_V(8); PG8_WAIT_L(0); PG8_BAR; PG8_MMA(0, 0, At, B0); PG8_MMA(0, 1, At, B1); PG8_BAR; PG8_SCHED;
;             PG8_LDA(At, 0, 1); PG8_STAGE(PG8_SB(0, 0), b2, voffB); PG8_STAGE(PG8_SB(0, 1), b2 + hstep, voffB); PG8_STAGE(PG8_SA(0, 0), a2, voffA);
;             PG8_WAIT_V(8); PG8_WAIT_L(0); PG8_BAR; PG8_MMA(1, 0, At, B0); PG8_MMA(1, 1, At, B1); PG8_BAR; PG8_SCHED;
;             PG8_LDB(B0, 1, 0); PG8_LDB(B1, 1, 1); PG8_SCHED; PG8_LDA(At, 1, 0); PG8_STAGE(PG8_SA(0, 1), a2 + hstep, voffA);
;             PG8_WAIT_V(8); PG8_WAIT_L(0); PG8_BAR; PG8_MMA(0, 0, At, B0); PG8_MMA(0, 1, At, B1); PG8_BAR; PG8_SCHED;
;             PG8_LDA(At, 1, 1); PG8_STAGE(PG8_SB(1, 0), b3, voffB); PG8_STAGE(PG8_SB(1, 1), b3 + hstep, voffB); PG8_STAGE(PG8_SA(1, 0), a3, voffA);
;             PG8_WAIT_V(8); PG8_WAIT_L(0); PG8_BAR; PG8_MMA(1, 0, At, B0); PG8_MMA(1, 1, At, B1); PG8_BAR; PG8_SCHED;
.Lprio_skip_117:
.LBB0_117:
	s_add_u32 s24, s62, 0xfff80080
	s_addc_u32 s25, s63, -1
	s_add_i32 s46, 0, 0x10000
	s_cmp_eq_u32 s96, 28
	s_cselect_b32 s67, s2, s25
	s_cselect_b32 s66, s3, s24
	s_cselect_b32 s25, s17, s95
	s_cselect_b32 s24, s19, s94
	s_add_i32 s47, 0, 0x14000
	v_add_u32_e32 v154, s46, v143
	v_add_u32_e32 v158, s47, v143
	ds_read_b128 v[138:141], v154
	ds_read_b128 v[146:149], v154 offset:1024
	ds_read_b128 v[150:153], v154 offset:2048
	ds_read_b128 v[154:157], v154 offset:3072
	ds_read_b128 v[170:173], v158
	ds_read_b128 v[174:177], v158 offset:1024
	ds_read_b128 v[178:181], v158 offset:2048
	ds_read_b128 v[182:185], v158 offset:3072
	s_add_i32 m0, s61, 0xc000
	ds_read_b128 v[186:189], v145
	ds_read_b128 v[190:193], v145 offset:1024
	ds_read_b128 v[194:197], v145 offset:2048
	ds_read_b128 v[198:201], v145 offset:3072
	ds_read_b128 v[202:205], v145 offset:4096
	ds_read_b128 v[206:209], v145 offset:5120
	ds_read_b128 v[210:213], v145 offset:6144
	ds_read_b128 v[214:217], v145 offset:7168
	global_load_lds_dwordx4 v134, s[62:63]
	s_add_i32 m0, s61, 0xe000
	s_nop 0
	global_load_lds_dwordx4 v136, s[62:63]
	s_waitcnt vmcnt(8) lgkmcnt(0)
	s_barrier
	v_mfma_f32_16x16x32_bf16 v[124:127], v[138:141], v[186:189], v[124:127]
	v_mfma_f32_16x16x32_bf16 v[120:123], v[150:153], v[186:189], v[120:123]
	v_mfma_f32_16x16x32_bf16 v[108:111], v[138:141], v[194:197], v[108:111]
	v_mfma_f32_16x16x32_bf16 v[104:107], v[150:153], v[194:197], v[104:107]
	v_mfma_f32_16x16x32_bf16 v[92:95], v[138:141], v[202:205], v[92:95]
	v_mfma_f32_16x16x32_bf16 v[88:91], v[150:153], v[202:205], v[88:91]
	v_mfma_f32_16x16x32_bf16 v[76:79], v[138:141], v[210:213], v[76:79]
	v_mfma_f32_16x16x32_bf16 v[72:75], v[150:153], v[210:213], v[72:75]
	v_mfma_f32_16x16x32_bf16 v[124:127], v[146:149], v[190:193], v[124:127]
	v_mfma_f32_16x16x32_bf16 v[120:123], v[154:157], v[190:193], v[120:123]
	v_mfma_f32_16x16x32_bf16 v[108:111], v[146:149], v[198:201], v[108:111]
	v_mfma_f32_16x16x32_bf16 v[104:107], v[154:157], v[198:201], v[104:107]
	v_mfma_f32_16x16x32_bf16 v[92:95], v[146:149], v[206:209], v[92:95]
	v_mfma_f32_16x16x32_bf16 v[88:91], v[154:157], v[206:209], v[88:91]
	v_mfma_f32_16x16x32_bf16 v[76:79], v[146:149], v[214:217], v[76:79]
	v_mfma_f32_16x16x32_bf16 v[72:75], v[154:157], v[214:217], v[72:75]
	v_mfma_f32_16x16x32_bf16 v[116:119], v[170:173], v[186:189], v[116:119]
	v_mfma_f32_16x16x32_bf16 v[112:115], v[178:181], v[186:189], v[112:115]
	v_mfma_f32_16x16x32_bf16 v[100:103], v[170:173], v[194:197], v[100:103]
	v_mfma_f32_16x16x32_bf16 v[96:99], v[178:181], v[194:197], v[96:99]
	v_mfma_f32_16x16x32_bf16 v[84:87], v[170:173], v[202:205], v[84:87]
	v_mfma_f32_16x16x32_bf16 v[80:83], v[178:181], v[202:205], v[80:83]
	v_mfma_f32_16x16x32_bf16 v[68:71], v[170:173], v[210:213], v[68:71]
	v_mfma_f32_16x16x32_bf16 v[64:67], v[178:181], v[210:213], v[64:67]
	v_mfma_f32_16x16x32_bf16 v[116:119], v[174:177], v[190:193], v[116:119]
	v_mfma_f32_16x16x32_bf16 v[112:115], v[182:185], v[190:193], v[112:115]
	v_mfma_f32_16x16x32_bf16 v[100:103], v[174:177], v[198:201], v[100:103]
	v_mfma_f32_16x16x32_bf16 v[96:99], v[182:185], v[198:201], v[96:99]
	v_mfma_f32_16x16x32_bf16 v[84:87], v[174:177], v[206:209], v[84:87]
	v_mfma_f32_16x16x32_bf16 v[80:83], v[182:185], v[206:209], v[80:83]
	v_mfma_f32_16x16x32_bf16 v[68:71], v[174:177], v[214:217], v[68:71]
	v_mfma_f32_16x16x32_bf16 v[64:67], v[182:185], v[214:217], v[64:67]
	s_barrier
	s_add_i32 s46, s46, s44
	s_mov_b32 m0, s46
	ds_read_b128 v[186:189], v145 offset:16384
	ds_read_b128 v[190:193], v145 offset:17408
	ds_read_b128 v[194:197], v145 offset:18432
	ds_read_b128 v[198:201], v145 offset:19456
	ds_read_b128 v[202:205], v145 offset:20480
	ds_read_b128 v[206:209], v145 offset:21504
	ds_read_b128 v[210:213], v145 offset:22528
	ds_read_b128 v[214:217], v145 offset:23552
	global_load_lds_dwordx4 v160, s[24:25]
	s_add_i32 m0, s46, 0x2000
	s_add_u32 vcc_lo, s24, 0x80000
	s_addc_u32 vcc_hi, s25, 0
	s_add_i32 s46, s47, s44
	global_load_lds_dwordx4 v132, s[24:25]
	v_lshl_add_u64 v[218:219], vcc, 0, v[160:161]
	s_mov_b32 m0, s46
	s_nop 0
	global_load_lds_dwordx4 v[218:219], off
	v_lshl_add_u64 v[218:219], vcc, 0, v[132:133]
	s_add_i32 m0, s46, 0x2000
	s_nop 0
	global_load_lds_dwordx4 v[218:219], off
	s_mov_b32 m0, s61
	s_nop 0
	global_load_lds_dwordx4 v128, s[66:67]
	s_mov_b32 m0, s73
	s_nop 0
	global_load_lds_dwordx4 v130, s[66:67]
	s_waitcnt vmcnt(8) lgkmcnt(0)
	s_barrier
	v_mfma_f32_16x16x32_bf16 v[60:63], v[138:141], v[186:189], v[60:63]
	v_mfma_f32_16x16x32_bf16 v[56:59], v[150:153], v[186:189], v[56:59]
	v_mfma_f32_16x16x32_bf16 v[44:47], v[138:141], v[194:197], v[44:47]
	v_mfma_f32_16x16x32_bf16 v[40:43], v[150:153], v[194:197], v[40:43]
	v_mfma_f32_16x16x32_bf16 v[28:31], v[138:141], v[202:205], v[28:31]
	v_mfma_f32_16x16x32_bf16 v[24:27], v[150:153], v[202:205], v[24:27]
	v_mfma_f32_16x16x32_bf16 v[12:15], v[138:141], v[210:213], v[12:15]
	v_mfma_f32_16x16x32_bf16 v[8:11], v[150:153], v[210:213], v[8:11]
	v_mfma_f32_16x16x32_bf16 v[60:63], v[146:149], v[190:193], v[60:63]
	v_mfma_f32_16x16x32_bf16 v[56:59], v[154:157], v[190:193], v[56:59]
	v_mfma_f32_16x16x32_bf16 v[44:47], v[146:149], v[198:201], v[44:47]
	v_mfma_f32_16x16x32_bf16 v[40:43], v[154:157], v[198:201], v[40:43]
	v_mfma_f32_16x16x32_bf16 v[28:31], v[146:149], v[206:209], v[28:31]
	v_mfma_f32_16x16x32_bf16 v[24:27], v[154:157], v[206:209], v[24:27]
	v_mfma_f32_16x16x32_bf16 v[12:15], v[146:149], v[214:217], v[12:15]
	v_mfma_f32_16x16x32_bf16 v[8:11], v[154:157], v[214:217], v[8:11]
	v_mfma_f32_16x16x32_bf16 v[52:55], v[170:173], v[186:189], v[52:55]
	v_mfma_f32_16x16x32_bf16 v[48:51], v[178:181], v[186:189], v[48:51]
	v_mfma_f32_16x16x32_bf16 v[36:39], v[170:173], v[194:197], v[36:39]
	v_mfma_f32_16x16x32_bf16 v[32:35], v[178:181], v[194:197], v[32:35]
	v_mfma_f32_16x16x32_bf16 v[20:23], v[170:173], v[202:205], v[20:23]
	v_mfma_f32_16x16x32_bf16 v[16:19], v[178:181], v[202:205], v[16:19]
	v_mfma_f32_16x16x32_bf16 v[4:7], v[170:173], v[210:213], v[4:7]
	v_mfma_f32_16x16x32_bf16 v[0:3], v[178:181], v[210:213], v[0:3]
	v_mfma_f32_16x16x32_bf16 v[52:55], v[174:177], v[190:193], v[52:55]
	v_mfma_f32_16x16x32_bf16 v[48:51], v[182:185], v[190:193], v[48:51]
	v_mfma_f32_16x16x32_bf16 v[36:39], v[174:177], v[198:201], v[36:39]
	v_mfma_f32_16x16x32_bf16 v[32:35], v[182:185], v[198:201], v[32:35]
	v_mfma_f32_16x16x32_bf16 v[20:23], v[174:177], v[206:209], v[20:23]
	v_mfma_f32_16x16x32_bf16 v[16:19], v[182:185], v[206:209], v[16:19]
	v_mfma_f32_16x16x32_bf16 v[4:7], v[174:177], v[214:217], v[4:7]
	v_mfma_f32_16x16x32_bf16 v[0:3], v[182:185], v[214:217], v[0:3]
	s_barrier
; #define PG8_STAGE(bufoff, gbase, voff) do { _Pragma("unroll") for (int _i = 0; _i < 2; ++_i) \
;         __builtin_amdgcn_global_load_lds((const unsigned*)((const char*)(gbase) + (voff)[_i]), (LAS unsigned*)(lds + (bufoff) + ldsw + _i * 8192), 16, 0, 0); } while (0)
; #define PG8_LDA(dst, b, h) do { _Pragma("unroll") for (int m = 0; m < 4; ++m) _Pragma("unroll") for (int k = 0; k < 2; ++k) dst[m][k] = *(const LAS bf16x8*)(lds + PG8_SA(b, h) + aoff + m * 2048 + k * 1024); } while (0)
; #define PG8_LDB(dst, b, h) do { _Pragma("unroll") for (int n = 0; n < 2; ++n) _Pragma("unroll") for (int k = 0; k < 2; ++k) dst[n][k] = *(const LAS bf16x8*)(lds + PG8_SB(b, h) + boff + n * 2048 + k * 1024); } while (0)
; #define PG8_WAIT_V(n) asm volatile("s_waitcnt vmcnt(" #n ")" ::: "memory")
; template <class Epi, class Sched, bool ALIGN_EPI = true, bool SP2 = true>
; __device__ __forceinline__ void gemm_phase(LAS unsigned char* lds, const Gemm g, const Sched& S, const Epi& E) {
;     ...
;         for (int t = 0; t < nt; t += 2) {
;             const bool last = (t == nt - 2);
;             const char* a1 = cA + (size_t)(t + 1) * kstep;
;             const char* a2 = last ? nA : cA + (size_t)(t + 2) * kstep; const char* b2 = last ? nB : cB + (size_t)(t + 2) * kstep;
;             const char* a3 = a2 + kstep; const char* b3 = b2 + kstep;
;             if constexpr (SP2) {
;             PG8_LDB(B0, 0, 0); PG8_LDB(B1, 0, 1); PG8_SCHED; PG8_LDA(At, 0, 0); PG8_STAGE(PG8_SA(1, 1), a1 + hstep, voffA);
;             PG8_WAIT_V(8); PG8_WAIT_L(0); PG8_BAR; PG8_MMA(0, 0, At, B0); PG8_MMA(0, 1, At, B1); PG8_BAR; PG8_SCHED;
;             PG8_LDA(At, 0, 1); PG8_STAGE(PG8_SB(0, 0), b2, voffB); PG8_STAGE(PG8_SB(0, 1), b2 + hstep, voffB); PG8_STAGE(PG8_SA(0, 0), a2, voffA);
;             PG8_WAIT_V(8); PG8_WAIT_L(0); PG8_BAR; PG8_MMA(1, 0, At, B0); PG8_MMA(1, 1, At, B1); PG8_BAR; PG8_SCHED;
;             PG8_LDB(B0, 1, 0); PG8_LDB(B1, 1, 1); PG8_SCHED; PG8_LDA(At, 1, 0); PG8_STAGE(PG8_SA(0, 1), a2 + hstep, voffA);
;             PG8_WAIT_V(8); PG8_WAIT_L(0); PG8_BAR; PG8_MMA(0, 0, At, B0); PG8_MMA(0, 1, At, B1); PG8_BAR; PG8_SCHED;
;             PG8_LDA(At, 1, 1); PG8_STAGE(PG8_SB(1, 0), b3, voffB); PG8_STAGE(PG8_SB(1, 1), b3 + hstep, voffB); PG8_STAGE(PG8_SA(1, 0), a3, voffA);
;             PG8_WAIT_V(8); PG8_WAIT_L(0); PG8_BAR; PG8_MMA(1, 0, At, B0); PG8_MMA(1, 1, At, B1); PG8_BAR; PG8_SCHED;
	s_add_i32 s46, 0, 0x18000
	s_add_i32 s47, 0, 0x1c000
	v_add_u32_e32 v154, s46, v143
	v_add_u32_e32 v182, s47, v143
	ds_read_b128 v[138:141], v154
	ds_read_b128 v[146:149], v154 offset:1024
	ds_read_b128 v[150:153], v154 offset:2048
	ds_read_b128 v[154:157], v154 offset:3072
	ds_read_b128 v[170:173], v182
	ds_read_b128 v[174:177], v182 offset:1024
	ds_read_b128 v[178:181], v182 offset:2048
	ds_read_b128 v[182:185], v182 offset:3072
	s_add_u32 s66, s66, 0x80000
	s_addc_u32 s67, s67, 0
	s_mov_b32 m0, s79
	ds_read_b128 v[186:189], v145 offset:32768
	ds_read_b128 v[190:193], v145 offset:33792
	ds_read_b128 v[194:197], v145 offset:34816
	ds_read_b128 v[198:201], v145 offset:35840
	ds_read_b128 v[202:205], v145 offset:36864
	ds_read_b128 v[206:209], v145 offset:37888
	ds_read_b128 v[210:213], v145 offset:38912
	ds_read_b128 v[214:217], v145 offset:39936
	global_load_lds_dwordx4 v128, s[66:67]
	s_mov_b32 m0, s82
	s_nop 0
	global_load_lds_dwordx4 v130, s[66:67]
	s_waitcnt vmcnt(8) lgkmcnt(0)
	s_barrier
	v_mfma_f32_16x16x32_bf16 v[124:127], v[138:141], v[186:189], v[124:127]
	v_mfma_f32_16x16x32_bf16 v[120:123], v[150:153], v[186:189], v[120:123]
	v_mfma_f32_16x16x32_bf16 v[108:111], v[138:141], v[194:197], v[108:111]
	v_mfma_f32_16x16x32_bf16 v[104:107], v[150:153], v[194:197], v[104:107]
	v_mfma_f32_16x16x32_bf16 v[92:95], v[138:141], v[202:205], v[92:95]
	v_mfma_f32_16x16x32_bf16 v[88:91], v[150:153], v[202:205], v[88:91]
	v_mfma_f32_16x16x32_bf16 v[76:79], v[138:141], v[210:213], v[76:79]
	v_mfma_f32_16x16x32_bf16 v[72:75], v[150:153], v[210:213], v[72:75]
	v_mfma_f32_16x16x32_bf16 v[124:127], v[146:149], v[190:193], v[124:127]
	v_mfma_f32_16x16x32_bf16 v[120:123], v[154:157], v[190:193], v[120:123]
	v_mfma_f32_16x16x32_bf16 v[108:111], v[146:149], v[198:201], v[108:111]
	v_mfma_f32_16x16x32_bf16 v[104:107], v[154:157], v[198:201], v[104:107]
	v_mfma_f32_16x16x32_bf16 v[92:95], v[146:149], v[206:209], v[92:95]
	v_mfma_f32_16x16x32_bf16 v[88:91], v[154:157], v[206:209], v[88:91]
	v_mfma_f32_16x16x32_bf16 v[76:79], v[146:149], v[214:217], v[76:79]
	v_mfma_f32_16x16x32_bf16 v[72:75], v[154:157], v[214:217], v[72:75]
	v_mfma_f32_16x16x32_bf16 v[116:119], v[170:173], v[186:189], v[116:119]
	v_mfma_f32_16x16x32_bf16 v[112:115], v[178:181], v[186:189], v[112:115]
	v_mfma_f32_16x16x32_bf16 v[100:103], v[170:173], v[194:197], v[100:103]
	v_mfma_f32_16x16x32_bf16 v[96:99], v[178:181], v[194:197], v[96:99]
	v_mfma_f32_16x16x32_bf16 v[84:87], v[170:173], v[202:205], v[84:87]
	v_mfma_f32_16x16x32_bf16 v[80:83], v[178:181], v[202:205], v[80:83]
	v_mfma_f32_16x16x32_bf16 v[68:71], v[170:173], v[210:213], v[68:71]
	v_mfma_f32_16x16x32_bf16 v[64:67], v[178:181], v[210:213], v[64:67]
	v_mfma_f32_16x16x32_bf16 v[116:119], v[174:177], v[190:193], v[116:119]
	v_mfma_f32_16x16x32_bf16 v[112:115], v[182:185], v[190:193], v[112:115]
	v_mfma_f32_16x16x32_bf16 v[100:103], v[174:177], v[198:201], v[100:103]
	v_mfma_f32_16x16x32_bf16 v[96:99], v[182:185], v[198:201], v[96:99]
	v_mfma_f32_16x16x32_bf16 v[84:87], v[174:177], v[206:209], v[84:87]
	v_mfma_f32_16x16x32_bf16 v[80:83], v[182:185], v[206:209], v[80:83]
	v_mfma_f32_16x16x32_bf16 v[68:71], v[174:177], v[214:217], v[68:71]
	v_mfma_f32_16x16x32_bf16 v[64:67], v[182:185], v[214:217], v[64:67]
	s_barrier
	s_add_i32 s46, s46, s44
	s_mov_b32 m0, s46
	ds_read_b128 v[186:189], v145 offset:49152
	ds_read_b128 v[190:193], v145 offset:50176
	ds_read_b128 v[194:197], v145 offset:51200
	ds_read_b128 v[198:201], v145 offset:52224
	ds_read_b128 v[202:205], v145 offset:53248
	ds_read_b128 v[206:209], v145 offset:54272
	ds_read_b128 v[210:213], v145 offset:55296
	ds_read_b128 v[214:217], v145 offset:56320
	s_add_u32 s98, s24, 0x80
	s_addc_u32 s99, s25, 0
	global_load_lds_dwordx4 v160, s[98:99]
	s_add_i32 m0, s46, 0x2000
	s_add_u32 s24, s24, 0x80080
	s_addc_u32 s25, s25, 0
	s_add_i32 s46, s47, s44
	global_load_lds_dwordx4 v132, s[98:99]
	s_mov_b32 m0, s46
	s_nop 0
	global_load_lds_dwordx4 v160, s[24:25]
	s_add_i32 m0, s46, 0x2000
	s_nop 0
	global_load_lds_dwordx4 v132, s[24:25]
	s_mov_b32 m0, s83
	s_nop 0
	s_add_u32 s98, s66, 0xfff80080
	s_addc_u32 s99, s67, -1
	global_load_lds_dwordx4 v128, s[98:99]
	s_mov_b32 m0, s90
	s_nop 0
	global_load_lds_dwordx4 v130, s[98:99]
	s_waitcnt vmcnt(8) lgkmcnt(0)
	s_barrier
	v_mfma_f32_16x16x32_bf16 v[60:63], v[138:141], v[186:189], v[60:63]
	v_mfma_f32_16x16x32_bf16 v[56:59], v[150:153], v[186:189], v[56:59]
	v_mfma_f32_16x16x32_bf16 v[44:47], v[138:141], v[194:197], v[44:47]
	v_mfma_f32_16x16x32_bf16 v[40:43], v[150:153], v[194:197], v[40:43]
	v_mfma_f32_16x16x32_bf16 v[28:31], v[138:141], v[202:205], v[28:31]
	v_mfma_f32_16x16x32_bf16 v[24:27], v[150:153], v[202:205], v[24:27]
	v_mfma_f32_16x16x32_bf16 v[12:15], v[138:141], v[210:213], v[12:15]
	v_mfma_f32_16x16x32_bf16 v[8:11], v[150:153], v[210:213], v[8:11]
	v_mfma_f32_16x16x32_bf16 v[60:63], v[146:149], v[190:193], v[60:63]
	v_mfma_f32_16x16x32_bf16 v[56:59], v[154:157], v[190:193], v[56:59]
	v_mfma_f32_16x16x32_bf16 v[44:47], v[146:149], v[198:201], v[44:47]
	v_mfma_f32_16x16x32_bf16 v[40:43], v[154:157], v[198:201], v[40:43]
	v_mfma_f32_16x16x32_bf16 v[28:31], v[146:149], v[206:209], v[28:31]
	v_mfma_f32_16x16x32_bf16 v[24:27], v[154:157], v[206:209], v[24:27]
	v_mfma_f32_16x16x32_bf16 v[12:15], v[146:149], v[214:217], v[12:15]
	v_mfma_f32_16x16x32_bf16 v[8:11], v[154:157], v[214:217], v[8:11]
	v_mfma_f32_16x16x32_bf16 v[52:55], v[170:173], v[186:189], v[52:55]
	v_mfma_f32_16x16x32_bf16 v[48:51], v[178:181], v[186:189], v[48:51]
	v_mfma_f32_16x16x32_bf16 v[36:39], v[170:173], v[194:197], v[36:39]
	v_mfma_f32_16x16x32_bf16 v[32:35], v[178:181], v[194:197], v[32:35]
	v_mfma_f32_16x16x32_bf16 v[20:23], v[170:173], v[202:205], v[20:23]
	v_mfma_f32_16x16x32_bf16 v[16:19], v[178:181], v[202:205], v[16:19]
	v_mfma_f32_16x16x32_bf16 v[4:7], v[170:173], v[210:213], v[4:7]
	v_mfma_f32_16x16x32_bf16 v[0:3], v[178:181], v[210:213], v[0:3]
	v_mfma_f32_16x16x32_bf16 v[52:55], v[174:177], v[190:193], v[52:55]
	v_mfma_f32_16x16x32_bf16 v[48:51], v[182:185], v[190:193], v[48:51]
	v_mfma_f32_16x16x32_bf16 v[36:39], v[174:177], v[198:201], v[36:39]
	v_mfma_f32_16x16x32_bf16 v[32:35], v[182:185], v[198:201], v[32:35]
	v_mfma_f32_16x16x32_bf16 v[20:23], v[174:177], v[206:209], v[20:23]
	v_mfma_f32_16x16x32_bf16 v[16:19], v[182:185], v[206:209], v[16:19]
	v_mfma_f32_16x16x32_bf16 v[4:7], v[174:177], v[214:217], v[4:7]
	v_mfma_f32_16x16x32_bf16 v[0:3], v[182:185], v[214:217], v[0:3]
	s_barrier
	s_add_i32 s96, s96, 2
	s_add_u32 s62, s62, 0x100
	s_addc_u32 s63, s63, 0
	s_add_u32 s94, s94, 0x100
	s_addc_u32 s95, s95, 0
	s_cmp_gt_u32 s96, 29
	s_cbranch_scc0 .LBB0_117
	s_setprio 0
	s_and_b64 vcc, exec, s[10:11]
	s_mov_b64 s[96:97], 0x80000
	s_cbranch_vccz .LBB0_120
	s_barrier

; #define PG8_STAGE(bufoff, gbase, voff) do { _Pragma("unroll") for (int _i = 0; _i < 2; ++_i) \
;         __builtin_amdgcn_global_load_lds((const unsigned*)((const char*)(gbase) + (voff)[_i]), (LAS unsigned*)(lds + (bufoff) + ldsw + _i * 8192), 16, 0, 0); } while (0)
; #define PG8_LDA(dst, b, h) do { _Pragma("unroll") for (int m = 0; m < 4; ++m) _Pragma("unroll") for (int k = 0; k < 2; ++k) dst[m][k] = *(const LAS bf16x8*)(lds + PG8_SA(b, h) + aoff + m * 2048 + k * 1024); } while (0)
; #define PG8_LDB(dst, b, h) do { _Pragma("unroll") for (int n = 0; n < 2; ++n) _Pragma("unroll") for (int k = 0; k < 2; ++k) dst[n][k] = *(const LAS bf16x8*)(lds + PG8_SB(b, h) + boff + n * 2048 + k * 1024); } while (0)
; #define PG8_WAIT_V(n) asm volatile("s_waitcnt vmcnt(" #n ")" ::: "memory")
; template <class Epi, class Sched, bool ALIGN_EPI = true, bool SP2 = true>
; __device__ __forceinline__ void gemm_phase(LAS unsigned char* lds, const Gemm g, const Sched& S, const Epi& E) {
;     ...
;         for (int t = 0; t < nt; t += 2) {
;             const bool last = (t == nt - 2);
;             const char* a1 = cA + (size_t)(t + 1) * kstep;
;             const char* a2 = last ? nA : cA + (size_t)(t + 2) * kstep; const char* b2 = last ? nB : cB + (size_t)(t + 2) * kstep;
;             const char* a3 = a2 + kstep; const char* b3 = b2 + kstep;
;             if constexpr (SP2) {
;             PG8_LDB(B0, 0, 0); PG8_LDB(B1, 0, 1); PG8_SCHED; PG8_LDA(At, 0, 0); PG8_STAGE(PG8_SA(1, 1), a1 + hstep, voffA);
;             PG8_WAIT_V(8); PG8_WAIT_L(0); PG8_BAR; PG8_MMA(0, 0, At, B0); PG8_MMA(0, 1, At, B1); PG8_BAR; PG8_SCHED;
;             PG8_LDA(At, 0, 1); PG8_STAGE(PG8_SB(0, 0), b2, voffB); PG8_STAGE(PG8_SB(0, 1), b2 + hstep, voffB); PG8_STAGE(PG8_SA(0, 0), a2, voffA);
;             PG8_WAIT_V(8); PG8_WAIT_L(0); PG8_BAR; PG8_MMA(1, 0, At, B0); PG8_MMA(1, 1, At, B1); PG8_BAR; PG8_SCHED;
;             PG8_LDB(B0, 1, 0); PG8_LDB(B1, 1, 1); PG8_SCHED; PG8_LDA(At, 1, 0); PG8_STAGE(PG8_SA(0, 1), a2 + hstep, voffA);
;             PG8_WAIT_V(8); PG8_WAIT_L(0); PG8_BAR; PG8_MMA(0, 0, At, B0); PG8_MMA(0, 1, At, B1); PG8_BAR; PG8_SCHED;
;             PG8_LDA(At, 1, 1); PG8_STAGE(PG8_SB(1, 0), b3, voffB); PG8_STAGE(PG8_SB(1, 1), b3 + hstep, voffB); PG8_STAGE(PG8_SA(1, 0), a3, voffA);
;             PG8_WAIT_V(8); PG8_WAIT_L(0); PG8_BAR; PG8_MMA(1, 0, At, B0); PG8_MMA(1, 1, At, B1); PG8_BAR; PG8_SCHED;
.Lprio_skip_145:
.LBB0_145:
	s_add_u32 s24, s72, 0xfff80080
	s_addc_u32 s25, s73, -1
	s_add_i32 s46, 0, 0x10000
	s_cmp_eq_u32 s95, 28
	s_cselect_b32 s83, s2, s25
	s_cselect_b32 s82, s3, s24
	v_add_u32_e32 v142, s46, v145
	s_cselect_b32 s25, s31, s53
	s_cselect_b32 s24, s44, s45
	s_add_i32 s47, 0, 0x14000
	ds_read_b128 v[138:141], v142
	ds_read_b128 v[148:151], v142 offset:1024
	ds_read_b128 v[152:155], v142 offset:2048
	ds_read_b128 v[156:159], v142 offset:3072
	v_add_u32_e32 v142, s47, v145
	ds_read_b128 v[170:173], v142
	ds_read_b128 v[174:177], v142 offset:1024
	ds_read_b128 v[178:181], v142 offset:2048
	ds_read_b128 v[182:185], v142 offset:3072
	s_add_i32 m0, s63, 0xc000
	ds_read_b128 v[186:189], v147
	ds_read_b128 v[190:193], v147 offset:1024
	ds_read_b128 v[194:197], v147 offset:2048
	ds_read_b128 v[198:201], v147 offset:3072
	ds_read_b128 v[202:205], v147 offset:4096
	ds_read_b128 v[206:209], v147 offset:5120
	ds_read_b128 v[210:213], v147 offset:6144
	ds_read_b128 v[214:217], v147 offset:7168
	global_load_lds_dwordx4 v134, s[72:73]
	s_add_i32 m0, s63, 0xe000
	s_nop 0
	global_load_lds_dwordx4 v136, s[72:73]
	s_waitcnt vmcnt(8) lgkmcnt(0)
	s_barrier
	v_mfma_f32_16x16x32_bf16 v[124:127], v[138:141], v[186:189], v[124:127]
	v_mfma_f32_16x16x32_bf16 v[120:123], v[152:155], v[186:189], v[120:123]
	v_mfma_f32_16x16x32_bf16 v[108:111], v[138:141], v[194:197], v[108:111]
	v_mfma_f32_16x16x32_bf16 v[104:107], v[152:155], v[194:197], v[104:107]
	v_mfma_f32_16x16x32_bf16 v[92:95], v[138:141], v[202:205], v[92:95]
	v_mfma_f32_16x16x32_bf16 v[88:91], v[152:155], v[202:205], v[88:91]
	v_mfma_f32_16x16x32_bf16 v[76:79], v[138:141], v[210:213], v[76:79]
	v_mfma_f32_16x16x32_bf16 v[72:75], v[152:155], v[210:213], v[72:75]
	v_mfma_f32_16x16x32_bf16 v[124:127], v[148:151], v[190:193], v[124:127]
	v_mfma_f32_16x16x32_bf16 v[120:123], v[156:159], v[190:193], v[120:123]
	v_mfma_f32_16x16x32_bf16 v[108:111], v[148:151], v[198:201], v[108:111]
	v_mfma_f32_16x16x32_bf16 v[104:107], v[156:159], v[198:201], v[104:107]
	v_mfma_f32_16x16x32_bf16 v[92:95], v[148:151], v[206:209], v[92:95]
	v_mfma_f32_16x16x32_bf16 v[88:91], v[156:159], v[206:209], v[88:91]
	v_mfma_f32_16x16x32_bf16 v[76:79], v[148:151], v[214:217], v[76:79]
	v_mfma_f32_16x16x32_bf16 v[72:75], v[156:159], v[214:217], v[72:75]
	v_mfma_f32_16x16x32_bf16 v[116:119], v[170:173], v[186:189], v[116:119]
	v_mfma_f32_16x16x32_bf16 v[112:115], v[178:181], v[186:189], v[112:115]
	v_mfma_f32_16x16x32_bf16 v[100:103], v[170:173], v[194:197], v[100:103]
	v_mfma_f32_16x16x32_bf16 v[96:99], v[178:181], v[194:197], v[96:99]
	v_mfma_f32_16x16x32_bf16 v[84:87], v[170:173], v[202:205], v[84:87]
	v_mfma_f32_16x16x32_bf16 v[80:83], v[178:181], v[202:205], v[80:83]
	v_mfma_f32_16x16x32_bf16 v[68:71], v[170:173], v[210:213], v[68:71]
	v_mfma_f32_16x16x32_bf16 v[64:67], v[178:181], v[210:213], v[64:67]
	v_mfma_f32_16x16x32_bf16 v[116:119], v[174:177], v[190:193], v[116:119]
	v_mfma_f32_16x16x32_bf16 v[112:115], v[182:185], v[190:193], v[112:115]
	v_mfma_f32_16x16x32_bf16 v[100:103], v[174:177], v[198:201], v[100:103]
	v_mfma_f32_16x16x32_bf16 v[96:99], v[182:185], v[198:201], v[96:99]
	v_mfma_f32_16x16x32_bf16 v[84:87], v[174:177], v[206:209], v[84:87]
	v_mfma_f32_16x16x32_bf16 v[80:83], v[182:185], v[206:209], v[80:83]
	v_mfma_f32_16x16x32_bf16 v[68:71], v[174:177], v[214:217], v[68:71]
	v_mfma_f32_16x16x32_bf16 v[64:67], v[182:185], v[214:217], v[64:67]
	s_barrier
	s_add_i32 s46, s46, s79
	s_mov_b32 m0, s46
	ds_read_b128 v[186:189], v147 offset:16384
	ds_read_b128 v[190:193], v147 offset:17408
	ds_read_b128 v[194:197], v147 offset:18432
	ds_read_b128 v[198:201], v147 offset:19456
	ds_read_b128 v[202:205], v147 offset:20480
	ds_read_b128 v[206:209], v147 offset:21504
	ds_read_b128 v[210:213], v147 offset:22528
	ds_read_b128 v[214:217], v147 offset:23552
	global_load_lds_dwordx4 v160, s[24:25]
	s_add_i32 m0, s46, 0x2000
	s_add_u32 s96, s24, 0x80000
	s_addc_u32 s97, s25, 0
	s_add_i32 s46, s47, s79
	global_load_lds_dwordx4 v132, s[24:25]
	s_mov_b32 m0, s46
	s_nop 0
	global_load_lds_dwordx4 v160, s[96:97]
	s_add_i32 m0, s46, 0x2000
	s_nop 0
	global_load_lds_dwordx4 v132, s[96:97]
	s_mov_b32 m0, s63
	s_nop 0
	global_load_lds_dwordx4 v128, s[82:83]
	s_mov_b32 m0, s67
	s_nop 0
	global_load_lds_dwordx4 v130, s[82:83]
	s_waitcnt vmcnt(8) lgkmcnt(0)
	s_barrier
	v_mfma_f32_16x16x32_bf16 v[60:63], v[138:141], v[186:189], v[60:63]
	v_mfma_f32_16x16x32_bf16 v[56:59], v[152:155], v[186:189], v[56:59]
	v_mfma_f32_16x16x32_bf16 v[44:47], v[138:141], v[194:197], v[44:47]
	v_mfma_f32_16x16x32_bf16 v[40:43], v[152:155], v[194:197], v[40:43]
	v_mfma_f32_16x16x32_bf16 v[28:31], v[138:141], v[202:205], v[28:31]
	v_mfma_f32_16x16x32_bf16 v[24:27], v[152:155], v[202:205], v[24:27]
	v_mfma_f32_16x16x32_bf16 v[12:15], v[138:141], v[210:213], v[12:15]
	v_mfma_f32_16x16x32_bf16 v[8:11], v[152:155], v[210:213], v[8:11]
	v_mfma_f32_16x16x32_bf16 v[60:63], v[148:151], v[190:193], v[60:63]
	v_mfma_f32_16x16x32_bf16 v[56:59], v[156:159], v[190:193], v[56:59]
	v_mfma_f32_16x16x32_bf16 v[44:47], v[148:151], v[198:201], v[44:47]
	v_mfma_f32_16x16x32_bf16 v[40:43], v[156:159], v[198:201], v[40:43]
	v_mfma_f32_16x16x32_bf16 v[28:31], v[148:151], v[206:209], v[28:31]
	v_mfma_f32_16x16x32_bf16 v[24:27], v[156:159], v[206:209], v[24:27]
	v_mfma_f32_16x16x32_bf16 v[12:15], v[148:151], v[214:217], v[12:15]
	v_mfma_f32_16x16x32_bf16 v[8:11], v[156:159], v[214:217], v[8:11]
	v_mfma_f32_16x16x32_bf16 v[52:55], v[170:173], v[186:189], v[52:55]
	v_mfma_f32_16x16x32_bf16 v[48:51], v[178:181], v[186:189], v[48:51]
	v_mfma_f32_16x16x32_bf16 v[36:39], v[170:173], v[194:197], v[36:39]
	v_mfma_f32_16x16x32_bf16 v[32:35], v[178:181], v[194:197], v[32:35]
	v_mfma_f32_16x16x32_bf16 v[20:23], v[170:173], v[202:205], v[20:23]
	v_mfma_f32_16x16x32_bf16 v[16:19], v[178:181], v[202:205], v[16:19]
	v_mfma_f32_16x16x32_bf16 v[4:7], v[170:173], v[210:213], v[4:7]
	v_mfma_f32_16x16x32_bf16 v[0:3], v[178:181], v[210:213], v[0:3]
	v_mfma_f32_16x16x32_bf16 v[52:55], v[174:177], v[190:193], v[52:55]
	v_mfma_f32_16x16x32_bf16 v[48:51], v[182:185], v[190:193], v[48:51]
	v_mfma_f32_16x16x32_bf16 v[36:39], v[174:177], v[198:201], v[36:39]
	v_mfma_f32_16x16x32_bf16 v[32:35], v[182:185], v[198:201], v[32:35]
	v_mfma_f32_16x16x32_bf16 v[20:23], v[174:177], v[206:209], v[20:23]
	v_mfma_f32_16x16x32_bf16 v[16:19], v[182:185], v[206:209], v[16:19]
	v_mfma_f32_16x16x32_bf16 v[4:7], v[174:177], v[214:217], v[4:7]
	v_mfma_f32_16x16x32_bf16 v[0:3], v[182:185], v[214:217], v[0:3]
	s_barrier
; #define PG8_STAGE(bufoff, gbase, voff) do { _Pragma("unroll") for (int _i = 0; _i < 2; ++_i) \
;         __builtin_amdgcn_global_load_lds((const unsigned*)((const char*)(gbase) + (voff)[_i]), (LAS unsigned*)(lds + (bufoff) + ldsw + _i * 8192), 16, 0, 0); } while (0)
; #define PG8_LDA(dst, b, h) do { _Pragma("unroll") for (int m = 0; m < 4; ++m) _Pragma("unroll") for (int k = 0; k < 2; ++k) dst[m][k] = *(const LAS bf16x8*)(lds + PG8_SA(b, h) + aoff + m * 2048 + k * 1024); } while (0)
; #define PG8_LDB(dst, b, h) do { _Pragma("unroll") for (int n = 0; n < 2; ++n) _Pragma("unroll") for (int k = 0; k < 2; ++k) dst[n][k] = *(const LAS bf16x8*)(lds + PG8_SB(b, h) + boff + n * 2048 + k * 1024); } while (0)
; #define PG8_WAIT_V(n) asm volatile("s_waitcnt vmcnt(" #n ")" ::: "memory")
; template <class Epi, class Sched, bool ALIGN_EPI = true, bool SP2 = true>
; __device__ __forceinline__ void gemm_phase(LAS unsigned char* lds, const Gemm g, const Sched& S, const Epi& E) {
;     ...
;         for (int t = 0; t < nt; t += 2) {
;             const bool last = (t == nt - 2);
;             const char* a1 = cA + (size_t)(t + 1) * kstep;
;             const char* a2 = last ? nA : cA + (size_t)(t + 2) * kstep; const char* b2 = last ? nB : cB + (size_t)(t + 2) * kstep;
;             const char* a3 = a2 + kstep; const char* b3 = b2 + kstep;
;             if constexpr (SP2) {
;             PG8_LDB(B0, 0, 0); PG8_LDB(B1, 0, 1); PG8_SCHED; PG8_LDA(At, 0, 0); PG8_STAGE(PG8_SA(1, 1), a1 + hstep, voffA);
;             PG8_WAIT_V(8); PG8_WAIT_L(0); PG8_BAR; PG8_MMA(0, 0, At, B0); PG8_MMA(0, 1, At, B1); PG8_BAR; PG8_SCHED;
;             PG8_LDA(At, 0, 1); PG8_STAGE(PG8_SB(0, 0), b2, voffB); PG8_STAGE(PG8_SB(0, 1), b2 + hstep, voffB); PG8_STAGE(PG8_SA(0, 0), a2, voffA);
;             PG8_WAIT_V(8); PG8_WAIT_L(0); PG8_BAR; PG8_MMA(1, 0, At, B0); PG8_MMA(1, 1, At, B1); PG8_BAR; PG8_SCHED;
;             PG8_LDB(B0, 1, 0); PG8_LDB(B1, 1, 1); PG8_SCHED; PG8_LDA(At, 1, 0); PG8_STAGE(PG8_SA(0, 1), a2 + hstep, voffA);
;             PG8_WAIT_V(8); PG8_WAIT_L(0); PG8_BAR; PG8_MMA(0, 0, At, B0); PG8_MMA(0, 1, At, B1); PG8_BAR; PG8_SCHED;
;             PG8_LDA(At, 1, 1); PG8_STAGE(PG8_SB(1, 0), b3, voffB); PG8_STAGE(PG8_SB(1, 1), b3 + hstep, voffB); PG8_STAGE(PG8_SA(1, 0), a3, voffA);
;             PG8_WAIT_V(8); PG8_WAIT_L(0); PG8_BAR; PG8_MMA(1, 0, At, B0); PG8_MMA(1, 1, At, B1); PG8_BAR; PG8_SCHED;
	s_add_i32 s46, 0, 0x18000
	s_add_i32 s47, 0, 0x1c000
	v_add_u32_e32 v156, s46, v145
	v_add_u32_e32 v182, s47, v145
	ds_read_b128 v[138:141], v156
	ds_read_b128 v[148:151], v156 offset:1024
	ds_read_b128 v[152:155], v156 offset:2048
	ds_read_b128 v[156:159], v156 offset:3072
	ds_read_b128 v[170:173], v182
	ds_read_b128 v[174:177], v182 offset:1024
	ds_read_b128 v[178:181], v182 offset:2048
	ds_read_b128 v[182:185], v182 offset:3072
	s_add_u32 s82, s82, 0x80000
	s_addc_u32 s83, s83, 0
	s_mov_b32 m0, s90
	ds_read_b128 v[186:189], v147 offset:32768
	ds_read_b128 v[190:193], v147 offset:33792
	ds_read_b128 v[194:197], v147 offset:34816
	ds_read_b128 v[198:201], v147 offset:35840
	ds_read_b128 v[202:205], v147 offset:36864
	ds_read_b128 v[206:209], v147 offset:37888
	ds_read_b128 v[210:213], v147 offset:38912
	ds_read_b128 v[214:217], v147 offset:39936
	global_load_lds_dwordx4 v128, s[82:83]
	s_mov_b32 m0, s91
	s_nop 0
	global_load_lds_dwordx4 v130, s[82:83]
	s_waitcnt vmcnt(8) lgkmcnt(0)
	s_barrier
	v_mfma_f32_16x16x32_bf16 v[124:127], v[138:141], v[186:189], v[124:127]
	v_mfma_f32_16x16x32_bf16 v[120:123], v[152:155], v[186:189], v[120:123]
	v_mfma_f32_16x16x32_bf16 v[108:111], v[138:141], v[194:197], v[108:111]
	v_mfma_f32_16x16x32_bf16 v[104:107], v[152:155], v[194:197], v[104:107]
	v_mfma_f32_16x16x32_bf16 v[92:95], v[138:141], v[202:205], v[92:95]
	v_mfma_f32_16x16x32_bf16 v[88:91], v[152:155], v[202:205], v[88:91]
	v_mfma_f32_16x16x32_bf16 v[76:79], v[138:141], v[210:213], v[76:79]
	v_mfma_f32_16x16x32_bf16 v[72:75], v[152:155], v[210:213], v[72:75]
	v_mfma_f32_16x16x32_bf16 v[124:127], v[148:151], v[190:193], v[124:127]
	v_mfma_f32_16x16x32_bf16 v[120:123], v[156:159], v[190:193], v[120:123]
	v_mfma_f32_16x16x32_bf16 v[108:111], v[148:151], v[198:201], v[108:111]
	v_mfma_f32_16x16x32_bf16 v[104:107], v[156:159], v[198:201], v[104:107]
	v_mfma_f32_16x16x32_bf16 v[92:95], v[148:151], v[206:209], v[92:95]
	v_mfma_f32_16x16x32_bf16 v[88:91], v[156:159], v[206:209], v[88:91]
	v_mfma_f32_16x16x32_bf16 v[76:79], v[148:151], v[214:217], v[76:79]
	v_mfma_f32_16x16x32_bf16 v[72:75], v[156:159], v[214:217], v[72:75]
	v_mfma_f32_16x16x32_bf16 v[116:119], v[170:173], v[186:189], v[116:119]
	v_mfma_f32_16x16x32_bf16 v[112:115], v[178:181], v[186:189], v[112:115]
	v_mfma_f32_16x16x32_bf16 v[100:103], v[170:173], v[194:197], v[100:103]
	v_mfma_f32_16x16x32_bf16 v[96:99], v[178:181], v[194:197], v[96:99]
	v_mfma_f32_16x16x32_bf16 v[84:87], v[170:173], v[202:205], v[84:87]
	v_mfma_f32_16x16x32_bf16 v[80:83], v[178:181], v[202:205], v[80:83]
	v_mfma_f32_16x16x32_bf16 v[68:71], v[170:173], v[210:213], v[68:71]
	v_mfma_f32_16x16x32_bf16 v[64:67], v[178:181], v[210:213], v[64:67]
	v_mfma_f32_16x16x32_bf16 v[116:119], v[174:177], v[190:193], v[116:119]
	v_mfma_f32_16x16x32_bf16 v[112:115], v[182:185], v[190:193], v[112:115]
	v_mfma_f32_16x16x32_bf16 v[100:103], v[174:177], v[198:201], v[100:103]
	v_mfma_f32_16x16x32_bf16 v[96:99], v[182:185], v[198:201], v[96:99]
	v_mfma_f32_16x16x32_bf16 v[84:87], v[174:177], v[206:209], v[84:87]
	v_mfma_f32_16x16x32_bf16 v[80:83], v[182:185], v[206:209], v[80:83]
	v_mfma_f32_16x16x32_bf16 v[68:71], v[174:177], v[214:217], v[68:71]
	v_mfma_f32_16x16x32_bf16 v[64:67], v[182:185], v[214:217], v[64:67]
	s_barrier
	s_add_i32 s46, s46, s79
	s_mov_b32 m0, s46
	ds_read_b128 v[186:189], v147 offset:49152
	ds_read_b128 v[190:193], v147 offset:50176
	ds_read_b128 v[194:197], v147 offset:51200
	ds_read_b128 v[198:201], v147 offset:52224
	ds_read_b128 v[202:205], v147 offset:53248
	ds_read_b128 v[206:209], v147 offset:54272
	ds_read_b128 v[210:213], v147 offset:55296
	ds_read_b128 v[214:217], v147 offset:56320
	s_add_u32 s98, s24, 0x80
	s_addc_u32 s99, s25, 0
	global_load_lds_dwordx4 v160, s[98:99]
	s_add_i32 m0, s46, 0x2000
	s_add_u32 s24, s24, 0x80080
	s_addc_u32 s25, s25, 0
	s_add_i32 s46, s47, s79
	global_load_lds_dwordx4 v132, s[98:99]
	s_mov_b32 m0, s46
	s_nop 0
	global_load_lds_dwordx4 v160, s[24:25]
	s_add_i32 m0, s46, 0x2000
	s_nop 0
	global_load_lds_dwordx4 v132, s[24:25]
	s_mov_b32 m0, s92
	s_nop 0
	s_add_u32 s98, s82, 0xfff80080
	s_addc_u32 s99, s83, -1
	global_load_lds_dwordx4 v128, s[98:99]
	s_mov_b32 m0, s93
	s_nop 0
	global_load_lds_dwordx4 v130, s[98:99]
	s_waitcnt vmcnt(8) lgkmcnt(0)
	s_barrier
	v_mfma_f32_16x16x32_bf16 v[60:63], v[138:141], v[186:189], v[60:63]
	v_mfma_f32_16x16x32_bf16 v[56:59], v[152:155], v[186:189], v[56:59]
	v_mfma_f32_16x16x32_bf16 v[44:47], v[138:141], v[194:197], v[44:47]
	v_mfma_f32_16x16x32_bf16 v[40:43], v[152:155], v[194:197], v[40:43]
	v_mfma_f32_16x16x32_bf16 v[28:31], v[138:141], v[202:205], v[28:31]
	v_mfma_f32_16x16x32_bf16 v[24:27], v[152:155], v[202:205], v[24:27]
	v_mfma_f32_16x16x32_bf16 v[12:15], v[138:141], v[210:213], v[12:15]
	v_mfma_f32_16x16x32_bf16 v[8:11], v[152:155], v[210:213], v[8:11]
	v_mfma_f32_16x16x32_bf16 v[60:63], v[148:151], v[190:193], v[60:63]
	v_mfma_f32_16x16x32_bf16 v[56:59], v[156:159], v[190:193], v[56:59]
	v_mfma_f32_16x16x32_bf16 v[44:47], v[148:151], v[198:201], v[44:47]
	v_mfma_f32_16x16x32_bf16 v[40:43], v[156:159], v[198:201], v[40:43]
	v_mfma_f32_16x16x32_bf16 v[28:31], v[148:151], v[206:209], v[28:31]
	v_mfma_f32_16x16x32_bf16 v[24:27], v[156:159], v[206:209], v[24:27]
	v_mfma_f32_16x16x32_bf16 v[12:15], v[148:151], v[214:217], v[12:15]
	v_mfma_f32_16x16x32_bf16 v[8:11], v[156:159], v[214:217], v[8:11]
	v_mfma_f32_16x16x32_bf16 v[52:55], v[170:173], v[186:189], v[52:55]
	v_mfma_f32_16x16x32_bf16 v[48:51], v[178:181], v[186:189], v[48:51]
	v_mfma_f32_16x16x32_bf16 v[36:39], v[170:173], v[194:197], v[36:39]
	v_mfma_f32_16x16x32_bf16 v[32:35], v[178:181], v[194:197], v[32:35]
	v_mfma_f32_16x16x32_bf16 v[20:23], v[170:173], v[202:205], v[20:23]
	v_mfma_f32_16x16x32_bf16 v[16:19], v[178:181], v[202:205], v[16:19]
	v_mfma_f32_16x16x32_bf16 v[4:7], v[170:173], v[210:213], v[4:7]
	v_mfma_f32_16x16x32_bf16 v[0:3], v[178:181], v[210:213], v[0:3]
	v_mfma_f32_16x16x32_bf16 v[52:55], v[174:177], v[190:193], v[52:55]
	v_mfma_f32_16x16x32_bf16 v[48:51], v[182:185], v[190:193], v[48:51]
	v_mfma_f32_16x16x32_bf16 v[36:39], v[174:177], v[198:201], v[36:39]
	v_mfma_f32_16x16x32_bf16 v[32:35], v[182:185], v[198:201], v[32:35]
	v_mfma_f32_16x16x32_bf16 v[20:23], v[174:177], v[206:209], v[20:23]
	v_mfma_f32_16x16x32_bf16 v[16:19], v[182:185], v[206:209], v[16:19]
	v_mfma_f32_16x16x32_bf16 v[4:7], v[174:177], v[214:217], v[4:7]
	v_mfma_f32_16x16x32_bf16 v[0:3], v[182:185], v[214:217], v[0:3]
	s_barrier
	s_add_i32 s95, s95, 2
	s_add_u32 s72, s72, 0x100
	s_addc_u32 s73, s73, 0
	s_add_u32 s45, s45, 0x100
	s_addc_u32 s53, s53, 0
	s_cmp_gt_u32 s95, 29
	s_cbranch_scc0 .LBB0_145
	s_setprio 0
	s_and_b64 vcc, exec, s[18:19]
	s_cbranch_vccz .LBB0_148
	s_barrier

; #define PG8_STAGE(bufoff, gbase, voff) do { _Pragma("unroll") for (int _i = 0; _i < 2; ++_i) \
;         __builtin_amdgcn_global_load_lds((const unsigned*)((const char*)(gbase) + (voff)[_i]), (LAS unsigned*)(lds + (bufoff) + ldsw + _i * 8192), 16, 0, 0); } while (0)
; #define PG8_LDA(dst, b, h) do { _Pragma("unroll") for (int m = 0; m < 4; ++m) _Pragma("unroll") for (int k = 0; k < 2; ++k) dst[m][k] = *(const LAS bf16x8*)(lds + PG8_SA(b, h) + aoff + m * 2048 + k * 1024); } while (0)
; #define PG8_LDB(dst, b, h) do { _Pragma("unroll") for (int n = 0; n < 2; ++n) _Pragma("unroll") for (int k = 0; k < 2; ++k) dst[n][k] = *(const LAS bf16x8*)(lds + PG8_SB(b, h) + boff + n * 2048 + k * 1024); } while (0)
; #define PG8_WAIT_V(n) asm volatile("s_waitcnt vmcnt(" #n ")" ::: "memory")
; template <class Epi, class Sched, bool ALIGN_EPI = true, bool SP2 = true>
; __device__ __forceinline__ void gemm_phase(LAS unsigned char* lds, const Gemm g, const Sched& S, const Epi& E) {
;     ...
;         for (int t = 0; t < nt; t += 2) {
;             const bool last = (t == nt - 2);
;             const char* a1 = cA + (size_t)(t + 1) * kstep;
;             const char* a2 = last ? nA : cA + (size_t)(t + 2) * kstep; const char* b2 = last ? nB : cB + (size_t)(t + 2) * kstep;
;             const char* a3 = a2 + kstep; const char* b3 = b2 + kstep;
;             if constexpr (SP2) {
;             PG8_LDB(B0, 0, 0); PG8_LDB(B1, 0, 1); PG8_SCHED; PG8_LDA(At, 0, 0); PG8_STAGE(PG8_SA(1, 1), a1 + hstep, voffA);
;             PG8_WAIT_V(8); PG8_WAIT_L(0); PG8_BAR; PG8_MMA(0, 0, At, B0); PG8_MMA(0, 1, At, B1); PG8_BAR; PG8_SCHED;
;             PG8_LDA(At, 0, 1); PG8_STAGE(PG8_SB(0, 0), b2, voffB); PG8_STAGE(PG8_SB(0, 1), b2 + hstep, voffB); PG8_STAGE(PG8_SA(0, 0), a2, voffA);
;             PG8_WAIT_V(8); PG8_WAIT_L(0); PG8_BAR; PG8_MMA(1, 0, At, B0); PG8_MMA(1, 1, At, B1); PG8_BAR; PG8_SCHED;
;             PG8_LDB(B0, 1, 0); PG8_LDB(B1, 1, 1); PG8_SCHED; PG8_LDA(At, 1, 0); PG8_STAGE(PG8_SA(0, 1), a2 + hstep, voffA);
;             PG8_WAIT_V(8); PG8_WAIT_L(0); PG8_BAR; PG8_MMA(0, 0, At, B0); PG8_MMA(0, 1, At, B1); PG8_BAR; PG8_SCHED;
;             PG8_LDA(At, 1, 1); PG8_STAGE(PG8_SB(1, 0), b3, voffB); PG8_STAGE(PG8_SB(1, 1), b3 + hstep, voffB); PG8_STAGE(PG8_SA(1, 0), a3, voffA);
;             PG8_WAIT_V(8); PG8_WAIT_L(0); PG8_BAR; PG8_MMA(1, 0, At, B0); PG8_MMA(1, 1, At, B1); PG8_BAR; PG8_SCHED;
.Lprio_skip_187:
.LBB0_187:
	s_add_u32 s24, s66, 0xfffc0080
	s_addc_u32 s25, s67, -1
	s_add_i32 s46, 0, 0x10000
	s_cmp_eq_u32 s53, 12
	s_cselect_b32 s73, s2, s25
	s_cselect_b32 s72, s3, s24
	s_cselect_b32 s25, s31, s45
	s_cselect_b32 s24, s43, s44
	s_add_i32 s47, 0, 0x14000
	v_add_u32_e32 v154, s46, v147
	v_add_u32_e32 v158, s47, v147
	ds_read_b128 v[138:141], v154
	ds_read_b128 v[142:145], v154 offset:1024
	ds_read_b128 v[150:153], v154 offset:2048
	ds_read_b128 v[154:157], v154 offset:3072
	ds_read_b128 v[170:173], v158
	ds_read_b128 v[174:177], v158 offset:1024
	ds_read_b128 v[178:181], v158 offset:2048
	ds_read_b128 v[182:185], v158 offset:3072
	s_add_i32 m0, s63, 0xc000
	ds_read_b128 v[186:189], v149
	ds_read_b128 v[190:193], v149 offset:1024
	ds_read_b128 v[194:197], v149 offset:2048
	ds_read_b128 v[198:201], v149 offset:3072
	ds_read_b128 v[202:205], v149 offset:4096
	ds_read_b128 v[206:209], v149 offset:5120
	ds_read_b128 v[210:213], v149 offset:6144
	ds_read_b128 v[214:217], v149 offset:7168
	global_load_lds_dwordx4 v134, s[66:67]
	s_add_i32 m0, s63, 0xe000
	s_nop 0
	global_load_lds_dwordx4 v136, s[66:67]
	s_waitcnt vmcnt(8) lgkmcnt(0)
	s_barrier
	v_mfma_f32_16x16x32_bf16 v[124:127], v[138:141], v[186:189], v[124:127]
	v_mfma_f32_16x16x32_bf16 v[120:123], v[150:153], v[186:189], v[120:123]
	v_mfma_f32_16x16x32_bf16 v[108:111], v[138:141], v[194:197], v[108:111]
	v_mfma_f32_16x16x32_bf16 v[104:107], v[150:153], v[194:197], v[104:107]
	v_mfma_f32_16x16x32_bf16 v[92:95], v[138:141], v[202:205], v[92:95]
	v_mfma_f32_16x16x32_bf16 v[88:91], v[150:153], v[202:205], v[88:91]
	v_mfma_f32_16x16x32_bf16 v[76:79], v[138:141], v[210:213], v[76:79]
	v_mfma_f32_16x16x32_bf16 v[72:75], v[150:153], v[210:213], v[72:75]
	v_mfma_f32_16x16x32_bf16 v[124:127], v[142:145], v[190:193], v[124:127]
	v_mfma_f32_16x16x32_bf16 v[120:123], v[154:157], v[190:193], v[120:123]
	v_mfma_f32_16x16x32_bf16 v[108:111], v[142:145], v[198:201], v[108:111]
	v_mfma_f32_16x16x32_bf16 v[104:107], v[154:157], v[198:201], v[104:107]
	v_mfma_f32_16x16x32_bf16 v[92:95], v[142:145], v[206:209], v[92:95]
	v_mfma_f32_16x16x32_bf16 v[88:91], v[154:157], v[206:209], v[88:91]
	v_mfma_f32_16x16x32_bf16 v[76:79], v[142:145], v[214:217], v[76:79]
	v_mfma_f32_16x16x32_bf16 v[72:75], v[154:157], v[214:217], v[72:75]
	v_mfma_f32_16x16x32_bf16 v[116:119], v[170:173], v[186:189], v[116:119]
	v_mfma_f32_16x16x32_bf16 v[112:115], v[178:181], v[186:189], v[112:115]
	v_mfma_f32_16x16x32_bf16 v[100:103], v[170:173], v[194:197], v[100:103]
	v_mfma_f32_16x16x32_bf16 v[96:99], v[178:181], v[194:197], v[96:99]
	v_mfma_f32_16x16x32_bf16 v[84:87], v[170:173], v[202:205], v[84:87]
	v_mfma_f32_16x16x32_bf16 v[80:83], v[178:181], v[202:205], v[80:83]
	v_mfma_f32_16x16x32_bf16 v[68:71], v[170:173], v[210:213], v[68:71]
	v_mfma_f32_16x16x32_bf16 v[64:67], v[178:181], v[210:213], v[64:67]
	v_mfma_f32_16x16x32_bf16 v[116:119], v[174:177], v[190:193], v[116:119]
	v_mfma_f32_16x16x32_bf16 v[112:115], v[182:185], v[190:193], v[112:115]
	v_mfma_f32_16x16x32_bf16 v[100:103], v[174:177], v[198:201], v[100:103]
	v_mfma_f32_16x16x32_bf16 v[96:99], v[182:185], v[198:201], v[96:99]
	v_mfma_f32_16x16x32_bf16 v[84:87], v[174:177], v[206:209], v[84:87]
	v_mfma_f32_16x16x32_bf16 v[80:83], v[182:185], v[206:209], v[80:83]
	v_mfma_f32_16x16x32_bf16 v[68:71], v[174:177], v[214:217], v[68:71]
	v_mfma_f32_16x16x32_bf16 v[64:67], v[182:185], v[214:217], v[64:67]
	s_barrier
	s_add_i32 s46, s46, s90
	s_mov_b32 m0, s46
	ds_read_b128 v[186:189], v149 offset:16384
	ds_read_b128 v[190:193], v149 offset:17408
	ds_read_b128 v[194:197], v149 offset:18432
	ds_read_b128 v[198:201], v149 offset:19456
	ds_read_b128 v[202:205], v149 offset:20480
	ds_read_b128 v[206:209], v149 offset:21504
	ds_read_b128 v[210:213], v149 offset:22528
	ds_read_b128 v[214:217], v149 offset:23552
	global_load_lds_dwordx4 v160, s[24:25]
	s_add_i32 m0, s46, 0x2000
	s_add_u32 vcc_lo, s24, 0x40000
	s_addc_u32 vcc_hi, s25, 0
	s_add_i32 s46, s47, s90
	global_load_lds_dwordx4 v132, s[24:25]
	v_lshl_add_u64 v[218:219], vcc, 0, v[160:161]
	s_mov_b32 m0, s46
	s_nop 0
	global_load_lds_dwordx4 v[218:219], off
	v_lshl_add_u64 v[218:219], vcc, 0, v[132:133]
	s_add_i32 m0, s46, 0x2000
	s_nop 0
	global_load_lds_dwordx4 v[218:219], off
	s_mov_b32 m0, s63
	s_nop 0
	global_load_lds_dwordx4 v128, s[72:73]
	s_mov_b32 m0, s91
	s_nop 0
	global_load_lds_dwordx4 v130, s[72:73]
	s_waitcnt vmcnt(8) lgkmcnt(0)
	s_barrier
	v_mfma_f32_16x16x32_bf16 v[60:63], v[138:141], v[186:189], v[60:63]
	v_mfma_f32_16x16x32_bf16 v[56:59], v[150:153], v[186:189], v[56:59]
	v_mfma_f32_16x16x32_bf16 v[44:47], v[138:141], v[194:197], v[44:47]
	v_mfma_f32_16x16x32_bf16 v[40:43], v[150:153], v[194:197], v[40:43]
	v_mfma_f32_16x16x32_bf16 v[28:31], v[138:141], v[202:205], v[28:31]
	v_mfma_f32_16x16x32_bf16 v[24:27], v[150:153], v[202:205], v[24:27]
	v_mfma_f32_16x16x32_bf16 v[12:15], v[138:141], v[210:213], v[12:15]
	v_mfma_f32_16x16x32_bf16 v[8:11], v[150:153], v[210:213], v[8:11]
	v_mfma_f32_16x16x32_bf16 v[60:63], v[142:145], v[190:193], v[60:63]
	v_mfma_f32_16x16x32_bf16 v[56:59], v[154:157], v[190:193], v[56:59]
	v_mfma_f32_16x16x32_bf16 v[44:47], v[142:145], v[198:201], v[44:47]
	v_mfma_f32_16x16x32_bf16 v[40:43], v[154:157], v[198:201], v[40:43]
	v_mfma_f32_16x16x32_bf16 v[28:31], v[142:145], v[206:209], v[28:31]
	v_mfma_f32_16x16x32_bf16 v[24:27], v[154:157], v[206:209], v[24:27]
	v_mfma_f32_16x16x32_bf16 v[12:15], v[142:145], v[214:217], v[12:15]
	v_mfma_f32_16x16x32_bf16 v[8:11], v[154:157], v[214:217], v[8:11]
	v_mfma_f32_16x16x32_bf16 v[52:55], v[170:173], v[186:189], v[52:55]
	v_mfma_f32_16x16x32_bf16 v[48:51], v[178:181], v[186:189], v[48:51]
	v_mfma_f32_16x16x32_bf16 v[36:39], v[170:173], v[194:197], v[36:39]
	v_mfma_f32_16x16x32_bf16 v[32:35], v[178:181], v[194:197], v[32:35]
	v_mfma_f32_16x16x32_bf16 v[20:23], v[170:173], v[202:205], v[20:23]
	v_mfma_f32_16x16x32_bf16 v[16:19], v[178:181], v[202:205], v[16:19]
	v_mfma_f32_16x16x32_bf16 v[4:7], v[170:173], v[210:213], v[4:7]
	v_mfma_f32_16x16x32_bf16 v[0:3], v[178:181], v[210:213], v[0:3]
	v_mfma_f32_16x16x32_bf16 v[52:55], v[174:177], v[190:193], v[52:55]
	v_mfma_f32_16x16x32_bf16 v[48:51], v[182:185], v[190:193], v[48:51]
	v_mfma_f32_16x16x32_bf16 v[36:39], v[174:177], v[198:201], v[36:39]
	v_mfma_f32_16x16x32_bf16 v[32:35], v[182:185], v[198:201], v[32:35]
	v_mfma_f32_16x16x32_bf16 v[20:23], v[174:177], v[206:209], v[20:23]
	v_mfma_f32_16x16x32_bf16 v[16:19], v[182:185], v[206:209], v[16:19]
	v_mfma_f32_16x16x32_bf16 v[4:7], v[174:177], v[214:217], v[4:7]
	v_mfma_f32_16x16x32_bf16 v[0:3], v[182:185], v[214:217], v[0:3]
	s_barrier
; #define PG8_STAGE(bufoff, gbase, voff) do { _Pragma("unroll") for (int _i = 0; _i < 2; ++_i) \
;         __builtin_amdgcn_global_load_lds((const unsigned*)((const char*)(gbase) + (voff)[_i]), (LAS unsigned*)(lds + (bufoff) + ldsw + _i * 8192), 16, 0, 0); } while (0)
; #define PG8_LDA(dst, b, h) do { _Pragma("unroll") for (int m = 0; m < 4; ++m) _Pragma("unroll") for (int k = 0; k < 2; ++k) dst[m][k] = *(const LAS bf16x8*)(lds + PG8_SA(b, h) + aoff + m * 2048 + k * 1024); } while (0)
; #define PG8_LDB(dst, b, h) do { _Pragma("unroll") for (int n = 0; n < 2; ++n) _Pragma("unroll") for (int k = 0; k < 2; ++k) dst[n][k] = *(const LAS bf16x8*)(lds + PG8_SB(b, h) + boff + n * 2048 + k * 1024); } while (0)
; #define PG8_WAIT_V(n) asm volatile("s_waitcnt vmcnt(" #n ")" ::: "memory")
; template <class Epi, class Sched, bool ALIGN_EPI = true, bool SP2 = true>
; __device__ __forceinline__ void gemm_phase(LAS unsigned char* lds, const Gemm g, const Sched& S, const Epi& E) {
;     ...
;         for (int t = 0; t < nt; t += 2) {
;             const bool last = (t == nt - 2);
;             const char* a1 = cA + (size_t)(t + 1) * kstep;
;             const char* a2 = last ? nA : cA + (size_t)(t + 2) * kstep; const char* b2 = last ? nB : cB + (size_t)(t + 2) * kstep;
;             const char* a3 = a2 + kstep; const char* b3 = b2 + kstep;
;             if constexpr (SP2) {
;             PG8_LDB(B0, 0, 0); PG8_LDB(B1, 0, 1); PG8_SCHED; PG8_LDA(At, 0, 0); PG8_STAGE(PG8_SA(1, 1), a1 + hstep, voffA);
;             PG8_WAIT_V(8); PG8_WAIT_L(0); PG8_BAR; PG8_MMA(0, 0, At, B0); PG8_MMA(0, 1, At, B1); PG8_BAR; PG8_SCHED;
;             PG8_LDA(At, 0, 1); PG8_STAGE(PG8_SB(0, 0), b2, voffB); PG8_STAGE(PG8_SB(0, 1), b2 + hstep, voffB); PG8_STAGE(PG8_SA(0, 0), a2, voffA);
;             PG8_WAIT_V(8); PG8_WAIT_L(0); PG8_BAR; PG8_MMA(1, 0, At, B0); PG8_MMA(1, 1, At, B1); PG8_BAR; PG8_SCHED;
;             PG8_LDB(B0, 1, 0); PG8_LDB(B1, 1, 1); PG8_SCHED; PG8_LDA(At, 1, 0); PG8_STAGE(PG8_SA(0, 1), a2 + hstep, voffA);
;             PG8_WAIT_V(8); PG8_WAIT_L(0); PG8_BAR; PG8_MMA(0, 0, At, B0); PG8_MMA(0, 1, At, B1); PG8_BAR; PG8_SCHED;
;             PG8_LDA(At, 1, 1); PG8_STAGE(PG8_SB(1, 0), b3, voffB); PG8_STAGE(PG8_SB(1, 1), b3 + hstep, voffB); PG8_STAGE(PG8_SA(1, 0), a3, voffA);
;             PG8_WAIT_V(8); PG8_WAIT_L(0); PG8_BAR; PG8_MMA(1, 0, At, B0); PG8_MMA(1, 1, At, B1); PG8_BAR; PG8_SCHED;
	s_add_i32 s46, 0, 0x18000
	s_add_i32 s47, 0, 0x1c000
	v_add_u32_e32 v154, s46, v147
	v_add_u32_e32 v182, s47, v147
	ds_read_b128 v[138:141], v154
	ds_read_b128 v[142:145], v154 offset:1024
	ds_read_b128 v[150:153], v154 offset:2048
	ds_read_b128 v[154:157], v154 offset:3072
	ds_read_b128 v[170:173], v182
	ds_read_b128 v[174:177], v182 offset:1024
	ds_read_b128 v[178:181], v182 offset:2048
	ds_read_b128 v[182:185], v182 offset:3072
	s_add_u32 s72, s72, 0x40000
	s_addc_u32 s73, s73, 0
	s_mov_b32 m0, s92
	ds_read_b128 v[186:189], v149 offset:32768
	ds_read_b128 v[190:193], v149 offset:33792
	ds_read_b128 v[194:197], v149 offset:34816
	ds_read_b128 v[198:201], v149 offset:35840
	ds_read_b128 v[202:205], v149 offset:36864
	ds_read_b128 v[206:209], v149 offset:37888
	ds_read_b128 v[210:213], v149 offset:38912
	ds_read_b128 v[214:217], v149 offset:39936
	global_load_lds_dwordx4 v128, s[72:73]
	s_mov_b32 m0, s93
	s_nop 0
	global_load_lds_dwordx4 v130, s[72:73]
	s_waitcnt vmcnt(8) lgkmcnt(0)
	s_barrier
	v_mfma_f32_16x16x32_bf16 v[124:127], v[138:141], v[186:189], v[124:127]
	v_mfma_f32_16x16x32_bf16 v[120:123], v[150:153], v[186:189], v[120:123]
	v_mfma_f32_16x16x32_bf16 v[108:111], v[138:141], v[194:197], v[108:111]
	v_mfma_f32_16x16x32_bf16 v[104:107], v[150:153], v[194:197], v[104:107]
	v_mfma_f32_16x16x32_bf16 v[92:95], v[138:141], v[202:205], v[92:95]
	v_mfma_f32_16x16x32_bf16 v[88:91], v[150:153], v[202:205], v[88:91]
	v_mfma_f32_16x16x32_bf16 v[76:79], v[138:141], v[210:213], v[76:79]
	v_mfma_f32_16x16x32_bf16 v[72:75], v[150:153], v[210:213], v[72:75]
	v_mfma_f32_16x16x32_bf16 v[124:127], v[142:145], v[190:193], v[124:127]
	v_mfma_f32_16x16x32_bf16 v[120:123], v[154:157], v[190:193], v[120:123]
	v_mfma_f32_16x16x32_bf16 v[108:111], v[142:145], v[198:201], v[108:111]
	v_mfma_f32_16x16x32_bf16 v[104:107], v[154:157], v[198:201], v[104:107]
	v_mfma_f32_16x16x32_bf16 v[92:95], v[142:145], v[206:209], v[92:95]
	v_mfma_f32_16x16x32_bf16 v[88:91], v[154:157], v[206:209], v[88:91]
	v_mfma_f32_16x16x32_bf16 v[76:79], v[142:145], v[214:217], v[76:79]
	v_mfma_f32_16x16x32_bf16 v[72:75], v[154:157], v[214:217], v[72:75]
	v_mfma_f32_16x16x32_bf16 v[116:119], v[170:173], v[186:189], v[116:119]
	v_mfma_f32_16x16x32_bf16 v[112:115], v[178:181], v[186:189], v[112:115]
	v_mfma_f32_16x16x32_bf16 v[100:103], v[170:173], v[194:197], v[100:103]
	v_mfma_f32_16x16x32_bf16 v[96:99], v[178:181], v[194:197], v[96:99]
	v_mfma_f32_16x16x32_bf16 v[84:87], v[170:173], v[202:205], v[84:87]
	v_mfma_f32_16x16x32_bf16 v[80:83], v[178:181], v[202:205], v[80:83]
	v_mfma_f32_16x16x32_bf16 v[68:71], v[170:173], v[210:213], v[68:71]
	v_mfma_f32_16x16x32_bf16 v[64:67], v[178:181], v[210:213], v[64:67]
	v_mfma_f32_16x16x32_bf16 v[116:119], v[174:177], v[190:193], v[116:119]
	v_mfma_f32_16x16x32_bf16 v[112:115], v[182:185], v[190:193], v[112:115]
	v_mfma_f32_16x16x32_bf16 v[100:103], v[174:177], v[198:201], v[100:103]
	v_mfma_f32_16x16x32_bf16 v[96:99], v[182:185], v[198:201], v[96:99]
	v_mfma_f32_16x16x32_bf16 v[84:87], v[174:177], v[206:209], v[84:87]
	v_mfma_f32_16x16x32_bf16 v[80:83], v[182:185], v[206:209], v[80:83]
	v_mfma_f32_16x16x32_bf16 v[68:71], v[174:177], v[214:217], v[68:71]
	v_mfma_f32_16x16x32_bf16 v[64:67], v[182:185], v[214:217], v[64:67]
	s_barrier
	s_add_i32 s46, s46, s90
	s_mov_b32 m0, s46
	ds_read_b128 v[186:189], v149 offset:49152
	ds_read_b128 v[190:193], v149 offset:50176
	ds_read_b128 v[194:197], v149 offset:51200
	ds_read_b128 v[198:201], v149 offset:52224
	ds_read_b128 v[202:205], v149 offset:53248
	ds_read_b128 v[206:209], v149 offset:54272
	ds_read_b128 v[210:213], v149 offset:55296
	ds_read_b128 v[214:217], v149 offset:56320
	s_add_u32 s98, s24, 0x80
	s_addc_u32 s99, s25, 0
	global_load_lds_dwordx4 v160, s[98:99]
	s_add_i32 m0, s46, 0x2000
	s_add_u32 s24, s24, 0x40080
	s_addc_u32 s25, s25, 0
	s_add_i32 s46, s47, s90
	global_load_lds_dwordx4 v132, s[98:99]
	s_mov_b32 m0, s46
	s_nop 0
	global_load_lds_dwordx4 v160, s[24:25]
	s_add_i32 m0, s46, 0x2000
	s_nop 0
	global_load_lds_dwordx4 v132, s[24:25]
	s_mov_b32 m0, s94
	s_nop 0
	s_add_u32 s98, s72, 0xfffc0080
	s_addc_u32 s99, s73, -1
	global_load_lds_dwordx4 v128, s[98:99]
	s_mov_b32 m0, s95
	s_nop 0
	global_load_lds_dwordx4 v130, s[98:99]
	s_waitcnt vmcnt(8) lgkmcnt(0)
	s_barrier
	v_mfma_f32_16x16x32_bf16 v[60:63], v[138:141], v[186:189], v[60:63]
	v_mfma_f32_16x16x32_bf16 v[56:59], v[150:153], v[186:189], v[56:59]
	v_mfma_f32_16x16x32_bf16 v[44:47], v[138:141], v[194:197], v[44:47]
	v_mfma_f32_16x16x32_bf16 v[40:43], v[150:153], v[194:197], v[40:43]
	v_mfma_f32_16x16x32_bf16 v[28:31], v[138:141], v[202:205], v[28:31]
	v_mfma_f32_16x16x32_bf16 v[24:27], v[150:153], v[202:205], v[24:27]
	v_mfma_f32_16x16x32_bf16 v[12:15], v[138:141], v[210:213], v[12:15]
	v_mfma_f32_16x16x32_bf16 v[8:11], v[150:153], v[210:213], v[8:11]
	v_mfma_f32_16x16x32_bf16 v[60:63], v[142:145], v[190:193], v[60:63]
	v_mfma_f32_16x16x32_bf16 v[56:59], v[154:157], v[190:193], v[56:59]
	v_mfma_f32_16x16x32_bf16 v[44:47], v[142:145], v[198:201], v[44:47]
	v_mfma_f32_16x16x32_bf16 v[40:43], v[154:157], v[198:201], v[40:43]
	v_mfma_f32_16x16x32_bf16 v[28:31], v[142:145], v[206:209], v[28:31]
	v_mfma_f32_16x16x32_bf16 v[24:27], v[154:157], v[206:209], v[24:27]
	v_mfma_f32_16x16x32_bf16 v[12:15], v[142:145], v[214:217], v[12:15]
	v_mfma_f32_16x16x32_bf16 v[8:11], v[154:157], v[214:217], v[8:11]
	v_mfma_f32_16x16x32_bf16 v[52:55], v[170:173], v[186:189], v[52:55]
	v_mfma_f32_16x16x32_bf16 v[48:51], v[178:181], v[186:189], v[48:51]
	v_mfma_f32_16x16x32_bf16 v[36:39], v[170:173], v[194:197], v[36:39]
	v_mfma_f32_16x16x32_bf16 v[32:35], v[178:181], v[194:197], v[32:35]
	v_mfma_f32_16x16x32_bf16 v[20:23], v[170:173], v[202:205], v[20:23]
	v_mfma_f32_16x16x32_bf16 v[16:19], v[178:181], v[202:205], v[16:19]
	v_mfma_f32_16x16x32_bf16 v[4:7], v[170:173], v[210:213], v[4:7]
	v_mfma_f32_16x16x32_bf16 v[0:3], v[178:181], v[210:213], v[0:3]
	v_mfma_f32_16x16x32_bf16 v[52:55], v[174:177], v[190:193], v[52:55]
	v_mfma_f32_16x16x32_bf16 v[48:51], v[182:185], v[190:193], v[48:51]
	v_mfma_f32_16x16x32_bf16 v[36:39], v[174:177], v[198:201], v[36:39]
	v_mfma_f32_16x16x32_bf16 v[32:35], v[182:185], v[198:201], v[32:35]
	v_mfma_f32_16x16x32_bf16 v[20:23], v[174:177], v[206:209], v[20:23]
	v_mfma_f32_16x16x32_bf16 v[16:19], v[182:185], v[206:209], v[16:19]
	v_mfma_f32_16x16x32_bf16 v[4:7], v[174:177], v[214:217], v[4:7]
	v_mfma_f32_16x16x32_bf16 v[0:3], v[182:185], v[214:217], v[0:3]
	s_barrier
	s_add_i32 s53, s53, 2
	s_add_u32 s66, s66, 0x100
	s_addc_u32 s67, s67, 0
	s_add_u32 s44, s44, 0x100
	s_addc_u32 s45, s45, 0
	s_cmp_gt_u32 s53, 13
	s_cbranch_scc0 .LBB0_187
	s_setprio 0
	s_and_b64 vcc, exec, s[18:19]
	s_cbranch_vccz .LBB0_190
	s_barrier

; #define PG8_STAGE(bufoff, gbase, voff) do { _Pragma("unroll") for (int _i = 0; _i < 2; ++_i) \
;         __builtin_amdgcn_global_load_lds((const unsigned*)((const char*)(gbase) + (voff)[_i]), (LAS unsigned*)(lds + (bufoff) + ldsw + _i * 8192), 16, 0, 0); } while (0)
; #define PG8_LDA(dst, b, h) do { _Pragma("unroll") for (int m = 0; m < 4; ++m) _Pragma("unroll") for (int k = 0; k < 2; ++k) dst[m][k] = *(const LAS bf16x8*)(lds + PG8_SA(b, h) + aoff + m * 2048 + k * 1024); } while (0)
; #define PG8_LDB(dst, b, h) do { _Pragma("unroll") for (int n = 0; n < 2; ++n) _Pragma("unroll") for (int k = 0; k < 2; ++k) dst[n][k] = *(const LAS bf16x8*)(lds + PG8_SB(b, h) + boff + n * 2048 + k * 1024); } while (0)
; #define PG8_WAIT_V(n) asm volatile("s_waitcnt vmcnt(" #n ")" ::: "memory")
; template <class Epi, class Sched, bool ALIGN_EPI = true, bool SP2 = true>
; __device__ __forceinline__ void gemm_phase(LAS unsigned char* lds, const Gemm g, const Sched& S, const Epi& E) {
;     ...
;         for (int t = 0; t < nt; t += 2) {
;             const bool last = (t == nt - 2);
;             const char* a1 = cA + (size_t)(t + 1) * kstep;
;             const char* a2 = last ? nA : cA + (size_t)(t + 2) * kstep; const char* b2 = last ? nB : cB + (size_t)(t + 2) * kstep;
;             const char* a3 = a2 + kstep; const char* b3 = b2 + kstep;
;             if constexpr (SP2) {
;             PG8_LDB(B0, 0, 0); PG8_LDB(B1, 0, 1); PG8_SCHED; PG8_LDA(At, 0, 0); PG8_STAGE(PG8_SA(1, 1), a1 + hstep, voffA);
;             PG8_WAIT_V(8); PG8_WAIT_L(0); PG8_BAR; PG8_MMA(0, 0, At, B0); PG8_MMA(0, 1, At, B1); PG8_BAR; PG8_SCHED;
;             PG8_LDA(At, 0, 1); PG8_STAGE(PG8_SB(0, 0), b2, voffB); PG8_STAGE(PG8_SB(0, 1), b2 + hstep, voffB); PG8_STAGE(PG8_SA(0, 0), a2, voffA);
;             PG8_WAIT_V(8); PG8_WAIT_L(0); PG8_BAR; PG8_MMA(1, 0, At, B0); PG8_MMA(1, 1, At, B1); PG8_BAR; PG8_SCHED;
;             PG8_LDB(B0, 1, 0); PG8_LDB(B1, 1, 1); PG8_SCHED; PG8_LDA(At, 1, 0); PG8_STAGE(PG8_SA(0, 1), a2 + hstep, voffA);
;             PG8_WAIT_V(8); PG8_WAIT_L(0); PG8_BAR; PG8_MMA(0, 0, At, B0); PG8_MMA(0, 1, At, B1); PG8_BAR; PG8_SCHED;
;             PG8_LDA(At, 1, 1); PG8_STAGE(PG8_SB(1, 0), b3, voffB); PG8_STAGE(PG8_SB(1, 1), b3 + hstep, voffB); PG8_STAGE(PG8_SA(1, 0), a3, voffA);
;             PG8_WAIT_V(8); PG8_WAIT_L(0); PG8_BAR; PG8_MMA(1, 0, At, B0); PG8_MMA(1, 1, At, B1); PG8_BAR; PG8_SCHED;
.Lprio_skip_211:
.LBB0_211:
	s_add_u32 s24, s60, 0xfffc0080
	s_addc_u32 s25, s61, -1
	s_add_i32 s46, 0, 0x10000
	s_cmp_eq_u32 s45, 12
	s_cselect_b32 s63, s2, s25
	s_cselect_b32 s62, s3, s24
	s_cselect_b32 s25, s17, s44
	s_cselect_b32 s24, s19, s43
	s_add_i32 s47, 0, 0x14000
	v_add_u32_e32 v154, s46, v147
	v_add_u32_e32 v158, s47, v147
	ds_read_b128 v[138:141], v154
	ds_read_b128 v[142:145], v154 offset:1024
	ds_read_b128 v[150:153], v154 offset:2048
	ds_read_b128 v[154:157], v154 offset:3072
	ds_read_b128 v[170:173], v158
	ds_read_b128 v[174:177], v158 offset:1024
	ds_read_b128 v[178:181], v158 offset:2048
	ds_read_b128 v[182:185], v158 offset:3072
	s_add_i32 m0, s55, 0xc000
	ds_read_b128 v[186:189], v149
	ds_read_b128 v[190:193], v149 offset:1024
	ds_read_b128 v[194:197], v149 offset:2048
	ds_read_b128 v[198:201], v149 offset:3072
	ds_read_b128 v[202:205], v149 offset:4096
	ds_read_b128 v[206:209], v149 offset:5120
	ds_read_b128 v[210:213], v149 offset:6144
	ds_read_b128 v[214:217], v149 offset:7168
	global_load_lds_dwordx4 v134, s[60:61]
	s_add_i32 m0, s55, 0xe000
	s_nop 0
	global_load_lds_dwordx4 v136, s[60:61]
	s_waitcnt vmcnt(8) lgkmcnt(0)
	s_barrier
	v_mfma_f32_16x16x32_bf16 v[124:127], v[138:141], v[186:189], v[124:127]
	v_mfma_f32_16x16x32_bf16 v[120:123], v[150:153], v[186:189], v[120:123]
	v_mfma_f32_16x16x32_bf16 v[108:111], v[138:141], v[194:197], v[108:111]
	v_mfma_f32_16x16x32_bf16 v[104:107], v[150:153], v[194:197], v[104:107]
	v_mfma_f32_16x16x32_bf16 v[92:95], v[138:141], v[202:205], v[92:95]
	v_mfma_f32_16x16x32_bf16 v[88:91], v[150:153], v[202:205], v[88:91]
	v_mfma_f32_16x16x32_bf16 v[76:79], v[138:141], v[210:213], v[76:79]
	v_mfma_f32_16x16x32_bf16 v[72:75], v[150:153], v[210:213], v[72:75]
	v_mfma_f32_16x16x32_bf16 v[124:127], v[142:145], v[190:193], v[124:127]
	v_mfma_f32_16x16x32_bf16 v[120:123], v[154:157], v[190:193], v[120:123]
	v_mfma_f32_16x16x32_bf16 v[108:111], v[142:145], v[198:201], v[108:111]
	v_mfma_f32_16x16x32_bf16 v[104:107], v[154:157], v[198:201], v[104:107]
	v_mfma_f32_16x16x32_bf16 v[92:95], v[142:145], v[206:209], v[92:95]
	v_mfma_f32_16x16x32_bf16 v[88:91], v[154:157], v[206:209], v[88:91]
	v_mfma_f32_16x16x32_bf16 v[76:79], v[142:145], v[214:217], v[76:79]
	v_mfma_f32_16x16x32_bf16 v[72:75], v[154:157], v[214:217], v[72:75]
	v_mfma_f32_16x16x32_bf16 v[116:119], v[170:173], v[186:189], v[116:119]
	v_mfma_f32_16x16x32_bf16 v[112:115], v[178:181], v[186:189], v[112:115]
	v_mfma_f32_16x16x32_bf16 v[100:103], v[170:173], v[194:197], v[100:103]
	v_mfma_f32_16x16x32_bf16 v[96:99], v[178:181], v[194:197], v[96:99]
	v_mfma_f32_16x16x32_bf16 v[84:87], v[170:173], v[202:205], v[84:87]
	v_mfma_f32_16x16x32_bf16 v[80:83], v[178:181], v[202:205], v[80:83]
	v_mfma_f32_16x16x32_bf16 v[68:71], v[170:173], v[210:213], v[68:71]
	v_mfma_f32_16x16x32_bf16 v[64:67], v[178:181], v[210:213], v[64:67]
	v_mfma_f32_16x16x32_bf16 v[116:119], v[174:177], v[190:193], v[116:119]
	v_mfma_f32_16x16x32_bf16 v[112:115], v[182:185], v[190:193], v[112:115]
	v_mfma_f32_16x16x32_bf16 v[100:103], v[174:177], v[198:201], v[100:103]
	v_mfma_f32_16x16x32_bf16 v[96:99], v[182:185], v[198:201], v[96:99]
	v_mfma_f32_16x16x32_bf16 v[84:87], v[174:177], v[206:209], v[84:87]
	v_mfma_f32_16x16x32_bf16 v[80:83], v[182:185], v[206:209], v[80:83]
	v_mfma_f32_16x16x32_bf16 v[68:71], v[174:177], v[214:217], v[68:71]
	v_mfma_f32_16x16x32_bf16 v[64:67], v[182:185], v[214:217], v[64:67]
	s_barrier
	s_add_i32 s46, s46, s73
	s_mov_b32 m0, s46
	ds_read_b128 v[186:189], v149 offset:16384
	ds_read_b128 v[190:193], v149 offset:17408
	ds_read_b128 v[194:197], v149 offset:18432
	ds_read_b128 v[198:201], v149 offset:19456
	ds_read_b128 v[202:205], v149 offset:20480
	ds_read_b128 v[206:209], v149 offset:21504
	ds_read_b128 v[210:213], v149 offset:22528
	ds_read_b128 v[214:217], v149 offset:23552
	global_load_lds_dwordx4 v160, s[24:25]
	s_add_i32 m0, s46, 0x2000
	s_add_u32 s94, s24, 0x40000
	s_addc_u32 s95, s25, 0
	s_add_i32 s46, s47, s73
	global_load_lds_dwordx4 v132, s[24:25]
	s_mov_b32 m0, s46
	s_nop 0
	global_load_lds_dwordx4 v160, s[94:95]
	s_add_i32 m0, s46, 0x2000
	s_nop 0
	global_load_lds_dwordx4 v132, s[94:95]
	s_mov_b32 m0, s55
	s_nop 0
	global_load_lds_dwordx4 v128, s[62:63]
	s_mov_b32 m0, s79
	s_nop 0
	global_load_lds_dwordx4 v130, s[62:63]
	s_waitcnt vmcnt(8) lgkmcnt(0)
	s_barrier
	v_mfma_f32_16x16x32_bf16 v[60:63], v[138:141], v[186:189], v[60:63]
	v_mfma_f32_16x16x32_bf16 v[56:59], v[150:153], v[186:189], v[56:59]
	v_mfma_f32_16x16x32_bf16 v[44:47], v[138:141], v[194:197], v[44:47]
	v_mfma_f32_16x16x32_bf16 v[40:43], v[150:153], v[194:197], v[40:43]
	v_mfma_f32_16x16x32_bf16 v[28:31], v[138:141], v[202:205], v[28:31]
	v_mfma_f32_16x16x32_bf16 v[24:27], v[150:153], v[202:205], v[24:27]
	v_mfma_f32_16x16x32_bf16 v[12:15], v[138:141], v[210:213], v[12:15]
	v_mfma_f32_16x16x32_bf16 v[8:11], v[150:153], v[210:213], v[8:11]
	v_mfma_f32_16x16x32_bf16 v[60:63], v[142:145], v[190:193], v[60:63]
	v_mfma_f32_16x16x32_bf16 v[56:59], v[154:157], v[190:193], v[56:59]
	v_mfma_f32_16x16x32_bf16 v[44:47], v[142:145], v[198:201], v[44:47]
	v_mfma_f32_16x16x32_bf16 v[40:43], v[154:157], v[198:201], v[40:43]
	v_mfma_f32_16x16x32_bf16 v[28:31], v[142:145], v[206:209], v[28:31]
	v_mfma_f32_16x16x32_bf16 v[24:27], v[154:157], v[206:209], v[24:27]
	v_mfma_f32_16x16x32_bf16 v[12:15], v[142:145], v[214:217], v[12:15]
	v_mfma_f32_16x16x32_bf16 v[8:11], v[154:157], v[214:217], v[8:11]
	v_mfma_f32_16x16x32_bf16 v[52:55], v[170:173], v[186:189], v[52:55]
	v_mfma_f32_16x16x32_bf16 v[48:51], v[178:181], v[186:189], v[48:51]
	v_mfma_f32_16x16x32_bf16 v[36:39], v[170:173], v[194:197], v[36:39]
	v_mfma_f32_16x16x32_bf16 v[32:35], v[178:181], v[194:197], v[32:35]
	v_mfma_f32_16x16x32_bf16 v[20:23], v[170:173], v[202:205], v[20:23]
	v_mfma_f32_16x16x32_bf16 v[16:19], v[178:181], v[202:205], v[16:19]
	v_mfma_f32_16x16x32_bf16 v[4:7], v[170:173], v[210:213], v[4:7]
	v_mfma_f32_16x16x32_bf16 v[0:3], v[178:181], v[210:213], v[0:3]
	v_mfma_f32_16x16x32_bf16 v[52:55], v[174:177], v[190:193], v[52:55]
	v_mfma_f32_16x16x32_bf16 v[48:51], v[182:185], v[190:193], v[48:51]
	v_mfma_f32_16x16x32_bf16 v[36:39], v[174:177], v[198:201], v[36:39]
	v_mfma_f32_16x16x32_bf16 v[32:35], v[182:185], v[198:201], v[32:35]
	v_mfma_f32_16x16x32_bf16 v[20:23], v[174:177], v[206:209], v[20:23]
	v_mfma_f32_16x16x32_bf16 v[16:19], v[182:185], v[206:209], v[16:19]
	v_mfma_f32_16x16x32_bf16 v[4:7], v[174:177], v[214:217], v[4:7]
	v_mfma_f32_16x16x32_bf16 v[0:3], v[182:185], v[214:217], v[0:3]
	s_barrier
; #define PG8_STAGE(bufoff, gbase, voff) do { _Pragma("unroll") for (int _i = 0; _i < 2; ++_i) \
;         __builtin_amdgcn_global_load_lds((const unsigned*)((const char*)(gbase) + (voff)[_i]), (LAS unsigned*)(lds + (bufoff) + ldsw + _i * 8192), 16, 0, 0); } while (0)
; #define PG8_LDA(dst, b, h) do { _Pragma("unroll") for (int m = 0; m < 4; ++m) _Pragma("unroll") for (int k = 0; k < 2; ++k) dst[m][k] = *(const LAS bf16x8*)(lds + PG8_SA(b, h) + aoff + m * 2048 + k * 1024); } while (0)
; #define PG8_LDB(dst, b, h) do { _Pragma("unroll") for (int n = 0; n < 2; ++n) _Pragma("unroll") for (int k = 0; k < 2; ++k) dst[n][k] = *(const LAS bf16x8*)(lds + PG8_SB(b, h) + boff + n * 2048 + k * 1024); } while (0)
; #define PG8_WAIT_V(n) asm volatile("s_waitcnt vmcnt(" #n ")" ::: "memory")
; template <class Epi, class Sched, bool ALIGN_EPI = true, bool SP2 = true>
; __device__ __forceinline__ void gemm_phase(LAS unsigned char* lds, const Gemm g, const Sched& S, const Epi& E) {
;     ...
;         for (int t = 0; t < nt; t += 2) {
;             const bool last = (t == nt - 2);
;             const char* a1 = cA + (size_t)(t + 1) * kstep;
;             const char* a2 = last ? nA : cA + (size_t)(t + 2) * kstep; const char* b2 = last ? nB : cB + (size_t)(t + 2) * kstep;
;             const char* a3 = a2 + kstep; const char* b3 = b2 + kstep;
;             if constexpr (SP2) {
;             PG8_LDB(B0, 0, 0); PG8_LDB(B1, 0, 1); PG8_SCHED; PG8_LDA(At, 0, 0); PG8_STAGE(PG8_SA(1, 1), a1 + hstep, voffA);
;             PG8_WAIT_V(8); PG8_WAIT_L(0); PG8_BAR; PG8_MMA(0, 0, At, B0); PG8_MMA(0, 1, At, B1); PG8_BAR; PG8_SCHED;
;             PG8_LDA(At, 0, 1); PG8_STAGE(PG8_SB(0, 0), b2, voffB); PG8_STAGE(PG8_SB(0, 1), b2 + hstep, voffB); PG8_STAGE(PG8_SA(0, 0), a2, voffA);
;             PG8_WAIT_V(8); PG8_WAIT_L(0); PG8_BAR; PG8_MMA(1, 0, At, B0); PG8_MMA(1, 1, At, B1); PG8_BAR; PG8_SCHED;
;             PG8_LDB(B0, 1, 0); PG8_LDB(B1, 1, 1); PG8_SCHED; PG8_LDA(At, 1, 0); PG8_STAGE(PG8_SA(0, 1), a2 + hstep, voffA);
;             PG8_WAIT_V(8); PG8_WAIT_L(0); PG8_BAR; PG8_MMA(0, 0, At, B0); PG8_MMA(0, 1, At, B1); PG8_BAR; PG8_SCHED;
;             PG8_LDA(At, 1, 1); PG8_STAGE(PG8_SB(1, 0), b3, voffB); PG8_STAGE(PG8_SB(1, 1), b3 + hstep, voffB); PG8_STAGE(PG8_SA(1, 0), a3, voffA);
;             PG8_WAIT_V(8); PG8_WAIT_L(0); PG8_BAR; PG8_MMA(1, 0, At, B0); PG8_MMA(1, 1, At, B1); PG8_BAR; PG8_SCHED;
	s_add_i32 s46, 0, 0x18000
	s_add_i32 s47, 0, 0x1c000
	v_add_u32_e32 v154, s46, v147
	v_add_u32_e32 v182, s47, v147
	ds_read_b128 v[138:141], v154
	ds_read_b128 v[142:145], v154 offset:1024
	ds_read_b128 v[150:153], v154 offset:2048
	ds_read_b128 v[154:157], v154 offset:3072
	ds_read_b128 v[170:173], v182
	ds_read_b128 v[174:177], v182 offset:1024
	ds_read_b128 v[178:181], v182 offset:2048
	ds_read_b128 v[182:185], v182 offset:3072
	s_add_u32 s62, s62, 0x40000
	s_addc_u32 s63, s63, 0
	s_mov_b32 m0, s82
	ds_read_b128 v[186:189], v149 offset:32768
	ds_read_b128 v[190:193], v149 offset:33792
	ds_read_b128 v[194:197], v149 offset:34816
	ds_read_b128 v[198:201], v149 offset:35840
	ds_read_b128 v[202:205], v149 offset:36864
	ds_read_b128 v[206:209], v149 offset:37888
	ds_read_b128 v[210:213], v149 offset:38912
	ds_read_b128 v[214:217], v149 offset:39936
	global_load_lds_dwordx4 v128, s[62:63]
	s_mov_b32 m0, s83
	s_nop 0
	global_load_lds_dwordx4 v130, s[62:63]
	s_waitcnt vmcnt(8) lgkmcnt(0)
	s_barrier
	v_mfma_f32_16x16x32_bf16 v[124:127], v[138:141], v[186:189], v[124:127]
	v_mfma_f32_16x16x32_bf16 v[120:123], v[150:153], v[186:189], v[120:123]
	v_mfma_f32_16x16x32_bf16 v[108:111], v[138:141], v[194:197], v[108:111]
	v_mfma_f32_16x16x32_bf16 v[104:107], v[150:153], v[194:197], v[104:107]
	v_mfma_f32_16x16x32_bf16 v[92:95], v[138:141], v[202:205], v[92:95]
	v_mfma_f32_16x16x32_bf16 v[88:91], v[150:153], v[202:205], v[88:91]
	v_mfma_f32_16x16x32_bf16 v[76:79], v[138:141], v[210:213], v[76:79]
	v_mfma_f32_16x16x32_bf16 v[72:75], v[150:153], v[210:213], v[72:75]
	v_mfma_f32_16x16x32_bf16 v[124:127], v[142:145], v[190:193], v[124:127]
	v_mfma_f32_16x16x32_bf16 v[120:123], v[154:157], v[190:193], v[120:123]
	v_mfma_f32_16x16x32_bf16 v[108:111], v[142:145], v[198:201], v[108:111]
	v_mfma_f32_16x16x32_bf16 v[104:107], v[154:157], v[198:201], v[104:107]
	v_mfma_f32_16x16x32_bf16 v[92:95], v[142:145], v[206:209], v[92:95]
	v_mfma_f32_16x16x32_bf16 v[88:91], v[154:157], v[206:209], v[88:91]
	v_mfma_f32_16x16x32_bf16 v[76:79], v[142:145], v[214:217], v[76:79]
	v_mfma_f32_16x16x32_bf16 v[72:75], v[154:157], v[214:217], v[72:75]
	v_mfma_f32_16x16x32_bf16 v[116:119], v[170:173], v[186:189], v[116:119]
	v_mfma_f32_16x16x32_bf16 v[112:115], v[178:181], v[186:189], v[112:115]
	v_mfma_f32_16x16x32_bf16 v[100:103], v[170:173], v[194:197], v[100:103]
	v_mfma_f32_16x16x32_bf16 v[96:99], v[178:181], v[194:197], v[96:99]
	v_mfma_f32_16x16x32_bf16 v[84:87], v[170:173], v[202:205], v[84:87]
	v_mfma_f32_16x16x32_bf16 v[80:83], v[178:181], v[202:205], v[80:83]
	v_mfma_f32_16x16x32_bf16 v[68:71], v[170:173], v[210:213], v[68:71]
	v_mfma_f32_16x16x32_bf16 v[64:67], v[178:181], v[210:213], v[64:67]
	v_mfma_f32_16x16x32_bf16 v[116:119], v[174:177], v[190:193], v[116:119]
	v_mfma_f32_16x16x32_bf16 v[112:115], v[182:185], v[190:193], v[112:115]
	v_mfma_f32_16x16x32_bf16 v[100:103], v[174:177], v[198:201], v[100:103]
	v_mfma_f32_16x16x32_bf16 v[96:99], v[182:185], v[198:201], v[96:99]
	v_mfma_f32_16x16x32_bf16 v[84:87], v[174:177], v[206:209], v[84:87]
	v_mfma_f32_16x16x32_bf16 v[80:83], v[182:185], v[206:209], v[80:83]
	v_mfma_f32_16x16x32_bf16 v[68:71], v[174:177], v[214:217], v[68:71]
	v_mfma_f32_16x16x32_bf16 v[64:67], v[182:185], v[214:217], v[64:67]
	s_barrier
	s_add_i32 s46, s46, s73
	s_mov_b32 m0, s46
	ds_read_b128 v[186:189], v149 offset:49152
	ds_read_b128 v[190:193], v149 offset:50176
	ds_read_b128 v[194:197], v149 offset:51200
	ds_read_b128 v[198:201], v149 offset:52224
	ds_read_b128 v[202:205], v149 offset:53248
	ds_read_b128 v[206:209], v149 offset:54272
	ds_read_b128 v[210:213], v149 offset:55296
	ds_read_b128 v[214:217], v149 offset:56320
	s_add_u32 s98, s24, 0x80
	s_addc_u32 s99, s25, 0
	global_load_lds_dwordx4 v160, s[98:99]
	s_add_i32 m0, s46, 0x2000
	s_add_u32 s24, s24, 0x40080
	s_addc_u32 s25, s25, 0
	s_add_i32 s46, s47, s73
	global_load_lds_dwordx4 v132, s[98:99]
	s_mov_b32 m0, s46
	s_nop 0
	global_load_lds_dwordx4 v160, s[24:25]
	s_add_i32 m0, s46, 0x2000
	s_nop 0
	global_load_lds_dwordx4 v132, s[24:25]
	s_mov_b32 m0, s90
	s_nop 0
	s_add_u32 s98, s62, 0xfffc0080
	s_addc_u32 s99, s63, -1
	global_load_lds_dwordx4 v128, s[98:99]
	s_mov_b32 m0, s91
	s_nop 0
	global_load_lds_dwordx4 v130, s[98:99]
	s_waitcnt vmcnt(8) lgkmcnt(0)
	s_barrier
	v_mfma_f32_16x16x32_bf16 v[60:63], v[138:141], v[186:189], v[60:63]
	v_mfma_f32_16x16x32_bf16 v[56:59], v[150:153], v[186:189], v[56:59]
	v_mfma_f32_16x16x32_bf16 v[44:47], v[138:141], v[194:197], v[44:47]
	v_mfma_f32_16x16x32_bf16 v[40:43], v[150:153], v[194:197], v[40:43]
	v_mfma_f32_16x16x32_bf16 v[28:31], v[138:141], v[202:205], v[28:31]
	v_mfma_f32_16x16x32_bf16 v[24:27], v[150:153], v[202:205], v[24:27]
	v_mfma_f32_16x16x32_bf16 v[12:15], v[138:141], v[210:213], v[12:15]
	v_mfma_f32_16x16x32_bf16 v[8:11], v[150:153], v[210:213], v[8:11]
	v_mfma_f32_16x16x32_bf16 v[60:63], v[142:145], v[190:193], v[60:63]
	v_mfma_f32_16x16x32_bf16 v[56:59], v[154:157], v[190:193], v[56:59]
	v_mfma_f32_16x16x32_bf16 v[44:47], v[142:145], v[198:201], v[44:47]
	v_mfma_f32_16x16x32_bf16 v[40:43], v[154:157], v[198:201], v[40:43]
	v_mfma_f32_16x16x32_bf16 v[28:31], v[142:145], v[206:209], v[28:31]
	v_mfma_f32_16x16x32_bf16 v[24:27], v[154:157], v[206:209], v[24:27]
	v_mfma_f32_16x16x32_bf16 v[12:15], v[142:145], v[214:217], v[12:15]
	v_mfma_f32_16x16x32_bf16 v[8:11], v[154:157], v[214:217], v[8:11]
	v_mfma_f32_16x16x32_bf16 v[52:55], v[170:173], v[186:189], v[52:55]
	v_mfma_f32_16x16x32_bf16 v[48:51], v[178:181], v[186:189], v[48:51]
	v_mfma_f32_16x16x32_bf16 v[36:39], v[170:173], v[194:197], v[36:39]
	v_mfma_f32_16x16x32_bf16 v[32:35], v[178:181], v[194:197], v[32:35]
	v_mfma_f32_16x16x32_bf16 v[20:23], v[170:173], v[202:205], v[20:23]
	v_mfma_f32_16x16x32_bf16 v[16:19], v[178:181], v[202:205], v[16:19]
	v_mfma_f32_16x16x32_bf16 v[4:7], v[170:173], v[210:213], v[4:7]
	v_mfma_f32_16x16x32_bf16 v[0:3], v[178:181], v[210:213], v[0:3]
	v_mfma_f32_16x16x32_bf16 v[52:55], v[174:177], v[190:193], v[52:55]
	v_mfma_f32_16x16x32_bf16 v[48:51], v[182:185], v[190:193], v[48:51]
	v_mfma_f32_16x16x32_bf16 v[36:39], v[174:177], v[198:201], v[36:39]
	v_mfma_f32_16x16x32_bf16 v[32:35], v[182:185], v[198:201], v[32:35]
	v_mfma_f32_16x16x32_bf16 v[20:23], v[174:177], v[206:209], v[20:23]
	v_mfma_f32_16x16x32_bf16 v[16:19], v[182:185], v[206:209], v[16:19]
	v_mfma_f32_16x16x32_bf16 v[4:7], v[174:177], v[214:217], v[4:7]
	v_mfma_f32_16x16x32_bf16 v[0:3], v[182:185], v[214:217], v[0:3]
	s_barrier
	s_add_i32 s45, s45, 2
	s_add_u32 s60, s60, 0x100
	s_addc_u32 s61, s61, 0
	s_add_u32 s43, s43, 0x100
	s_addc_u32 s44, s44, 0
	s_cmp_gt_u32 s45, 13
	s_cbranch_scc0 .LBB0_211
	s_setprio 0
	s_and_b64 vcc, exec, s[14:15]
	s_cbranch_vccz .LBB0_214
	s_barrier

; #define PG8_STAGE(bufoff, gbase, voff) do { _Pragma("unroll") for (int _i = 0; _i < 2; ++_i) \
;         __builtin_amdgcn_global_load_lds((const unsigned*)((const char*)(gbase) + (voff)[_i]), (LAS unsigned*)(lds + (bufoff) + ldsw + _i * 8192), 16, 0, 0); } while (0)
; #define PG8_LDA(dst, b, h) do { _Pragma("unroll") for (int m = 0; m < 4; ++m) _Pragma("unroll") for (int k = 0; k < 2; ++k) dst[m][k] = *(const LAS bf16x8*)(lds + PG8_SA(b, h) + aoff + m * 2048 + k * 1024); } while (0)
; #define PG8_LDB(dst, b, h) do { _Pragma("unroll") for (int n = 0; n < 2; ++n) _Pragma("unroll") for (int k = 0; k < 2; ++k) dst[n][k] = *(const LAS bf16x8*)(lds + PG8_SB(b, h) + boff + n * 2048 + k * 1024); } while (0)
; #define PG8_WAIT_V(n) asm volatile("s_waitcnt vmcnt(" #n ")" ::: "memory")
; template <class Epi, class Sched, bool ALIGN_EPI = true, bool SP2 = true>
; __device__ __forceinline__ void gemm_phase(LAS unsigned char* lds, const Gemm g, const Sched& S, const Epi& E) {
;     ...
;         for (int t = 0; t < nt; t += 2) {
;             const bool last = (t == nt - 2);
;             const char* a1 = cA + (size_t)(t + 1) * kstep;
;             const char* a2 = last ? nA : cA + (size_t)(t + 2) * kstep; const char* b2 = last ? nB : cB + (size_t)(t + 2) * kstep;
;             const char* a3 = a2 + kstep; const char* b3 = b2 + kstep;
;             if constexpr (SP2) {
;             PG8_LDB(B0, 0, 0); PG8_LDB(B1, 0, 1); PG8_SCHED; PG8_LDA(At, 0, 0); PG8_STAGE(PG8_SA(1, 1), a1 + hstep, voffA);
;             PG8_WAIT_V(8); PG8_WAIT_L(0); PG8_BAR; PG8_MMA(0, 0, At, B0); PG8_MMA(0, 1, At, B1); PG8_BAR; PG8_SCHED;
;             PG8_LDA(At, 0, 1); PG8_STAGE(PG8_SB(0, 0), b2, voffB); PG8_STAGE(PG8_SB(0, 1), b2 + hstep, voffB); PG8_STAGE(PG8_SA(0, 0), a2, voffA);
;             PG8_WAIT_V(8); PG8_WAIT_L(0); PG8_BAR; PG8_MMA(1, 0, At, B0); PG8_MMA(1, 1, At, B1); PG8_BAR; PG8_SCHED;
;             PG8_LDB(B0, 1, 0); PG8_LDB(B1, 1, 1); PG8_SCHED; PG8_LDA(At, 1, 0); PG8_STAGE(PG8_SA(0, 1), a2 + hstep, voffA);
;             PG8_WAIT_V(8); PG8_WAIT_L(0); PG8_BAR; PG8_MMA(0, 0, At, B0); PG8_MMA(0, 1, At, B1); PG8_BAR; PG8_SCHED;
;             PG8_LDA(At, 1, 1); PG8_STAGE(PG8_SB(1, 0), b3, voffB); PG8_STAGE(PG8_SB(1, 1), b3 + hstep, voffB); PG8_STAGE(PG8_SA(1, 0), a3, voffA);
;             PG8_WAIT_V(8); PG8_WAIT_L(0); PG8_BAR; PG8_MMA(1, 0, At, B0); PG8_MMA(1, 1, At, B1); PG8_BAR; PG8_SCHED;
.Lprio_skip_237:
.LBB0_237:
	s_add_u32 s24, s54, 0xfffc0080
	s_addc_u32 s25, s55, -1
	s_add_i32 s46, 0, 0x10000
	s_cmp_eq_u32 s92, 12
	s_cselect_b32 s61, s2, s25
	s_cselect_b32 s60, s3, s24
	v_add_u32_e32 v142, s46, v145
	s_cselect_b32 s25, s17, s91
	s_cselect_b32 s24, s19, s90
	s_add_i32 s47, 0, 0x14000
	ds_read_b128 v[138:141], v142
	ds_read_b128 v[148:151], v142 offset:1024
	ds_read_b128 v[152:155], v142 offset:2048
	ds_read_b128 v[156:159], v142 offset:3072
	v_add_u32_e32 v142, s47, v145
	ds_read_b128 v[170:173], v142
	ds_read_b128 v[174:177], v142 offset:1024
	ds_read_b128 v[178:181], v142 offset:2048
	ds_read_b128 v[182:185], v142 offset:3072
	s_add_i32 m0, s44, 0xc000
	ds_read_b128 v[186:189], v147
	ds_read_b128 v[190:193], v147 offset:1024
	ds_read_b128 v[194:197], v147 offset:2048
	ds_read_b128 v[198:201], v147 offset:3072
	ds_read_b128 v[202:205], v147 offset:4096
	ds_read_b128 v[206:209], v147 offset:5120
	ds_read_b128 v[210:213], v147 offset:6144
	ds_read_b128 v[214:217], v147 offset:7168
	global_load_lds_dwordx4 v134, s[54:55]
	s_add_i32 m0, s44, 0xe000
	s_nop 0
	global_load_lds_dwordx4 v136, s[54:55]
	s_waitcnt vmcnt(8) lgkmcnt(0)
	s_barrier
	v_mfma_f32_16x16x32_bf16 v[124:127], v[138:141], v[186:189], v[124:127]
	v_mfma_f32_16x16x32_bf16 v[120:123], v[152:155], v[186:189], v[120:123]
	v_mfma_f32_16x16x32_bf16 v[108:111], v[138:141], v[194:197], v[108:111]
	v_mfma_f32_16x16x32_bf16 v[104:107], v[152:155], v[194:197], v[104:107]
	v_mfma_f32_16x16x32_bf16 v[92:95], v[138:141], v[202:205], v[92:95]
	v_mfma_f32_16x16x32_bf16 v[88:91], v[152:155], v[202:205], v[88:91]
	v_mfma_f32_16x16x32_bf16 v[76:79], v[138:141], v[210:213], v[76:79]
	v_mfma_f32_16x16x32_bf16 v[72:75], v[152:155], v[210:213], v[72:75]
	v_mfma_f32_16x16x32_bf16 v[124:127], v[148:151], v[190:193], v[124:127]
	v_mfma_f32_16x16x32_bf16 v[120:123], v[156:159], v[190:193], v[120:123]
	v_mfma_f32_16x16x32_bf16 v[108:111], v[148:151], v[198:201], v[108:111]
	v_mfma_f32_16x16x32_bf16 v[104:107], v[156:159], v[198:201], v[104:107]
	v_mfma_f32_16x16x32_bf16 v[92:95], v[148:151], v[206:209], v[92:95]
	v_mfma_f32_16x16x32_bf16 v[88:91], v[156:159], v[206:209], v[88:91]
	v_mfma_f32_16x16x32_bf16 v[76:79], v[148:151], v[214:217], v[76:79]
	v_mfma_f32_16x16x32_bf16 v[72:75], v[156:159], v[214:217], v[72:75]
	v_mfma_f32_16x16x32_bf16 v[116:119], v[170:173], v[186:189], v[116:119]
	v_mfma_f32_16x16x32_bf16 v[112:115], v[178:181], v[186:189], v[112:115]
	v_mfma_f32_16x16x32_bf16 v[100:103], v[170:173], v[194:197], v[100:103]
	v_mfma_f32_16x16x32_bf16 v[96:99], v[178:181], v[194:197], v[96:99]
	v_mfma_f32_16x16x32_bf16 v[84:87], v[170:173], v[202:205], v[84:87]
	v_mfma_f32_16x16x32_bf16 v[80:83], v[178:181], v[202:205], v[80:83]
	v_mfma_f32_16x16x32_bf16 v[68:71], v[170:173], v[210:213], v[68:71]
	v_mfma_f32_16x16x32_bf16 v[64:67], v[178:181], v[210:213], v[64:67]
	v_mfma_f32_16x16x32_bf16 v[116:119], v[174:177], v[190:193], v[116:119]
	v_mfma_f32_16x16x32_bf16 v[112:115], v[182:185], v[190:193], v[112:115]
	v_mfma_f32_16x16x32_bf16 v[100:103], v[174:177], v[198:201], v[100:103]
	v_mfma_f32_16x16x32_bf16 v[96:99], v[182:185], v[198:201], v[96:99]
	v_mfma_f32_16x16x32_bf16 v[84:87], v[174:177], v[206:209], v[84:87]
	v_mfma_f32_16x16x32_bf16 v[80:83], v[182:185], v[206:209], v[80:83]
	v_mfma_f32_16x16x32_bf16 v[68:71], v[174:177], v[214:217], v[68:71]
	v_mfma_f32_16x16x32_bf16 v[64:67], v[182:185], v[214:217], v[64:67]
	s_barrier
	s_add_i32 s46, s46, s43
	s_mov_b32 m0, s46
	ds_read_b128 v[186:189], v147 offset:16384
	ds_read_b128 v[190:193], v147 offset:17408
	ds_read_b128 v[194:197], v147 offset:18432
	ds_read_b128 v[198:201], v147 offset:19456
	ds_read_b128 v[202:205], v147 offset:20480
	ds_read_b128 v[206:209], v147 offset:21504
	ds_read_b128 v[210:213], v147 offset:22528
	ds_read_b128 v[214:217], v147 offset:23552
	global_load_lds_dwordx4 v160, s[24:25]
	s_add_i32 m0, s46, 0x2000
	s_add_u32 s94, s24, 0x40000
	s_addc_u32 s95, s25, 0
	s_add_i32 s46, s47, s43
	global_load_lds_dwordx4 v128, s[24:25]
	s_mov_b32 m0, s46
	s_nop 0
	global_load_lds_dwordx4 v160, s[94:95]
	s_add_i32 m0, s46, 0x2000
	s_nop 0
	global_load_lds_dwordx4 v128, s[94:95]
	s_mov_b32 m0, s44
	s_nop 0
	global_load_lds_dwordx4 v132, s[60:61]
	s_mov_b32 m0, s45
	s_nop 0
	global_load_lds_dwordx4 v130, s[60:61]
	s_waitcnt vmcnt(8) lgkmcnt(0)
	s_barrier
	v_mfma_f32_16x16x32_bf16 v[60:63], v[138:141], v[186:189], v[60:63]
	v_mfma_f32_16x16x32_bf16 v[56:59], v[152:155], v[186:189], v[56:59]
	v_mfma_f32_16x16x32_bf16 v[44:47], v[138:141], v[194:197], v[44:47]
	v_mfma_f32_16x16x32_bf16 v[40:43], v[152:155], v[194:197], v[40:43]
	v_mfma_f32_16x16x32_bf16 v[28:31], v[138:141], v[202:205], v[28:31]
	v_mfma_f32_16x16x32_bf16 v[24:27], v[152:155], v[202:205], v[24:27]
	v_mfma_f32_16x16x32_bf16 v[12:15], v[138:141], v[210:213], v[12:15]
	v_mfma_f32_16x16x32_bf16 v[8:11], v[152:155], v[210:213], v[8:11]
	v_mfma_f32_16x16x32_bf16 v[60:63], v[148:151], v[190:193], v[60:63]
	v_mfma_f32_16x16x32_bf16 v[56:59], v[156:159], v[190:193], v[56:59]
	v_mfma_f32_16x16x32_bf16 v[44:47], v[148:151], v[198:201], v[44:47]
	v_mfma_f32_16x16x32_bf16 v[40:43], v[156:159], v[198:201], v[40:43]
	v_mfma_f32_16x16x32_bf16 v[28:31], v[148:151], v[206:209], v[28:31]
	v_mfma_f32_16x16x32_bf16 v[24:27], v[156:159], v[206:209], v[24:27]
	v_mfma_f32_16x16x32_bf16 v[12:15], v[148:151], v[214:217], v[12:15]
	v_mfma_f32_16x16x32_bf16 v[8:11], v[156:159], v[214:217], v[8:11]
	v_mfma_f32_16x16x32_bf16 v[52:55], v[170:173], v[186:189], v[52:55]
	v_mfma_f32_16x16x32_bf16 v[48:51], v[178:181], v[186:189], v[48:51]
	v_mfma_f32_16x16x32_bf16 v[36:39], v[170:173], v[194:197], v[36:39]
	v_mfma_f32_16x16x32_bf16 v[32:35], v[178:181], v[194:197], v[32:35]
	v_mfma_f32_16x16x32_bf16 v[20:23], v[170:173], v[202:205], v[20:23]
	v_mfma_f32_16x16x32_bf16 v[16:19], v[178:181], v[202:205], v[16:19]
	v_mfma_f32_16x16x32_bf16 v[4:7], v[170:173], v[210:213], v[4:7]
	v_mfma_f32_16x16x32_bf16 v[0:3], v[178:181], v[210:213], v[0:3]
	v_mfma_f32_16x16x32_bf16 v[52:55], v[174:177], v[190:193], v[52:55]
	v_mfma_f32_16x16x32_bf16 v[48:51], v[182:185], v[190:193], v[48:51]
	v_mfma_f32_16x16x32_bf16 v[36:39], v[174:177], v[198:201], v[36:39]
	v_mfma_f32_16x16x32_bf16 v[32:35], v[182:185], v[198:201], v[32:35]
	v_mfma_f32_16x16x32_bf16 v[20:23], v[174:177], v[206:209], v[20:23]
	v_mfma_f32_16x16x32_bf16 v[16:19], v[182:185], v[206:209], v[16:19]
	v_mfma_f32_16x16x32_bf16 v[4:7], v[174:177], v[214:217], v[4:7]
	v_mfma_f32_16x16x32_bf16 v[0:3], v[182:185], v[214:217], v[0:3]
	s_barrier
; #define PG8_STAGE(bufoff, gbase, voff) do { _Pragma("unroll") for (int _i = 0; _i < 2; ++_i) \
;         __builtin_amdgcn_global_load_lds((const unsigned*)((const char*)(gbase) + (voff)[_i]), (LAS unsigned*)(lds + (bufoff) + ldsw + _i * 8192), 16, 0, 0); } while (0)
; #define PG8_LDA(dst, b, h) do { _Pragma("unroll") for (int m = 0; m < 4; ++m) _Pragma("unroll") for (int k = 0; k < 2; ++k) dst[m][k] = *(const LAS bf16x8*)(lds + PG8_SA(b, h) + aoff + m * 2048 + k * 1024); } while (0)
; #define PG8_LDB(dst, b, h) do { _Pragma("unroll") for (int n = 0; n < 2; ++n) _Pragma("unroll") for (int k = 0; k < 2; ++k) dst[n][k] = *(const LAS bf16x8*)(lds + PG8_SB(b, h) + boff + n * 2048 + k * 1024); } while (0)
; #define PG8_WAIT_V(n) asm volatile("s_waitcnt vmcnt(" #n ")" ::: "memory")
; template <class Epi, class Sched, bool ALIGN_EPI = true, bool SP2 = true>
; __device__ __forceinline__ void gemm_phase(LAS unsigned char* lds, const Gemm g, const Sched& S, const Epi& E) {
;     ...
;         for (int t = 0; t < nt; t += 2) {
;             const bool last = (t == nt - 2);
;             const char* a1 = cA + (size_t)(t + 1) * kstep;
;             const char* a2 = last ? nA : cA + (size_t)(t + 2) * kstep; const char* b2 = last ? nB : cB + (size_t)(t + 2) * kstep;
;             const char* a3 = a2 + kstep; const char* b3 = b2 + kstep;
;             if constexpr (SP2) {
;             PG8_LDB(B0, 0, 0); PG8_LDB(B1, 0, 1); PG8_SCHED; PG8_LDA(At, 0, 0); PG8_STAGE(PG8_SA(1, 1), a1 + hstep, voffA);
;             PG8_WAIT_V(8); PG8_WAIT_L(0); PG8_BAR; PG8_MMA(0, 0, At, B0); PG8_MMA(0, 1, At, B1); PG8_BAR; PG8_SCHED;
;             PG8_LDA(At, 0, 1); PG8_STAGE(PG8_SB(0, 0), b2, voffB); PG8_STAGE(PG8_SB(0, 1), b2 + hstep, voffB); PG8_STAGE(PG8_SA(0, 0), a2, voffA);
;             PG8_WAIT_V(8); PG8_WAIT_L(0); PG8_BAR; PG8_MMA(1, 0, At, B0); PG8_MMA(1, 1, At, B1); PG8_BAR; PG8_SCHED;
;             PG8_LDB(B0, 1, 0); PG8_LDB(B1, 1, 1); PG8_SCHED; PG8_LDA(At, 1, 0); PG8_STAGE(PG8_SA(0, 1), a2 + hstep, voffA);
;             PG8_WAIT_V(8); PG8_WAIT_L(0); PG8_BAR; PG8_MMA(0, 0, At, B0); PG8_MMA(0, 1, At, B1); PG8_BAR; PG8_SCHED;
;             PG8_LDA(At, 1, 1); PG8_STAGE(PG8_SB(1, 0), b3, voffB); PG8_STAGE(PG8_SB(1, 1), b3 + hstep, voffB); PG8_STAGE(PG8_SA(1, 0), a3, voffA);
;             PG8_WAIT_V(8); PG8_WAIT_L(0); PG8_BAR; PG8_MMA(1, 0, At, B0); PG8_MMA(1, 1, At, B1); PG8_BAR; PG8_SCHED;
	s_add_i32 s46, 0, 0x18000
	s_add_i32 s47, 0, 0x1c000
	v_add_u32_e32 v156, s46, v145
	v_add_u32_e32 v182, s47, v145
	ds_read_b128 v[138:141], v156
	ds_read_b128 v[148:151], v156 offset:1024
	ds_read_b128 v[152:155], v156 offset:2048
	ds_read_b128 v[156:159], v156 offset:3072
	ds_read_b128 v[170:173], v182
	ds_read_b128 v[174:177], v182 offset:1024
	ds_read_b128 v[178:181], v182 offset:2048
	ds_read_b128 v[182:185], v182 offset:3072
	s_add_u32 s60, s60, 0x40000
	s_addc_u32 s61, s61, 0
	s_mov_b32 m0, s62
	ds_read_b128 v[186:189], v147 offset:32768
	ds_read_b128 v[190:193], v147 offset:33792
	ds_read_b128 v[194:197], v147 offset:34816
	ds_read_b128 v[198:201], v147 offset:35840
	ds_read_b128 v[202:205], v147 offset:36864
	ds_read_b128 v[206:209], v147 offset:37888
	ds_read_b128 v[210:213], v147 offset:38912
	ds_read_b128 v[214:217], v147 offset:39936
	global_load_lds_dwordx4 v132, s[60:61]
	s_mov_b32 m0, s63
	s_nop 0
	global_load_lds_dwordx4 v130, s[60:61]
	s_waitcnt vmcnt(8) lgkmcnt(0)
	s_barrier
	v_mfma_f32_16x16x32_bf16 v[124:127], v[138:141], v[186:189], v[124:127]
	v_mfma_f32_16x16x32_bf16 v[120:123], v[152:155], v[186:189], v[120:123]
	v_mfma_f32_16x16x32_bf16 v[108:111], v[138:141], v[194:197], v[108:111]
	v_mfma_f32_16x16x32_bf16 v[104:107], v[152:155], v[194:197], v[104:107]
	v_mfma_f32_16x16x32_bf16 v[92:95], v[138:141], v[202:205], v[92:95]
	v_mfma_f32_16x16x32_bf16 v[88:91], v[152:155], v[202:205], v[88:91]
	v_mfma_f32_16x16x32_bf16 v[76:79], v[138:141], v[210:213], v[76:79]
	v_mfma_f32_16x16x32_bf16 v[72:75], v[152:155], v[210:213], v[72:75]
	v_mfma_f32_16x16x32_bf16 v[124:127], v[148:151], v[190:193], v[124:127]
	v_mfma_f32_16x16x32_bf16 v[120:123], v[156:159], v[190:193], v[120:123]
	v_mfma_f32_16x16x32_bf16 v[108:111], v[148:151], v[198:201], v[108:111]
	v_mfma_f32_16x16x32_bf16 v[104:107], v[156:159], v[198:201], v[104:107]
	v_mfma_f32_16x16x32_bf16 v[92:95], v[148:151], v[206:209], v[92:95]
	v_mfma_f32_16x16x32_bf16 v[88:91], v[156:159], v[206:209], v[88:91]
	v_mfma_f32_16x16x32_bf16 v[76:79], v[148:151], v[214:217], v[76:79]
	v_mfma_f32_16x16x32_bf16 v[72:75], v[156:159], v[214:217], v[72:75]
	v_mfma_f32_16x16x32_bf16 v[116:119], v[170:173], v[186:189], v[116:119]
	v_mfma_f32_16x16x32_bf16 v[112:115], v[178:181], v[186:189], v[112:115]
	v_mfma_f32_16x16x32_bf16 v[100:103], v[170:173], v[194:197], v[100:103]
	v_mfma_f32_16x16x32_bf16 v[96:99], v[178:181], v[194:197], v[96:99]
	v_mfma_f32_16x16x32_bf16 v[84:87], v[170:173], v[202:205], v[84:87]
	v_mfma_f32_16x16x32_bf16 v[80:83], v[178:181], v[202:205], v[80:83]
	v_mfma_f32_16x16x32_bf16 v[68:71], v[170:173], v[210:213], v[68:71]
	v_mfma_f32_16x16x32_bf16 v[64:67], v[178:181], v[210:213], v[64:67]
	v_mfma_f32_16x16x32_bf16 v[116:119], v[174:177], v[190:193], v[116:119]
	v_mfma_f32_16x16x32_bf16 v[112:115], v[182:185], v[190:193], v[112:115]
	v_mfma_f32_16x16x32_bf16 v[100:103], v[174:177], v[198:201], v[100:103]
	v_mfma_f32_16x16x32_bf16 v[96:99], v[182:185], v[198:201], v[96:99]
	v_mfma_f32_16x16x32_bf16 v[84:87], v[174:177], v[206:209], v[84:87]
	v_mfma_f32_16x16x32_bf16 v[80:83], v[182:185], v[206:209], v[80:83]
	v_mfma_f32_16x16x32_bf16 v[68:71], v[174:177], v[214:217], v[68:71]
	v_mfma_f32_16x16x32_bf16 v[64:67], v[182:185], v[214:217], v[64:67]
	s_barrier
	s_add_i32 s46, s46, s43
	s_mov_b32 m0, s46
	ds_read_b128 v[186:189], v147 offset:49152
	ds_read_b128 v[190:193], v147 offset:50176
	ds_read_b128 v[194:197], v147 offset:51200
	ds_read_b128 v[198:201], v147 offset:52224
	ds_read_b128 v[202:205], v147 offset:53248
	ds_read_b128 v[206:209], v147 offset:54272
	ds_read_b128 v[210:213], v147 offset:55296
	ds_read_b128 v[214:217], v147 offset:56320
	s_add_u32 s98, s24, 0x80
	s_addc_u32 s99, s25, 0
	global_load_lds_dwordx4 v160, s[98:99]
	s_add_i32 m0, s46, 0x2000
	s_add_u32 s24, s24, 0x40080
	s_addc_u32 s25, s25, 0
	s_add_i32 s46, s47, s43
	global_load_lds_dwordx4 v128, s[98:99]
	s_mov_b32 m0, s46
	s_nop 0
	global_load_lds_dwordx4 v160, s[24:25]
	s_add_i32 m0, s46, 0x2000
	s_nop 0
	global_load_lds_dwordx4 v128, s[24:25]
	s_mov_b32 m0, s67
	s_nop 0
	s_add_u32 s98, s60, 0xfffc0080
	s_addc_u32 s99, s61, -1
	global_load_lds_dwordx4 v132, s[98:99]
	s_mov_b32 m0, s72
	s_nop 0
	global_load_lds_dwordx4 v130, s[98:99]
	s_waitcnt vmcnt(8) lgkmcnt(0)
	s_barrier
	v_mfma_f32_16x16x32_bf16 v[60:63], v[138:141], v[186:189], v[60:63]
	v_mfma_f32_16x16x32_bf16 v[56:59], v[152:155], v[186:189], v[56:59]
	v_mfma_f32_16x16x32_bf16 v[44:47], v[138:141], v[194:197], v[44:47]
	v_mfma_f32_16x16x32_bf16 v[40:43], v[152:155], v[194:197], v[40:43]
	v_mfma_f32_16x16x32_bf16 v[28:31], v[138:141], v[202:205], v[28:31]
	v_mfma_f32_16x16x32_bf16 v[24:27], v[152:155], v[202:205], v[24:27]
	v_mfma_f32_16x16x32_bf16 v[12:15], v[138:141], v[210:213], v[12:15]
	v_mfma_f32_16x16x32_bf16 v[8:11], v[152:155], v[210:213], v[8:11]
	v_mfma_f32_16x16x32_bf16 v[60:63], v[148:151], v[190:193], v[60:63]
	v_mfma_f32_16x16x32_bf16 v[56:59], v[156:159], v[190:193], v[56:59]
	v_mfma_f32_16x16x32_bf16 v[44:47], v[148:151], v[198:201], v[44:47]
	v_mfma_f32_16x16x32_bf16 v[40:43], v[156:159], v[198:201], v[40:43]
	v_mfma_f32_16x16x32_bf16 v[28:31], v[148:151], v[206:209], v[28:31]
	v_mfma_f32_16x16x32_bf16 v[24:27], v[156:159], v[206:209], v[24:27]
	v_mfma_f32_16x16x32_bf16 v[12:15], v[148:151], v[214:217], v[12:15]
	v_mfma_f32_16x16x32_bf16 v[8:11], v[156:159], v[214:217], v[8:11]
	v_mfma_f32_16x16x32_bf16 v[52:55], v[170:173], v[186:189], v[52:55]
	v_mfma_f32_16x16x32_bf16 v[48:51], v[178:181], v[186:189], v[48:51]
	v_mfma_f32_16x16x32_bf16 v[36:39], v[170:173], v[194:197], v[36:39]
	v_mfma_f32_16x16x32_bf16 v[32:35], v[178:181], v[194:197], v[32:35]
	v_mfma_f32_16x16x32_bf16 v[20:23], v[170:173], v[202:205], v[20:23]
	v_mfma_f32_16x16x32_bf16 v[16:19], v[178:181], v[202:205], v[16:19]
	v_mfma_f32_16x16x32_bf16 v[4:7], v[170:173], v[210:213], v[4:7]
	v_mfma_f32_16x16x32_bf16 v[0:3], v[178:181], v[210:213], v[0:3]
	v_mfma_f32_16x16x32_bf16 v[52:55], v[174:177], v[190:193], v[52:55]
	v_mfma_f32_16x16x32_bf16 v[48:51], v[182:185], v[190:193], v[48:51]
	v_mfma_f32_16x16x32_bf16 v[36:39], v[174:177], v[198:201], v[36:39]
	v_mfma_f32_16x16x32_bf16 v[32:35], v[182:185], v[198:201], v[32:35]
	v_mfma_f32_16x16x32_bf16 v[20:23], v[174:177], v[206:209], v[20:23]
	v_mfma_f32_16x16x32_bf16 v[16:19], v[182:185], v[206:209], v[16:19]
	v_mfma_f32_16x16x32_bf16 v[4:7], v[174:177], v[214:217], v[4:7]
	v_mfma_f32_16x16x32_bf16 v[0:3], v[182:185], v[214:217], v[0:3]
	s_barrier
	s_add_i32 s92, s92, 2
	s_add_u32 s54, s54, 0x100
	s_addc_u32 s55, s55, 0
	s_add_u32 s90, s90, 0x100
	s_addc_u32 s91, s91, 0
	s_cmp_gt_u32 s92, 13
	s_cbranch_scc0 .LBB0_237
	s_setprio 0
	s_and_b64 vcc, exec, s[14:15]
	s_cbranch_vccz .LBB0_240
	s_barrier

; #define PG8_STAGE(bufoff, gbase, voff) do { _Pragma("unroll") for (int _i = 0; _i < 2; ++_i) \
;         __builtin_amdgcn_global_load_lds((const unsigned*)((const char*)(gbase) + (voff)[_i]), (LAS unsigned*)(lds + (bufoff) + ldsw + _i * 8192), 16, 0, 0); } while (0)
; #define PG8_LDA(dst, b, h) do { _Pragma("unroll") for (int m = 0; m < 4; ++m) _Pragma("unroll") for (int k = 0; k < 2; ++k) dst[m][k] = *(const LAS bf16x8*)(lds + PG8_SA(b, h) + aoff + m * 2048 + k * 1024); } while (0)
; #define PG8_LDB(dst, b, h) do { _Pragma("unroll") for (int n = 0; n < 2; ++n) _Pragma("unroll") for (int k = 0; k < 2; ++k) dst[n][k] = *(const LAS bf16x8*)(lds + PG8_SB(b, h) + boff + n * 2048 + k * 1024); } while (0)
; #define PG8_WAIT_V(n) asm volatile("s_waitcnt vmcnt(" #n ")" ::: "memory")
; template <class Epi, class Sched, bool ALIGN_EPI = true, bool SP2 = true>
; __device__ __forceinline__ void gemm_phase(LAS unsigned char* lds, const Gemm g, const Sched& S, const Epi& E) {
;     ...
;         for (int t = 0; t < nt; t += 2) {
;             const bool last = (t == nt - 2);
;             const char* a1 = cA + (size_t)(t + 1) * kstep;
;             const char* a2 = last ? nA : cA + (size_t)(t + 2) * kstep; const char* b2 = last ? nB : cB + (size_t)(t + 2) * kstep;
;             const char* a3 = a2 + kstep; const char* b3 = b2 + kstep;
;             if constexpr (SP2) {
;             PG8_LDB(B0, 0, 0); PG8_LDB(B1, 0, 1); PG8_SCHED; PG8_LDA(At, 0, 0); PG8_STAGE(PG8_SA(1, 1), a1 + hstep, voffA);
;             PG8_WAIT_V(8); PG8_WAIT_L(0); PG8_BAR; PG8_MMA(0, 0, At, B0); PG8_MMA(0, 1, At, B1); PG8_BAR; PG8_SCHED;
;             PG8_LDA(At, 0, 1); PG8_STAGE(PG8_SB(0, 0), b2, voffB); PG8_STAGE(PG8_SB(0, 1), b2 + hstep, voffB); PG8_STAGE(PG8_SA(0, 0), a2, voffA);
;             PG8_WAIT_V(8); PG8_WAIT_L(0); PG8_BAR; PG8_MMA(1, 0, At, B0); PG8_MMA(1, 1, At, B1); PG8_BAR; PG8_SCHED;
;             PG8_LDB(B0, 1, 0); PG8_LDB(B1, 1, 1); PG8_SCHED; PG8_LDA(At, 1, 0); PG8_STAGE(PG8_SA(0, 1), a2 + hstep, voffA);
;             PG8_WAIT_V(8); PG8_WAIT_L(0); PG8_BAR; PG8_MMA(0, 0, At, B0); PG8_MMA(0, 1, At, B1); PG8_BAR; PG8_SCHED;
;             PG8_LDA(At, 1, 1); PG8_STAGE(PG8_SB(1, 0), b3, voffB); PG8_STAGE(PG8_SB(1, 1), b3 + hstep, voffB); PG8_STAGE(PG8_SA(1, 0), a3, voffA);
;             PG8_WAIT_V(8); PG8_WAIT_L(0); PG8_BAR; PG8_MMA(1, 0, At, B0); PG8_MMA(1, 1, At, B1); PG8_BAR; PG8_SCHED;
.Lprio_skip_354:
.LBB0_354:
	s_add_u32 s24, s62, 0xfff80080
	s_addc_u32 s25, s63, -1
	s_add_i32 s43, 0, 0x10000
	s_cmp_eq_u32 s42, 28
	s_cselect_b32 s83, s2, s25
	s_cselect_b32 s82, s3, s24
	s_cselect_b32 s25, s7, s19
	s_cselect_b32 s24, s9, s18
	s_add_i32 s46, 0, 0x14000
	v_add_u32_e32 v150, s43, v155
	v_add_u32_e32 v158, s46, v155
	ds_read_b128 v[138:141], v150
	ds_read_b128 v[142:145], v150 offset:1024
	ds_read_b128 v[146:149], v150 offset:2048
	ds_read_b128 v[150:153], v150 offset:3072
	ds_read_b128 v[170:173], v158
	ds_read_b128 v[174:177], v158 offset:1024
	ds_read_b128 v[178:181], v158 offset:2048
	ds_read_b128 v[182:185], v158 offset:3072
	s_add_i32 m0, s16, 0xc000
	ds_read_b128 v[186:189], v157
	ds_read_b128 v[190:193], v157 offset:1024
	ds_read_b128 v[194:197], v157 offset:2048
	ds_read_b128 v[198:201], v157 offset:3072
	ds_read_b128 v[202:205], v157 offset:4096
	ds_read_b128 v[206:209], v157 offset:5120
	ds_read_b128 v[210:213], v157 offset:6144
	ds_read_b128 v[214:217], v157 offset:7168
	global_load_lds_dwordx4 v134, s[62:63]
	s_add_i32 m0, s16, 0xe000
	s_nop 0
	global_load_lds_dwordx4 v136, s[62:63]
	s_waitcnt vmcnt(8) lgkmcnt(0)
	s_barrier
	v_mfma_f32_16x16x32_bf16 v[124:127], v[138:141], v[186:189], v[124:127]
	v_mfma_f32_16x16x32_bf16 v[120:123], v[146:149], v[186:189], v[120:123]
	v_mfma_f32_16x16x32_bf16 v[108:111], v[138:141], v[194:197], v[108:111]
	v_mfma_f32_16x16x32_bf16 v[104:107], v[146:149], v[194:197], v[104:107]
	v_mfma_f32_16x16x32_bf16 v[92:95], v[138:141], v[202:205], v[92:95]
	v_mfma_f32_16x16x32_bf16 v[88:91], v[146:149], v[202:205], v[88:91]
	v_mfma_f32_16x16x32_bf16 v[76:79], v[138:141], v[210:213], v[76:79]
	v_mfma_f32_16x16x32_bf16 v[72:75], v[146:149], v[210:213], v[72:75]
	v_mfma_f32_16x16x32_bf16 v[124:127], v[142:145], v[190:193], v[124:127]
	v_mfma_f32_16x16x32_bf16 v[120:123], v[150:153], v[190:193], v[120:123]
	v_mfma_f32_16x16x32_bf16 v[108:111], v[142:145], v[198:201], v[108:111]
	v_mfma_f32_16x16x32_bf16 v[104:107], v[150:153], v[198:201], v[104:107]
	v_mfma_f32_16x16x32_bf16 v[92:95], v[142:145], v[206:209], v[92:95]
	v_mfma_f32_16x16x32_bf16 v[88:91], v[150:153], v[206:209], v[88:91]
	v_mfma_f32_16x16x32_bf16 v[76:79], v[142:145], v[214:217], v[76:79]
	v_mfma_f32_16x16x32_bf16 v[72:75], v[150:153], v[214:217], v[72:75]
	v_mfma_f32_16x16x32_bf16 v[116:119], v[170:173], v[186:189], v[116:119]
	v_mfma_f32_16x16x32_bf16 v[112:115], v[178:181], v[186:189], v[112:115]
	v_mfma_f32_16x16x32_bf16 v[100:103], v[170:173], v[194:197], v[100:103]
	v_mfma_f32_16x16x32_bf16 v[96:99], v[178:181], v[194:197], v[96:99]
	v_mfma_f32_16x16x32_bf16 v[84:87], v[170:173], v[202:205], v[84:87]
	v_mfma_f32_16x16x32_bf16 v[80:83], v[178:181], v[202:205], v[80:83]
	v_mfma_f32_16x16x32_bf16 v[68:71], v[170:173], v[210:213], v[68:71]
	v_mfma_f32_16x16x32_bf16 v[64:67], v[178:181], v[210:213], v[64:67]
	v_mfma_f32_16x16x32_bf16 v[116:119], v[174:177], v[190:193], v[116:119]
	v_mfma_f32_16x16x32_bf16 v[112:115], v[182:185], v[190:193], v[112:115]
	v_mfma_f32_16x16x32_bf16 v[100:103], v[174:177], v[198:201], v[100:103]
	v_mfma_f32_16x16x32_bf16 v[96:99], v[182:185], v[198:201], v[96:99]
	v_mfma_f32_16x16x32_bf16 v[84:87], v[174:177], v[206:209], v[84:87]
	v_mfma_f32_16x16x32_bf16 v[80:83], v[182:185], v[206:209], v[80:83]
	v_mfma_f32_16x16x32_bf16 v[68:71], v[174:177], v[214:217], v[68:71]
	v_mfma_f32_16x16x32_bf16 v[64:67], v[182:185], v[214:217], v[64:67]
	s_barrier
	s_add_i32 s43, s43, s41
	s_mov_b32 m0, s43
	ds_read_b128 v[186:189], v157 offset:16384
	ds_read_b128 v[190:193], v157 offset:17408
	ds_read_b128 v[194:197], v157 offset:18432
	ds_read_b128 v[198:201], v157 offset:19456
	ds_read_b128 v[202:205], v157 offset:20480
	ds_read_b128 v[206:209], v157 offset:21504
	ds_read_b128 v[210:213], v157 offset:22528
	ds_read_b128 v[214:217], v157 offset:23552
	global_load_lds_dwordx4 v160, s[24:25]
	s_add_i32 m0, s43, 0x2000
	s_add_u32 s44, s24, 0x80000
	s_addc_u32 s45, s25, 0
	s_add_i32 s43, s46, s41
	global_load_lds_dwordx4 v132, s[24:25]
	s_mov_b32 m0, s43
	s_nop 0
	global_load_lds_dwordx4 v160, s[44:45]
	s_add_i32 m0, s43, 0x2000
	s_nop 0
	global_load_lds_dwordx4 v132, s[44:45]
	s_mov_b32 m0, s16
	s_nop 0
	global_load_lds_dwordx4 v128, s[82:83]
	s_mov_b32 m0, s17
	s_nop 0
	global_load_lds_dwordx4 v130, s[82:83]
	s_waitcnt vmcnt(8) lgkmcnt(0)
	s_barrier
	v_mfma_f32_16x16x32_bf16 v[60:63], v[138:141], v[186:189], v[60:63]
	v_mfma_f32_16x16x32_bf16 v[56:59], v[146:149], v[186:189], v[56:59]
	v_mfma_f32_16x16x32_bf16 v[44:47], v[138:141], v[194:197], v[44:47]
	v_mfma_f32_16x16x32_bf16 v[40:43], v[146:149], v[194:197], v[40:43]
	v_mfma_f32_16x16x32_bf16 v[28:31], v[138:141], v[202:205], v[28:31]
	v_mfma_f32_16x16x32_bf16 v[24:27], v[146:149], v[202:205], v[24:27]
	v_mfma_f32_16x16x32_bf16 v[12:15], v[138:141], v[210:213], v[12:15]
	v_mfma_f32_16x16x32_bf16 v[8:11], v[146:149], v[210:213], v[8:11]
	v_mfma_f32_16x16x32_bf16 v[60:63], v[142:145], v[190:193], v[60:63]
	v_mfma_f32_16x16x32_bf16 v[56:59], v[150:153], v[190:193], v[56:59]
	v_mfma_f32_16x16x32_bf16 v[44:47], v[142:145], v[198:201], v[44:47]
	v_mfma_f32_16x16x32_bf16 v[40:43], v[150:153], v[198:201], v[40:43]
	v_mfma_f32_16x16x32_bf16 v[28:31], v[142:145], v[206:209], v[28:31]
	v_mfma_f32_16x16x32_bf16 v[24:27], v[150:153], v[206:209], v[24:27]
	v_mfma_f32_16x16x32_bf16 v[12:15], v[142:145], v[214:217], v[12:15]
	v_mfma_f32_16x16x32_bf16 v[8:11], v[150:153], v[214:217], v[8:11]
	v_mfma_f32_16x16x32_bf16 v[52:55], v[170:173], v[186:189], v[52:55]
	v_mfma_f32_16x16x32_bf16 v[48:51], v[178:181], v[186:189], v[48:51]
	v_mfma_f32_16x16x32_bf16 v[36:39], v[170:173], v[194:197], v[36:39]
	v_mfma_f32_16x16x32_bf16 v[32:35], v[178:181], v[194:197], v[32:35]
	v_mfma_f32_16x16x32_bf16 v[20:23], v[170:173], v[202:205], v[20:23]
	v_mfma_f32_16x16x32_bf16 v[16:19], v[178:181], v[202:205], v[16:19]
	v_mfma_f32_16x16x32_bf16 v[4:7], v[170:173], v[210:213], v[4:7]
	v_mfma_f32_16x16x32_bf16 v[0:3], v[178:181], v[210:213], v[0:3]
	v_mfma_f32_16x16x32_bf16 v[52:55], v[174:177], v[190:193], v[52:55]
	v_mfma_f32_16x16x32_bf16 v[48:51], v[182:185], v[190:193], v[48:51]
	v_mfma_f32_16x16x32_bf16 v[36:39], v[174:177], v[198:201], v[36:39]
	v_mfma_f32_16x16x32_bf16 v[32:35], v[182:185], v[198:201], v[32:35]
	v_mfma_f32_16x16x32_bf16 v[20:23], v[174:177], v[206:209], v[20:23]
	v_mfma_f32_16x16x32_bf16 v[16:19], v[182:185], v[206:209], v[16:19]
	v_mfma_f32_16x16x32_bf16 v[4:7], v[174:177], v[214:217], v[4:7]
	v_mfma_f32_16x16x32_bf16 v[0:3], v[182:185], v[214:217], v[0:3]
	s_barrier
; #define PG8_STAGE(bufoff, gbase, voff) do { _Pragma("unroll") for (int _i = 0; _i < 2; ++_i) \
;         __builtin_amdgcn_global_load_lds((const unsigned*)((const char*)(gbase) + (voff)[_i]), (LAS unsigned*)(lds + (bufoff) + ldsw + _i * 8192), 16, 0, 0); } while (0)
; #define PG8_LDA(dst, b, h) do { _Pragma("unroll") for (int m = 0; m < 4; ++m) _Pragma("unroll") for (int k = 0; k < 2; ++k) dst[m][k] = *(const LAS bf16x8*)(lds + PG8_SA(b, h) + aoff + m * 2048 + k * 1024); } while (0)
; #define PG8_LDB(dst, b, h) do { _Pragma("unroll") for (int n = 0; n < 2; ++n) _Pragma("unroll") for (int k = 0; k < 2; ++k) dst[n][k] = *(const LAS bf16x8*)(lds + PG8_SB(b, h) + boff + n * 2048 + k * 1024); } while (0)
; #define PG8_MMA(ai, bj, At, Bt) do { __builtin_amdgcn_s_setprio(1); _Pragma("unroll") for (int m = 0; m < 4; ++m) _Pragma("unroll") for (int n = 0; n < 2; ++n) _Pragma("unroll") for (int k = 0; k < 2; ++k) \
;         acc[ai][bj][m][n] = __builtin_amdgcn_mfma_f32_16x16x32_bf16(Bt[n][k], At[m][k], acc[ai][bj][m][n], 0, 0, 0); __builtin_amdgcn_s_setprio(0); } while (0)
; #define PG8_WAIT_V(n) asm volatile("s_waitcnt vmcnt(" #n ")" ::: "memory")
; #define PG8_WAIT_L(n) asm volatile("s_waitcnt lgkmcnt(" #n ")" ::: "memory")
; #define PG8_BAR __builtin_amdgcn_s_barrier()
; #define PG8_SCHED __builtin_amdgcn_sched_barrier(0)
; template <class Epi, class Sched, bool ALIGN_EPI = true, bool SP2 = true>
; __device__ __forceinline__ void gemm_phase(LAS unsigned char* lds, const Gemm g, const Sched& S, const Epi& E) {
;     ...
;             PG8_LDB(B0, 1, 0); PG8_LDB(B1, 1, 1); PG8_SCHED; PG8_LDA(At, 1, 0); PG8_STAGE(PG8_SA(0, 1), a2 + hstep, voffA);
;             PG8_WAIT_V(8); PG8_WAIT_L(0); PG8_BAR; PG8_MMA(0, 0, At, B0); PG8_MMA(0, 1, At, B1); PG8_BAR; PG8_SCHED;
;             PG8_LDA(At, 1, 1); PG8_STAGE(PG8_SB(1, 0), b3, voffB); PG8_STAGE(PG8_SB(1, 1), b3 + hstep, voffB); PG8_STAGE(PG8_SA(1, 0), a3, voffA);
;             PG8_WAIT_V(8); PG8_WAIT_L(0); PG8_BAR; PG8_MMA(1, 0, At, B0); PG8_MMA(1, 1, At, B1); PG8_BAR; PG8_SCHED;
;     ...
;         if constexpr (ALIGN_EPI) { if (wr == 0) PG8_BAR; }
	s_add_i32 s43, 0, 0x18000
	s_add_i32 s46, 0, 0x1c000
	v_add_u32_e32 v150, s43, v155
	v_add_u32_e32 v166, s46, v155
	ds_read_b128 v[138:141], v150
	ds_read_b128 v[142:145], v150 offset:1024
	ds_read_b128 v[146:149], v150 offset:2048
	ds_read_b128 v[150:153], v150 offset:3072
	ds_read_b128 v[170:173], v166
	ds_read_b128 v[174:177], v166 offset:1024
	ds_read_b128 v[178:181], v166 offset:2048
	ds_read_b128 v[182:185], v166 offset:3072
	s_add_u32 s44, s82, 0x80000
	s_addc_u32 s45, s83, 0
	s_mov_b32 m0, s30
	ds_read_b128 v[186:189], v157 offset:32768
	ds_read_b128 v[190:193], v157 offset:33792
	ds_read_b128 v[194:197], v157 offset:34816
	ds_read_b128 v[198:201], v157 offset:35840
	ds_read_b128 v[202:205], v157 offset:36864
	ds_read_b128 v[206:209], v157 offset:37888
	ds_read_b128 v[210:213], v157 offset:38912
	ds_read_b128 v[214:217], v157 offset:39936
	global_load_lds_dwordx4 v128, s[44:45]
	s_mov_b32 m0, s31
	s_nop 0
	global_load_lds_dwordx4 v130, s[44:45]
	s_waitcnt vmcnt(8) lgkmcnt(0)
	s_barrier
	v_mfma_f32_16x16x32_bf16 v[124:127], v[138:141], v[186:189], v[124:127]
	v_mfma_f32_16x16x32_bf16 v[120:123], v[146:149], v[186:189], v[120:123]
	v_mfma_f32_16x16x32_bf16 v[108:111], v[138:141], v[194:197], v[108:111]
	v_mfma_f32_16x16x32_bf16 v[104:107], v[146:149], v[194:197], v[104:107]
	v_mfma_f32_16x16x32_bf16 v[92:95], v[138:141], v[202:205], v[92:95]
	v_mfma_f32_16x16x32_bf16 v[88:91], v[146:149], v[202:205], v[88:91]
	v_mfma_f32_16x16x32_bf16 v[76:79], v[138:141], v[210:213], v[76:79]
	v_mfma_f32_16x16x32_bf16 v[72:75], v[146:149], v[210:213], v[72:75]
	v_mfma_f32_16x16x32_bf16 v[124:127], v[142:145], v[190:193], v[124:127]
	v_mfma_f32_16x16x32_bf16 v[120:123], v[150:153], v[190:193], v[120:123]
	v_mfma_f32_16x16x32_bf16 v[108:111], v[142:145], v[198:201], v[108:111]
	v_mfma_f32_16x16x32_bf16 v[104:107], v[150:153], v[198:201], v[104:107]
	v_mfma_f32_16x16x32_bf16 v[92:95], v[142:145], v[206:209], v[92:95]
	v_mfma_f32_16x16x32_bf16 v[88:91], v[150:153], v[206:209], v[88:91]
	v_mfma_f32_16x16x32_bf16 v[76:79], v[142:145], v[214:217], v[76:79]
	v_mfma_f32_16x16x32_bf16 v[72:75], v[150:153], v[214:217], v[72:75]
	v_mfma_f32_16x16x32_bf16 v[116:119], v[170:173], v[186:189], v[116:119]
	v_mfma_f32_16x16x32_bf16 v[112:115], v[178:181], v[186:189], v[112:115]
	v_mfma_f32_16x16x32_bf16 v[100:103], v[170:173], v[194:197], v[100:103]
	v_mfma_f32_16x16x32_bf16 v[96:99], v[178:181], v[194:197], v[96:99]
	v_mfma_f32_16x16x32_bf16 v[84:87], v[170:173], v[202:205], v[84:87]
	v_mfma_f32_16x16x32_bf16 v[80:83], v[178:181], v[202:205], v[80:83]
	v_mfma_f32_16x16x32_bf16 v[68:71], v[170:173], v[210:213], v[68:71]
	v_mfma_f32_16x16x32_bf16 v[64:67], v[178:181], v[210:213], v[64:67]
	v_mfma_f32_16x16x32_bf16 v[116:119], v[174:177], v[190:193], v[116:119]
	v_mfma_f32_16x16x32_bf16 v[112:115], v[182:185], v[190:193], v[112:115]
	v_mfma_f32_16x16x32_bf16 v[100:103], v[174:177], v[198:201], v[100:103]
	v_mfma_f32_16x16x32_bf16 v[96:99], v[182:185], v[198:201], v[96:99]
	v_mfma_f32_16x16x32_bf16 v[84:87], v[174:177], v[206:209], v[84:87]
	v_mfma_f32_16x16x32_bf16 v[80:83], v[182:185], v[206:209], v[80:83]
	v_mfma_f32_16x16x32_bf16 v[68:71], v[174:177], v[214:217], v[68:71]
	v_mfma_f32_16x16x32_bf16 v[64:67], v[182:185], v[214:217], v[64:67]
	s_barrier
	s_add_i32 s43, s43, s41
	s_mov_b32 m0, s43
	ds_read_b128 v[186:189], v157 offset:49152
	ds_read_b128 v[190:193], v157 offset:50176
	ds_read_b128 v[194:197], v157 offset:51200
	ds_read_b128 v[198:201], v157 offset:52224
	ds_read_b128 v[202:205], v157 offset:53248
	ds_read_b128 v[206:209], v157 offset:54272
	ds_read_b128 v[210:213], v157 offset:55296
	ds_read_b128 v[214:217], v157 offset:56320
	s_add_u32 s98, s24, 0x80
	s_addc_u32 s99, s25, 0
	global_load_lds_dwordx4 v160, s[98:99]
	s_add_i32 m0, s43, 0x2000
	s_add_u32 s24, s24, 0x80080
	s_addc_u32 s25, s25, 0
	s_add_i32 s43, s46, s41
	global_load_lds_dwordx4 v132, s[98:99]
	s_mov_b32 m0, s43
	s_nop 0
	global_load_lds_dwordx4 v160, s[24:25]
	s_add_i32 m0, s43, 0x2000
	s_nop 0
	global_load_lds_dwordx4 v132, s[24:25]
	s_mov_b32 m0, s60
	s_nop 0
	s_add_u32 s98, s82, 0x80
	s_addc_u32 s99, s83, 0
	global_load_lds_dwordx4 v128, s[98:99]
	s_mov_b32 m0, s61
	s_nop 0
	global_load_lds_dwordx4 v130, s[98:99]
	s_waitcnt vmcnt(8) lgkmcnt(0)
	s_barrier
	v_mfma_f32_16x16x32_bf16 v[60:63], v[138:141], v[186:189], v[60:63]
	v_mfma_f32_16x16x32_bf16 v[56:59], v[146:149], v[186:189], v[56:59]
	v_mfma_f32_16x16x32_bf16 v[44:47], v[138:141], v[194:197], v[44:47]
	v_mfma_f32_16x16x32_bf16 v[40:43], v[146:149], v[194:197], v[40:43]
	v_mfma_f32_16x16x32_bf16 v[28:31], v[138:141], v[202:205], v[28:31]
	v_mfma_f32_16x16x32_bf16 v[24:27], v[146:149], v[202:205], v[24:27]
	v_mfma_f32_16x16x32_bf16 v[12:15], v[138:141], v[210:213], v[12:15]
	v_mfma_f32_16x16x32_bf16 v[8:11], v[146:149], v[210:213], v[8:11]
	v_mfma_f32_16x16x32_bf16 v[60:63], v[142:145], v[190:193], v[60:63]
	v_mfma_f32_16x16x32_bf16 v[56:59], v[150:153], v[190:193], v[56:59]
	v_mfma_f32_16x16x32_bf16 v[44:47], v[142:145], v[198:201], v[44:47]
	v_mfma_f32_16x16x32_bf16 v[40:43], v[150:153], v[198:201], v[40:43]
	v_mfma_f32_16x16x32_bf16 v[28:31], v[142:145], v[206:209], v[28:31]
	v_mfma_f32_16x16x32_bf16 v[24:27], v[150:153], v[206:209], v[24:27]
	v_mfma_f32_16x16x32_bf16 v[12:15], v[142:145], v[214:217], v[12:15]
	v_mfma_f32_16x16x32_bf16 v[8:11], v[150:153], v[214:217], v[8:11]
	v_mfma_f32_16x16x32_bf16 v[52:55], v[170:173], v[186:189], v[52:55]
	v_mfma_f32_16x16x32_bf16 v[48:51], v[178:181], v[186:189], v[48:51]
	v_mfma_f32_16x16x32_bf16 v[36:39], v[170:173], v[194:197], v[36:39]
	v_mfma_f32_16x16x32_bf16 v[32:35], v[178:181], v[194:197], v[32:35]
	v_mfma_f32_16x16x32_bf16 v[20:23], v[170:173], v[202:205], v[20:23]
	v_mfma_f32_16x16x32_bf16 v[16:19], v[178:181], v[202:205], v[16:19]
	v_mfma_f32_16x16x32_bf16 v[4:7], v[170:173], v[210:213], v[4:7]
	v_mfma_f32_16x16x32_bf16 v[0:3], v[178:181], v[210:213], v[0:3]
	v_mfma_f32_16x16x32_bf16 v[52:55], v[174:177], v[190:193], v[52:55]
	v_mfma_f32_16x16x32_bf16 v[48:51], v[182:185], v[190:193], v[48:51]
	v_mfma_f32_16x16x32_bf16 v[36:39], v[174:177], v[198:201], v[36:39]
	v_mfma_f32_16x16x32_bf16 v[32:35], v[182:185], v[198:201], v[32:35]
	v_mfma_f32_16x16x32_bf16 v[20:23], v[174:177], v[206:209], v[20:23]
	v_mfma_f32_16x16x32_bf16 v[16:19], v[182:185], v[206:209], v[16:19]
	v_mfma_f32_16x16x32_bf16 v[4:7], v[174:177], v[214:217], v[4:7]
	v_mfma_f32_16x16x32_bf16 v[0:3], v[182:185], v[214:217], v[0:3]
	s_barrier
	s_add_i32 s42, s42, 2
	s_add_u32 s62, s62, 0x100
	s_addc_u32 s63, s63, 0
	s_add_u32 s18, s18, 0x100
	s_addc_u32 s19, s19, 0
	s_cmp_gt_u32 s42, 29
	s_cbranch_scc0 .LBB0_354
	s_setprio 0
	s_and_b64 vcc, exec, s[14:15]
	s_cbranch_vccz .LBB0_357
	s_barrier

; #define PG8_STAGE(bufoff, gbase, voff) do { _Pragma("unroll") for (int _i = 0; _i < 2; ++_i) \
;         __builtin_amdgcn_global_load_lds((const unsigned*)((const char*)(gbase) + (voff)[_i]), (LAS unsigned*)(lds + (bufoff) + ldsw + _i * 8192), 16, 0, 0); } while (0)
; #define PG8_LDA(dst, b, h) do { _Pragma("unroll") for (int m = 0; m < 4; ++m) _Pragma("unroll") for (int k = 0; k < 2; ++k) dst[m][k] = *(const LAS bf16x8*)(lds + PG8_SA(b, h) + aoff + m * 2048 + k * 1024); } while (0)
; #define PG8_LDB(dst, b, h) do { _Pragma("unroll") for (int n = 0; n < 2; ++n) _Pragma("unroll") for (int k = 0; k < 2; ++k) dst[n][k] = *(const LAS bf16x8*)(lds + PG8_SB(b, h) + boff + n * 2048 + k * 1024); } while (0)
; #define PG8_MMA(ai, bj, At, Bt) do { __builtin_amdgcn_s_setprio(1); _Pragma("unroll") for (int m = 0; m < 4; ++m) _Pragma("unroll") for (int n = 0; n < 2; ++n) _Pragma("unroll") for (int k = 0; k < 2; ++k) \
;         acc[ai][bj][m][n] = __builtin_amdgcn_mfma_f32_16x16x32_bf16(Bt[n][k], At[m][k], acc[ai][bj][m][n], 0, 0, 0); __builtin_amdgcn_s_setprio(0); } while (0)
; #define PG8_BAR __builtin_amdgcn_s_barrier()
; template <class Epi, class Sched, bool ALIGN_EPI = true, bool SP2 = true>
; __device__ __forceinline__ void gemm_phase(LAS unsigned char* lds, const Gemm g, const Sched& S, const Epi& E) {
;     ...
;         const char* nA = has_next ? (const char*)g.A + (size_t)nxt.pm * tstep : cA; const char* nB = has_next ? (const char*)g.Bt + (size_t)nxt.pn * tstep : cB;
;         for (int t = 0; t < nt; t += 2) {
;             const bool last = (t == nt - 2);
;             const char* a1 = cA + (size_t)(t + 1) * kstep;
;             const char* a2 = last ? nA : cA + (size_t)(t + 2) * kstep; const char* b2 = last ? nB : cB + (size_t)(t + 2) * kstep;
;             const char* a3 = a2 + kstep; const char* b3 = b2 + kstep;
;             if constexpr (SP2) {
;             PG8_LDB(B0, 0, 0); PG8_LDB(B1, 0, 1); PG8_SCHED; PG8_LDA(At, 0, 0); PG8_STAGE(PG8_SA(1, 1), a1 + hstep, voffA);
;             PG8_WAIT_V(8); PG8_WAIT_L(0); PG8_BAR; PG8_MMA(0, 0, At, B0); PG8_MMA(0, 1, At, B1); PG8_BAR; PG8_SCHED;
;             PG8_LDA(At, 0, 1); PG8_STAGE(PG8_SB(0, 0), b2, voffB); PG8_STAGE(PG8_SB(0, 1), b2 + hstep, voffB); PG8_STAGE(PG8_SA(0, 0), a2, voffA);
;             PG8_WAIT_V(8); PG8_WAIT_L(0); PG8_BAR; PG8_MMA(1, 0, At, B0); PG8_MMA(1, 1, At, B1); PG8_BAR; PG8_SCHED;
.Lprio_skip_566:
.LBB0_566:
	s_add_u32 s54, s52, 0x100
	s_addc_u32 s55, s53, 0
	s_add_i32 s46, 0, 0x10000
	s_cmpk_eq_i32 s89, 0x54
	s_cselect_b32 s61, s9, s55
	s_cselect_b32 s60, s8, s54
	v_add_u32_e32 v142, s46, v145
	s_cselect_b32 s25, s31, s3
	s_cselect_b32 s24, s30, s2
	s_add_i32 s47, 0, 0x14000
	ds_read_b128 v[138:141], v142
	ds_read_b128 v[148:151], v142 offset:1024
	ds_read_b128 v[152:155], v142 offset:2048
	ds_read_b128 v[156:159], v142 offset:3072
	v_add_u32_e32 v142, s47, v145
	ds_read_b128 v[170:173], v142
	ds_read_b128 v[174:177], v142 offset:1024
	ds_read_b128 v[178:181], v142 offset:2048
	ds_read_b128 v[182:185], v142 offset:3072
	s_add_i32 m0, s63, 0xc000
	ds_read_b128 v[186:189], v147
	ds_read_b128 v[190:193], v147 offset:1024
	ds_read_b128 v[194:197], v147 offset:2048
	ds_read_b128 v[198:201], v147 offset:3072
	ds_read_b128 v[202:205], v147 offset:4096
	ds_read_b128 v[206:209], v147 offset:5120
	ds_read_b128 v[210:213], v147 offset:6144
	ds_read_b128 v[214:217], v147 offset:7168
	global_load_lds_dwordx4 v134, s[52:53]
	s_add_i32 m0, s63, 0xe000
	s_nop 0
	global_load_lds_dwordx4 v136, s[52:53]
	s_waitcnt vmcnt(8) lgkmcnt(0)
	s_barrier
	v_mfma_f32_16x16x32_bf16 v[124:127], v[138:141], v[186:189], v[124:127]
	v_mfma_f32_16x16x32_bf16 v[120:123], v[152:155], v[186:189], v[120:123]
	v_mfma_f32_16x16x32_bf16 v[108:111], v[138:141], v[194:197], v[108:111]
	v_mfma_f32_16x16x32_bf16 v[104:107], v[152:155], v[194:197], v[104:107]
	v_mfma_f32_16x16x32_bf16 v[92:95], v[138:141], v[202:205], v[92:95]
	v_mfma_f32_16x16x32_bf16 v[88:91], v[152:155], v[202:205], v[88:91]
	v_mfma_f32_16x16x32_bf16 v[76:79], v[138:141], v[210:213], v[76:79]
	v_mfma_f32_16x16x32_bf16 v[72:75], v[152:155], v[210:213], v[72:75]
	v_mfma_f32_16x16x32_bf16 v[124:127], v[148:151], v[190:193], v[124:127]
	v_mfma_f32_16x16x32_bf16 v[120:123], v[156:159], v[190:193], v[120:123]
	v_mfma_f32_16x16x32_bf16 v[108:111], v[148:151], v[198:201], v[108:111]
	v_mfma_f32_16x16x32_bf16 v[104:107], v[156:159], v[198:201], v[104:107]
	v_mfma_f32_16x16x32_bf16 v[92:95], v[148:151], v[206:209], v[92:95]
	v_mfma_f32_16x16x32_bf16 v[88:91], v[156:159], v[206:209], v[88:91]
	v_mfma_f32_16x16x32_bf16 v[76:79], v[148:151], v[214:217], v[76:79]
	v_mfma_f32_16x16x32_bf16 v[72:75], v[156:159], v[214:217], v[72:75]
	v_mfma_f32_16x16x32_bf16 v[116:119], v[170:173], v[186:189], v[116:119]
	v_mfma_f32_16x16x32_bf16 v[112:115], v[178:181], v[186:189], v[112:115]
	v_mfma_f32_16x16x32_bf16 v[100:103], v[170:173], v[194:197], v[100:103]
	v_mfma_f32_16x16x32_bf16 v[96:99], v[178:181], v[194:197], v[96:99]
	v_mfma_f32_16x16x32_bf16 v[84:87], v[170:173], v[202:205], v[84:87]
	v_mfma_f32_16x16x32_bf16 v[80:83], v[178:181], v[202:205], v[80:83]
	v_mfma_f32_16x16x32_bf16 v[68:71], v[170:173], v[210:213], v[68:71]
	v_mfma_f32_16x16x32_bf16 v[64:67], v[178:181], v[210:213], v[64:67]
	v_mfma_f32_16x16x32_bf16 v[116:119], v[174:177], v[190:193], v[116:119]
	v_mfma_f32_16x16x32_bf16 v[112:115], v[182:185], v[190:193], v[112:115]
	v_mfma_f32_16x16x32_bf16 v[100:103], v[174:177], v[198:201], v[100:103]
	v_mfma_f32_16x16x32_bf16 v[96:99], v[182:185], v[198:201], v[96:99]
	v_mfma_f32_16x16x32_bf16 v[84:87], v[174:177], v[206:209], v[84:87]
	v_mfma_f32_16x16x32_bf16 v[80:83], v[182:185], v[206:209], v[80:83]
	v_mfma_f32_16x16x32_bf16 v[68:71], v[174:177], v[214:217], v[68:71]
	v_mfma_f32_16x16x32_bf16 v[64:67], v[182:185], v[214:217], v[64:67]
	s_barrier
	s_add_i32 s46, s46, s62
	s_mov_b32 m0, s46
	ds_read_b128 v[186:189], v147 offset:16384
	ds_read_b128 v[190:193], v147 offset:17408
	ds_read_b128 v[194:197], v147 offset:18432
	ds_read_b128 v[198:201], v147 offset:19456
	ds_read_b128 v[202:205], v147 offset:20480
	ds_read_b128 v[206:209], v147 offset:21504
	ds_read_b128 v[210:213], v147 offset:22528
	ds_read_b128 v[214:217], v147 offset:23552
	global_load_lds_dwordx4 v160, s[24:25]
	s_add_i32 m0, s46, 0x2000
	s_add_u32 s52, s24, 0x160000
	s_addc_u32 s53, s25, 0
	s_add_i32 s46, s47, s62
	global_load_lds_dwordx4 v132, s[24:25]
	s_mov_b32 m0, s46
	s_nop 0
	global_load_lds_dwordx4 v160, s[52:53]
	s_add_i32 m0, s46, 0x2000
	s_nop 0
	global_load_lds_dwordx4 v132, s[52:53]
	s_mov_b32 m0, s63
	s_nop 0
	global_load_lds_dwordx4 v128, s[60:61]
	s_mov_b32 m0, s66
	s_nop 0
	global_load_lds_dwordx4 v130, s[60:61]
	s_waitcnt vmcnt(8) lgkmcnt(0)
	s_barrier
	v_mfma_f32_16x16x32_bf16 v[60:63], v[138:141], v[186:189], v[60:63]
	v_mfma_f32_16x16x32_bf16 v[56:59], v[152:155], v[186:189], v[56:59]
	v_mfma_f32_16x16x32_bf16 v[44:47], v[138:141], v[194:197], v[44:47]
	v_mfma_f32_16x16x32_bf16 v[40:43], v[152:155], v[194:197], v[40:43]
	v_mfma_f32_16x16x32_bf16 v[28:31], v[138:141], v[202:205], v[28:31]
	v_mfma_f32_16x16x32_bf16 v[24:27], v[152:155], v[202:205], v[24:27]
	v_mfma_f32_16x16x32_bf16 v[12:15], v[138:141], v[210:213], v[12:15]
	v_mfma_f32_16x16x32_bf16 v[8:11], v[152:155], v[210:213], v[8:11]
	v_mfma_f32_16x16x32_bf16 v[60:63], v[148:151], v[190:193], v[60:63]
	v_mfma_f32_16x16x32_bf16 v[56:59], v[156:159], v[190:193], v[56:59]
	v_mfma_f32_16x16x32_bf16 v[44:47], v[148:151], v[198:201], v[44:47]
	v_mfma_f32_16x16x32_bf16 v[40:43], v[156:159], v[198:201], v[40:43]
	v_mfma_f32_16x16x32_bf16 v[28:31], v[148:151], v[206:209], v[28:31]
	v_mfma_f32_16x16x32_bf16 v[24:27], v[156:159], v[206:209], v[24:27]
	v_mfma_f32_16x16x32_bf16 v[12:15], v[148:151], v[214:217], v[12:15]
	v_mfma_f32_16x16x32_bf16 v[8:11], v[156:159], v[214:217], v[8:11]
	v_mfma_f32_16x16x32_bf16 v[52:55], v[170:173], v[186:189], v[52:55]
	v_mfma_f32_16x16x32_bf16 v[48:51], v[178:181], v[186:189], v[48:51]
	v_mfma_f32_16x16x32_bf16 v[36:39], v[170:173], v[194:197], v[36:39]
	v_mfma_f32_16x16x32_bf16 v[32:35], v[178:181], v[194:197], v[32:35]
	v_mfma_f32_16x16x32_bf16 v[20:23], v[170:173], v[202:205], v[20:23]
	v_mfma_f32_16x16x32_bf16 v[16:19], v[178:181], v[202:205], v[16:19]
	v_mfma_f32_16x16x32_bf16 v[4:7], v[170:173], v[210:213], v[4:7]
	v_mfma_f32_16x16x32_bf16 v[0:3], v[178:181], v[210:213], v[0:3]
	v_mfma_f32_16x16x32_bf16 v[52:55], v[174:177], v[190:193], v[52:55]
	v_mfma_f32_16x16x32_bf16 v[48:51], v[182:185], v[190:193], v[48:51]
	v_mfma_f32_16x16x32_bf16 v[36:39], v[174:177], v[198:201], v[36:39]
	v_mfma_f32_16x16x32_bf16 v[32:35], v[182:185], v[198:201], v[32:35]
	v_mfma_f32_16x16x32_bf16 v[20:23], v[174:177], v[206:209], v[20:23]
	v_mfma_f32_16x16x32_bf16 v[16:19], v[182:185], v[206:209], v[16:19]
	v_mfma_f32_16x16x32_bf16 v[4:7], v[174:177], v[214:217], v[4:7]
	v_mfma_f32_16x16x32_bf16 v[0:3], v[182:185], v[214:217], v[0:3]
	s_barrier
; #define PG8_STAGE(bufoff, gbase, voff) do { _Pragma("unroll") for (int _i = 0; _i < 2; ++_i) \
;         __builtin_amdgcn_global_load_lds((const unsigned*)((const char*)(gbase) + (voff)[_i]), (LAS unsigned*)(lds + (bufoff) + ldsw + _i * 8192), 16, 0, 0); } while (0)
; #define PG8_LDA(dst, b, h) do { _Pragma("unroll") for (int m = 0; m < 4; ++m) _Pragma("unroll") for (int k = 0; k < 2; ++k) dst[m][k] = *(const LAS bf16x8*)(lds + PG8_SA(b, h) + aoff + m * 2048 + k * 1024); } while (0)
; #define PG8_LDB(dst, b, h) do { _Pragma("unroll") for (int n = 0; n < 2; ++n) _Pragma("unroll") for (int k = 0; k < 2; ++k) dst[n][k] = *(const LAS bf16x8*)(lds + PG8_SB(b, h) + boff + n * 2048 + k * 1024); } while (0)
; #define PG8_MMA(ai, bj, At, Bt) do { __builtin_amdgcn_s_setprio(1); _Pragma("unroll") for (int m = 0; m < 4; ++m) _Pragma("unroll") for (int n = 0; n < 2; ++n) _Pragma("unroll") for (int k = 0; k < 2; ++k) \
;         acc[ai][bj][m][n] = __builtin_amdgcn_mfma_f32_16x16x32_bf16(Bt[n][k], At[m][k], acc[ai][bj][m][n], 0, 0, 0); __builtin_amdgcn_s_setprio(0); } while (0)
; #define PG8_WAIT_V(n) asm volatile("s_waitcnt vmcnt(" #n ")" ::: "memory")
; #define PG8_WAIT_L(n) asm volatile("s_waitcnt lgkmcnt(" #n ")" ::: "memory")
; #define PG8_BAR __builtin_amdgcn_s_barrier()
; #define PG8_SCHED __builtin_amdgcn_sched_barrier(0)
; template <class Epi, class Sched, bool ALIGN_EPI = true, bool SP2 = true>
; __device__ __forceinline__ void gemm_phase(LAS unsigned char* lds, const Gemm g, const Sched& S, const Epi& E) {
;     ...
;             PG8_LDB(B0, 1, 0); PG8_LDB(B1, 1, 1); PG8_SCHED; PG8_LDA(At, 1, 0); PG8_STAGE(PG8_SA(0, 1), a2 + hstep, voffA);
;             PG8_WAIT_V(8); PG8_WAIT_L(0); PG8_BAR; PG8_MMA(0, 0, At, B0); PG8_MMA(0, 1, At, B1); PG8_BAR; PG8_SCHED;
;             PG8_LDA(At, 1, 1); PG8_STAGE(PG8_SB(1, 0), b3, voffB); PG8_STAGE(PG8_SB(1, 1), b3 + hstep, voffB); PG8_STAGE(PG8_SA(1, 0), a3, voffA);
;             PG8_WAIT_V(8); PG8_WAIT_L(0); PG8_BAR; PG8_MMA(1, 0, At, B0); PG8_MMA(1, 1, At, B1); PG8_BAR; PG8_SCHED;
;     ...
;         if constexpr (ALIGN_EPI) { if (wr == 0) PG8_BAR; }
	s_add_i32 s46, 0, 0x18000
	s_add_i32 s47, 0, 0x1c000
	v_add_u32_e32 v156, s46, v145
	v_add_u32_e32 v166, s47, v145
	ds_read_b128 v[138:141], v156
	ds_read_b128 v[148:151], v156 offset:1024
	ds_read_b128 v[152:155], v156 offset:2048
	ds_read_b128 v[156:159], v156 offset:3072
	ds_read_b128 v[170:173], v166
	ds_read_b128 v[174:177], v166 offset:1024
	ds_read_b128 v[178:181], v166 offset:2048
	ds_read_b128 v[182:185], v166 offset:3072
	s_add_u32 s52, s60, 0x160000
	s_addc_u32 s53, s61, 0
	s_mov_b32 m0, s67
	ds_read_b128 v[186:189], v147 offset:32768
	ds_read_b128 v[190:193], v147 offset:33792
	ds_read_b128 v[194:197], v147 offset:34816
	ds_read_b128 v[198:201], v147 offset:35840
	ds_read_b128 v[202:205], v147 offset:36864
	ds_read_b128 v[206:209], v147 offset:37888
	ds_read_b128 v[210:213], v147 offset:38912
	ds_read_b128 v[214:217], v147 offset:39936
	global_load_lds_dwordx4 v128, s[52:53]
	s_mov_b32 m0, s72
	s_nop 0
	global_load_lds_dwordx4 v130, s[52:53]
	s_waitcnt vmcnt(8) lgkmcnt(0)
	s_barrier
	v_mfma_f32_16x16x32_bf16 v[124:127], v[138:141], v[186:189], v[124:127]
	v_mfma_f32_16x16x32_bf16 v[120:123], v[152:155], v[186:189], v[120:123]
	v_mfma_f32_16x16x32_bf16 v[108:111], v[138:141], v[194:197], v[108:111]
	v_mfma_f32_16x16x32_bf16 v[104:107], v[152:155], v[194:197], v[104:107]
	v_mfma_f32_16x16x32_bf16 v[92:95], v[138:141], v[202:205], v[92:95]
	v_mfma_f32_16x16x32_bf16 v[88:91], v[152:155], v[202:205], v[88:91]
	v_mfma_f32_16x16x32_bf16 v[76:79], v[138:141], v[210:213], v[76:79]
	v_mfma_f32_16x16x32_bf16 v[72:75], v[152:155], v[210:213], v[72:75]
	v_mfma_f32_16x16x32_bf16 v[124:127], v[148:151], v[190:193], v[124:127]
	v_mfma_f32_16x16x32_bf16 v[120:123], v[156:159], v[190:193], v[120:123]
	v_mfma_f32_16x16x32_bf16 v[108:111], v[148:151], v[198:201], v[108:111]
	v_mfma_f32_16x16x32_bf16 v[104:107], v[156:159], v[198:201], v[104:107]
	v_mfma_f32_16x16x32_bf16 v[92:95], v[148:151], v[206:209], v[92:95]
	v_mfma_f32_16x16x32_bf16 v[88:91], v[156:159], v[206:209], v[88:91]
	v_mfma_f32_16x16x32_bf16 v[76:79], v[148:151], v[214:217], v[76:79]
	v_mfma_f32_16x16x32_bf16 v[72:75], v[156:159], v[214:217], v[72:75]
	v_mfma_f32_16x16x32_bf16 v[116:119], v[170:173], v[186:189], v[116:119]
	v_mfma_f32_16x16x32_bf16 v[112:115], v[178:181], v[186:189], v[112:115]
	v_mfma_f32_16x16x32_bf16 v[100:103], v[170:173], v[194:197], v[100:103]
	v_mfma_f32_16x16x32_bf16 v[96:99], v[178:181], v[194:197], v[96:99]
	v_mfma_f32_16x16x32_bf16 v[84:87], v[170:173], v[202:205], v[84:87]
	v_mfma_f32_16x16x32_bf16 v[80:83], v[178:181], v[202:205], v[80:83]
	v_mfma_f32_16x16x32_bf16 v[68:71], v[170:173], v[210:213], v[68:71]
	v_mfma_f32_16x16x32_bf16 v[64:67], v[178:181], v[210:213], v[64:67]
	v_mfma_f32_16x16x32_bf16 v[116:119], v[174:177], v[190:193], v[116:119]
	v_mfma_f32_16x16x32_bf16 v[112:115], v[182:185], v[190:193], v[112:115]
	v_mfma_f32_16x16x32_bf16 v[100:103], v[174:177], v[198:201], v[100:103]
	v_mfma_f32_16x16x32_bf16 v[96:99], v[182:185], v[198:201], v[96:99]
	v_mfma_f32_16x16x32_bf16 v[84:87], v[174:177], v[206:209], v[84:87]
	v_mfma_f32_16x16x32_bf16 v[80:83], v[182:185], v[206:209], v[80:83]
	v_mfma_f32_16x16x32_bf16 v[68:71], v[174:177], v[214:217], v[68:71]
	v_mfma_f32_16x16x32_bf16 v[64:67], v[182:185], v[214:217], v[64:67]
	s_barrier
	s_add_i32 s46, s46, s62
	s_mov_b32 m0, s46
	ds_read_b128 v[186:189], v147 offset:49152
	ds_read_b128 v[190:193], v147 offset:50176
	ds_read_b128 v[194:197], v147 offset:51200
	ds_read_b128 v[198:201], v147 offset:52224
	ds_read_b128 v[202:205], v147 offset:53248
	ds_read_b128 v[206:209], v147 offset:54272
	ds_read_b128 v[210:213], v147 offset:55296
	ds_read_b128 v[214:217], v147 offset:56320
	s_add_u32 s98, s24, 0x80
	s_addc_u32 s99, s25, 0
	global_load_lds_dwordx4 v160, s[98:99]
	s_add_i32 m0, s46, 0x2000
	s_add_u32 s24, s24, 0x160080
	s_addc_u32 s25, s25, 0
	s_add_i32 s46, s47, s62
	global_load_lds_dwordx4 v132, s[98:99]
	s_mov_b32 m0, s46
	s_nop 0
	global_load_lds_dwordx4 v160, s[24:25]
	s_add_i32 m0, s46, 0x2000
	s_nop 0
	global_load_lds_dwordx4 v132, s[24:25]
	s_mov_b32 m0, s73
	s_nop 0
	s_add_u32 s98, s52, 0xffea0080
	s_addc_u32 s99, s53, -1
	global_load_lds_dwordx4 v128, s[98:99]
	s_mov_b32 m0, s79
	s_nop 0
	global_load_lds_dwordx4 v130, s[98:99]
	s_waitcnt vmcnt(8) lgkmcnt(0)
	s_barrier
	v_mfma_f32_16x16x32_bf16 v[60:63], v[138:141], v[186:189], v[60:63]
	v_mfma_f32_16x16x32_bf16 v[56:59], v[152:155], v[186:189], v[56:59]
	v_mfma_f32_16x16x32_bf16 v[44:47], v[138:141], v[194:197], v[44:47]
	v_mfma_f32_16x16x32_bf16 v[40:43], v[152:155], v[194:197], v[40:43]
	v_mfma_f32_16x16x32_bf16 v[28:31], v[138:141], v[202:205], v[28:31]
	v_mfma_f32_16x16x32_bf16 v[24:27], v[152:155], v[202:205], v[24:27]
	v_mfma_f32_16x16x32_bf16 v[12:15], v[138:141], v[210:213], v[12:15]
	v_mfma_f32_16x16x32_bf16 v[8:11], v[152:155], v[210:213], v[8:11]
	v_mfma_f32_16x16x32_bf16 v[60:63], v[148:151], v[190:193], v[60:63]
	v_mfma_f32_16x16x32_bf16 v[56:59], v[156:159], v[190:193], v[56:59]
	v_mfma_f32_16x16x32_bf16 v[44:47], v[148:151], v[198:201], v[44:47]
	v_mfma_f32_16x16x32_bf16 v[40:43], v[156:159], v[198:201], v[40:43]
	v_mfma_f32_16x16x32_bf16 v[28:31], v[148:151], v[206:209], v[28:31]
	v_mfma_f32_16x16x32_bf16 v[24:27], v[156:159], v[206:209], v[24:27]
	v_mfma_f32_16x16x32_bf16 v[12:15], v[148:151], v[214:217], v[12:15]
	v_mfma_f32_16x16x32_bf16 v[8:11], v[156:159], v[214:217], v[8:11]
	v_mfma_f32_16x16x32_bf16 v[52:55], v[170:173], v[186:189], v[52:55]
	v_mfma_f32_16x16x32_bf16 v[48:51], v[178:181], v[186:189], v[48:51]
	v_mfma_f32_16x16x32_bf16 v[36:39], v[170:173], v[194:197], v[36:39]
	v_mfma_f32_16x16x32_bf16 v[32:35], v[178:181], v[194:197], v[32:35]
	v_mfma_f32_16x16x32_bf16 v[20:23], v[170:173], v[202:205], v[20:23]
	v_mfma_f32_16x16x32_bf16 v[16:19], v[178:181], v[202:205], v[16:19]
	v_mfma_f32_16x16x32_bf16 v[4:7], v[170:173], v[210:213], v[4:7]
	v_mfma_f32_16x16x32_bf16 v[0:3], v[178:181], v[210:213], v[0:3]
	v_mfma_f32_16x16x32_bf16 v[52:55], v[174:177], v[190:193], v[52:55]
	v_mfma_f32_16x16x32_bf16 v[48:51], v[182:185], v[190:193], v[48:51]
	v_mfma_f32_16x16x32_bf16 v[36:39], v[174:177], v[198:201], v[36:39]
	v_mfma_f32_16x16x32_bf16 v[32:35], v[182:185], v[198:201], v[32:35]
	v_mfma_f32_16x16x32_bf16 v[20:23], v[174:177], v[206:209], v[20:23]
	v_mfma_f32_16x16x32_bf16 v[16:19], v[182:185], v[206:209], v[16:19]
	v_mfma_f32_16x16x32_bf16 v[4:7], v[174:177], v[214:217], v[4:7]
	v_mfma_f32_16x16x32_bf16 v[0:3], v[182:185], v[214:217], v[0:3]
	s_barrier
	s_add_i32 s89, s89, 2
	s_add_u32 s2, s2, 0x100
	s_addc_u32 s3, s3, 0
	s_cmpk_gt_u32 s89, 0x55
	s_mov_b64 s[52:53], s[54:55]
	s_cbranch_scc0 .LBB0_566
	s_setprio 0
	s_and_b64 vcc, exec, s[18:19]
	s_cbranch_vccz .LBB0_569
	s_barrier

; #define PG8_STAGE(bufoff, gbase, voff) do { _Pragma("unroll") for (int _i = 0; _i < 2; ++_i) \
;         __builtin_amdgcn_global_load_lds((const unsigned*)((const char*)(gbase) + (voff)[_i]), (LAS unsigned*)(lds + (bufoff) + ldsw + _i * 8192), 16, 0, 0); } while (0)
; #define PG8_LDA(dst, b, h) do { _Pragma("unroll") for (int m = 0; m < 4; ++m) _Pragma("unroll") for (int k = 0; k < 2; ++k) dst[m][k] = *(const LAS bf16x8*)(lds + PG8_SA(b, h) + aoff + m * 2048 + k * 1024); } while (0)
; #define PG8_LDB(dst, b, h) do { _Pragma("unroll") for (int n = 0; n < 2; ++n) _Pragma("unroll") for (int k = 0; k < 2; ++k) dst[n][k] = *(const LAS bf16x8*)(lds + PG8_SB(b, h) + boff + n * 2048 + k * 1024); } while (0)
; #define PG8_MMA(ai, bj, At, Bt) do { __builtin_amdgcn_s_setprio(1); _Pragma("unroll") for (int m = 0; m < 4; ++m) _Pragma("unroll") for (int n = 0; n < 2; ++n) _Pragma("unroll") for (int k = 0; k < 2; ++k) \
;         acc[ai][bj][m][n] = __builtin_amdgcn_mfma_f32_16x16x32_bf16(Bt[n][k], At[m][k], acc[ai][bj][m][n], 0, 0, 0); __builtin_amdgcn_s_setprio(0); } while (0)
; #define PG8_BAR __builtin_amdgcn_s_barrier()
; template <class Epi, class Sched, bool ALIGN_EPI = true, bool SP2 = true>
; __device__ __forceinline__ void gemm_phase(LAS unsigned char* lds, const Gemm g, const Sched& S, const Epi& E) {
;     ...
;         const char* nA = has_next ? (const char*)g.A + (size_t)nxt.pm * tstep : cA; const char* nB = has_next ? (const char*)g.Bt + (size_t)nxt.pn * tstep : cB;
;         for (int t = 0; t < nt; t += 2) {
;             const bool last = (t == nt - 2);
;             const char* a1 = cA + (size_t)(t + 1) * kstep;
;             const char* a2 = last ? nA : cA + (size_t)(t + 2) * kstep; const char* b2 = last ? nB : cB + (size_t)(t + 2) * kstep;
;             const char* a3 = a2 + kstep; const char* b3 = b2 + kstep;
;             if constexpr (SP2) {
;             PG8_LDB(B0, 0, 0); PG8_LDB(B1, 0, 1); PG8_SCHED; PG8_LDA(At, 0, 0); PG8_STAGE(PG8_SA(1, 1), a1 + hstep, voffA);
;             PG8_WAIT_V(8); PG8_WAIT_L(0); PG8_BAR; PG8_MMA(0, 0, At, B0); PG8_MMA(0, 1, At, B1); PG8_BAR; PG8_SCHED;
;             PG8_LDA(At, 0, 1); PG8_STAGE(PG8_SB(0, 0), b2, voffB); PG8_STAGE(PG8_SB(0, 1), b2 + hstep, voffB); PG8_STAGE(PG8_SA(0, 0), a2, voffA);
;             PG8_WAIT_V(8); PG8_WAIT_L(0); PG8_BAR; PG8_MMA(1, 0, At, B0); PG8_MMA(1, 1, At, B1); PG8_BAR; PG8_SCHED;
.Lprio_skip_600:
.LBB0_600:
	s_add_u32 s24, s54, 0xfff80080
	s_addc_u32 s25, s55, -1
	s_add_i32 s46, 0, 0x10000
	s_cmp_eq_u32 s83, 28
	s_cselect_b32 s61, s2, s25
	s_cselect_b32 s60, s3, s24
	v_add_u32_e32 v142, s46, v145
	s_cselect_b32 s25, s15, s82
	s_cselect_b32 s24, s17, s79
	s_add_i32 s47, 0, 0x14000
	ds_read_b128 v[138:141], v142
	ds_read_b128 v[148:151], v142 offset:1024
	ds_read_b128 v[152:155], v142 offset:2048
	ds_read_b128 v[156:159], v142 offset:3072
	v_add_u32_e32 v142, s47, v145
	ds_read_b128 v[170:173], v142
	ds_read_b128 v[174:177], v142 offset:1024
	ds_read_b128 v[178:181], v142 offset:2048
	ds_read_b128 v[182:185], v142 offset:3072
	s_add_i32 m0, s43, 0xc000
	ds_read_b128 v[186:189], v147
	ds_read_b128 v[190:193], v147 offset:1024
	ds_read_b128 v[194:197], v147 offset:2048
	ds_read_b128 v[198:201], v147 offset:3072
	ds_read_b128 v[202:205], v147 offset:4096
	ds_read_b128 v[206:209], v147 offset:5120
	ds_read_b128 v[210:213], v147 offset:6144
	ds_read_b128 v[214:217], v147 offset:7168
	global_load_lds_dwordx4 v134, s[54:55]
	s_add_i32 m0, s43, 0xe000
	s_nop 0
	global_load_lds_dwordx4 v136, s[54:55]
	s_waitcnt vmcnt(8) lgkmcnt(0)
	s_barrier
	v_mfma_f32_16x16x32_bf16 v[124:127], v[138:141], v[186:189], v[124:127]
	v_mfma_f32_16x16x32_bf16 v[116:119], v[152:155], v[186:189], v[116:119]
	v_mfma_f32_16x16x32_bf16 v[108:111], v[138:141], v[194:197], v[108:111]
	v_mfma_f32_16x16x32_bf16 v[100:103], v[152:155], v[194:197], v[100:103]
	v_mfma_f32_16x16x32_bf16 v[92:95], v[138:141], v[202:205], v[92:95]
	v_mfma_f32_16x16x32_bf16 v[84:87], v[152:155], v[202:205], v[84:87]
	v_mfma_f32_16x16x32_bf16 v[76:79], v[138:141], v[210:213], v[76:79]
	v_mfma_f32_16x16x32_bf16 v[68:71], v[152:155], v[210:213], v[68:71]
	v_mfma_f32_16x16x32_bf16 v[124:127], v[148:151], v[190:193], v[124:127]
	v_mfma_f32_16x16x32_bf16 v[116:119], v[156:159], v[190:193], v[116:119]
	v_mfma_f32_16x16x32_bf16 v[108:111], v[148:151], v[198:201], v[108:111]
	v_mfma_f32_16x16x32_bf16 v[100:103], v[156:159], v[198:201], v[100:103]
	v_mfma_f32_16x16x32_bf16 v[92:95], v[148:151], v[206:209], v[92:95]
	v_mfma_f32_16x16x32_bf16 v[84:87], v[156:159], v[206:209], v[84:87]
	v_mfma_f32_16x16x32_bf16 v[76:79], v[148:151], v[214:217], v[76:79]
	v_mfma_f32_16x16x32_bf16 v[68:71], v[156:159], v[214:217], v[68:71]
	v_mfma_f32_16x16x32_bf16 v[120:123], v[170:173], v[186:189], v[120:123]
	v_mfma_f32_16x16x32_bf16 v[112:115], v[178:181], v[186:189], v[112:115]
	v_mfma_f32_16x16x32_bf16 v[104:107], v[170:173], v[194:197], v[104:107]
	v_mfma_f32_16x16x32_bf16 v[96:99], v[178:181], v[194:197], v[96:99]
	v_mfma_f32_16x16x32_bf16 v[88:91], v[170:173], v[202:205], v[88:91]
	v_mfma_f32_16x16x32_bf16 v[80:83], v[178:181], v[202:205], v[80:83]
	v_mfma_f32_16x16x32_bf16 v[72:75], v[170:173], v[210:213], v[72:75]
	v_mfma_f32_16x16x32_bf16 v[64:67], v[178:181], v[210:213], v[64:67]
	v_mfma_f32_16x16x32_bf16 v[120:123], v[174:177], v[190:193], v[120:123]
	v_mfma_f32_16x16x32_bf16 v[112:115], v[182:185], v[190:193], v[112:115]
	v_mfma_f32_16x16x32_bf16 v[104:107], v[174:177], v[198:201], v[104:107]
	v_mfma_f32_16x16x32_bf16 v[96:99], v[182:185], v[198:201], v[96:99]
	v_mfma_f32_16x16x32_bf16 v[88:91], v[174:177], v[206:209], v[88:91]
	v_mfma_f32_16x16x32_bf16 v[80:83], v[182:185], v[206:209], v[80:83]
	v_mfma_f32_16x16x32_bf16 v[72:75], v[174:177], v[214:217], v[72:75]
	v_mfma_f32_16x16x32_bf16 v[64:67], v[182:185], v[214:217], v[64:67]
	s_barrier
	s_add_i32 s46, s46, s62
	s_mov_b32 m0, s46
	ds_read_b128 v[186:189], v147 offset:16384
	ds_read_b128 v[190:193], v147 offset:17408
	ds_read_b128 v[194:197], v147 offset:18432
	ds_read_b128 v[198:201], v147 offset:19456
	ds_read_b128 v[202:205], v147 offset:20480
	ds_read_b128 v[206:209], v147 offset:21504
	ds_read_b128 v[210:213], v147 offset:22528
	ds_read_b128 v[214:217], v147 offset:23552
	global_load_lds_dwordx4 v160, s[24:25]
	s_add_i32 m0, s46, 0x2000
	s_add_u32 s88, s24, 0x80000
	s_addc_u32 s89, s25, 0
	s_add_i32 s46, s47, s62
	global_load_lds_dwordx4 v128, s[24:25]
	s_mov_b32 m0, s46
	s_nop 0
	global_load_lds_dwordx4 v160, s[88:89]
	s_add_i32 m0, s46, 0x2000
	s_nop 0
	global_load_lds_dwordx4 v128, s[88:89]
	s_mov_b32 m0, s43
	s_nop 0
	global_load_lds_dwordx4 v132, s[60:61]
	s_mov_b32 m0, s44
	s_nop 0
	global_load_lds_dwordx4 v130, s[60:61]
	s_waitcnt vmcnt(8) lgkmcnt(0)
	s_barrier
	v_mfma_f32_16x16x32_bf16 v[60:63], v[138:141], v[186:189], v[60:63]
	v_mfma_f32_16x16x32_bf16 v[52:55], v[152:155], v[186:189], v[52:55]
	v_mfma_f32_16x16x32_bf16 v[44:47], v[138:141], v[194:197], v[44:47]
	v_mfma_f32_16x16x32_bf16 v[36:39], v[152:155], v[194:197], v[36:39]
	v_mfma_f32_16x16x32_bf16 v[28:31], v[138:141], v[202:205], v[28:31]
	v_mfma_f32_16x16x32_bf16 v[20:23], v[152:155], v[202:205], v[20:23]
	v_mfma_f32_16x16x32_bf16 v[12:15], v[138:141], v[210:213], v[12:15]
	v_mfma_f32_16x16x32_bf16 v[4:7], v[152:155], v[210:213], v[4:7]
	v_mfma_f32_16x16x32_bf16 v[60:63], v[148:151], v[190:193], v[60:63]
	v_mfma_f32_16x16x32_bf16 v[52:55], v[156:159], v[190:193], v[52:55]
	v_mfma_f32_16x16x32_bf16 v[44:47], v[148:151], v[198:201], v[44:47]
	v_mfma_f32_16x16x32_bf16 v[36:39], v[156:159], v[198:201], v[36:39]
	v_mfma_f32_16x16x32_bf16 v[28:31], v[148:151], v[206:209], v[28:31]
	v_mfma_f32_16x16x32_bf16 v[20:23], v[156:159], v[206:209], v[20:23]
	v_mfma_f32_16x16x32_bf16 v[12:15], v[148:151], v[214:217], v[12:15]
	v_mfma_f32_16x16x32_bf16 v[4:7], v[156:159], v[214:217], v[4:7]
	v_mfma_f32_16x16x32_bf16 v[56:59], v[170:173], v[186:189], v[56:59]
	v_mfma_f32_16x16x32_bf16 v[48:51], v[178:181], v[186:189], v[48:51]
	v_mfma_f32_16x16x32_bf16 v[40:43], v[170:173], v[194:197], v[40:43]
	v_mfma_f32_16x16x32_bf16 v[32:35], v[178:181], v[194:197], v[32:35]
	v_mfma_f32_16x16x32_bf16 v[24:27], v[170:173], v[202:205], v[24:27]
	v_mfma_f32_16x16x32_bf16 v[16:19], v[178:181], v[202:205], v[16:19]
	v_mfma_f32_16x16x32_bf16 v[8:11], v[170:173], v[210:213], v[8:11]
	v_mfma_f32_16x16x32_bf16 v[0:3], v[178:181], v[210:213], v[0:3]
	v_mfma_f32_16x16x32_bf16 v[56:59], v[174:177], v[190:193], v[56:59]
	v_mfma_f32_16x16x32_bf16 v[48:51], v[182:185], v[190:193], v[48:51]
	v_mfma_f32_16x16x32_bf16 v[40:43], v[174:177], v[198:201], v[40:43]
	v_mfma_f32_16x16x32_bf16 v[32:35], v[182:185], v[198:201], v[32:35]
	v_mfma_f32_16x16x32_bf16 v[24:27], v[174:177], v[206:209], v[24:27]
	v_mfma_f32_16x16x32_bf16 v[16:19], v[182:185], v[206:209], v[16:19]
	v_mfma_f32_16x16x32_bf16 v[8:11], v[174:177], v[214:217], v[8:11]
	v_mfma_f32_16x16x32_bf16 v[0:3], v[182:185], v[214:217], v[0:3]
	s_barrier
; #define PG8_STAGE(bufoff, gbase, voff) do { _Pragma("unroll") for (int _i = 0; _i < 2; ++_i) \
;         __builtin_amdgcn_global_load_lds((const unsigned*)((const char*)(gbase) + (voff)[_i]), (LAS unsigned*)(lds + (bufoff) + ldsw + _i * 8192), 16, 0, 0); } while (0)
; #define PG8_LDA(dst, b, h) do { _Pragma("unroll") for (int m = 0; m < 4; ++m) _Pragma("unroll") for (int k = 0; k < 2; ++k) dst[m][k] = *(const LAS bf16x8*)(lds + PG8_SA(b, h) + aoff + m * 2048 + k * 1024); } while (0)
; #define PG8_LDB(dst, b, h) do { _Pragma("unroll") for (int n = 0; n < 2; ++n) _Pragma("unroll") for (int k = 0; k < 2; ++k) dst[n][k] = *(const LAS bf16x8*)(lds + PG8_SB(b, h) + boff + n * 2048 + k * 1024); } while (0)
; #define PG8_MMA(ai, bj, At, Bt) do { __builtin_amdgcn_s_setprio(1); _Pragma("unroll") for (int m = 0; m < 4; ++m) _Pragma("unroll") for (int n = 0; n < 2; ++n) _Pragma("unroll") for (int k = 0; k < 2; ++k) \
;         acc[ai][bj][m][n] = __builtin_amdgcn_mfma_f32_16x16x32_bf16(Bt[n][k], At[m][k], acc[ai][bj][m][n], 0, 0, 0); __builtin_amdgcn_s_setprio(0); } while (0)
; #define PG8_WAIT_V(n) asm volatile("s_waitcnt vmcnt(" #n ")" ::: "memory")
; #define PG8_WAIT_L(n) asm volatile("s_waitcnt lgkmcnt(" #n ")" ::: "memory")
; #define PG8_BAR __builtin_amdgcn_s_barrier()
; #define PG8_SCHED __builtin_amdgcn_sched_barrier(0)
; template <class Epi, class Sched, bool ALIGN_EPI = true, bool SP2 = true>
; __device__ __forceinline__ void gemm_phase(LAS unsigned char* lds, const Gemm g, const Sched& S, const Epi& E) {
;     ...
;             PG8_LDB(B0, 1, 0); PG8_LDB(B1, 1, 1); PG8_SCHED; PG8_LDA(At, 1, 0); PG8_STAGE(PG8_SA(0, 1), a2 + hstep, voffA);
;             PG8_WAIT_V(8); PG8_WAIT_L(0); PG8_BAR; PG8_MMA(0, 0, At, B0); PG8_MMA(0, 1, At, B1); PG8_BAR; PG8_SCHED;
;             PG8_LDA(At, 1, 1); PG8_STAGE(PG8_SB(1, 0), b3, voffB); PG8_STAGE(PG8_SB(1, 1), b3 + hstep, voffB); PG8_STAGE(PG8_SA(1, 0), a3, voffA);
;             PG8_WAIT_V(8); PG8_WAIT_L(0); PG8_BAR; PG8_MMA(1, 0, At, B0); PG8_MMA(1, 1, At, B1); PG8_BAR; PG8_SCHED;
;     ...
;         if constexpr (ALIGN_EPI) { if (wr == 0) PG8_BAR; }
	s_add_i32 s46, 0, 0x18000
	s_add_i32 s47, 0, 0x1c000
	v_add_u32_e32 v156, s46, v145
	v_add_u32_e32 v166, s47, v145
	ds_read_b128 v[138:141], v156
	ds_read_b128 v[148:151], v156 offset:1024
	ds_read_b128 v[152:155], v156 offset:2048
	ds_read_b128 v[156:159], v156 offset:3072
	ds_read_b128 v[170:173], v166
	ds_read_b128 v[174:177], v166 offset:1024
	ds_read_b128 v[178:181], v166 offset:2048
	ds_read_b128 v[182:185], v166 offset:3072
	s_add_u32 s60, s60, 0x80000
	s_addc_u32 s61, s61, 0
	s_mov_b32 m0, s45
	ds_read_b128 v[186:189], v147 offset:32768
	ds_read_b128 v[190:193], v147 offset:33792
	ds_read_b128 v[194:197], v147 offset:34816
	ds_read_b128 v[198:201], v147 offset:35840
	ds_read_b128 v[202:205], v147 offset:36864
	ds_read_b128 v[206:209], v147 offset:37888
	ds_read_b128 v[210:213], v147 offset:38912
	ds_read_b128 v[214:217], v147 offset:39936
	global_load_lds_dwordx4 v132, s[60:61]
	s_mov_b32 m0, s53
	s_nop 0
	global_load_lds_dwordx4 v130, s[60:61]
	s_waitcnt vmcnt(8) lgkmcnt(0)
	s_barrier
	v_mfma_f32_16x16x32_bf16 v[124:127], v[138:141], v[186:189], v[124:127]
	v_mfma_f32_16x16x32_bf16 v[116:119], v[152:155], v[186:189], v[116:119]
	v_mfma_f32_16x16x32_bf16 v[108:111], v[138:141], v[194:197], v[108:111]
	v_mfma_f32_16x16x32_bf16 v[100:103], v[152:155], v[194:197], v[100:103]
	v_mfma_f32_16x16x32_bf16 v[92:95], v[138:141], v[202:205], v[92:95]
	v_mfma_f32_16x16x32_bf16 v[84:87], v[152:155], v[202:205], v[84:87]
	v_mfma_f32_16x16x32_bf16 v[76:79], v[138:141], v[210:213], v[76:79]
	v_mfma_f32_16x16x32_bf16 v[68:71], v[152:155], v[210:213], v[68:71]
	v_mfma_f32_16x16x32_bf16 v[124:127], v[148:151], v[190:193], v[124:127]
	v_mfma_f32_16x16x32_bf16 v[116:119], v[156:159], v[190:193], v[116:119]
	v_mfma_f32_16x16x32_bf16 v[108:111], v[148:151], v[198:201], v[108:111]
	v_mfma_f32_16x16x32_bf16 v[100:103], v[156:159], v[198:201], v[100:103]
	v_mfma_f32_16x16x32_bf16 v[92:95], v[148:151], v[206:209], v[92:95]
	v_mfma_f32_16x16x32_bf16 v[84:87], v[156:159], v[206:209], v[84:87]
	v_mfma_f32_16x16x32_bf16 v[76:79], v[148:151], v[214:217], v[76:79]
	v_mfma_f32_16x16x32_bf16 v[68:71], v[156:159], v[214:217], v[68:71]
	v_mfma_f32_16x16x32_bf16 v[120:123], v[170:173], v[186:189], v[120:123]
	v_mfma_f32_16x16x32_bf16 v[112:115], v[178:181], v[186:189], v[112:115]
	v_mfma_f32_16x16x32_bf16 v[104:107], v[170:173], v[194:197], v[104:107]
	v_mfma_f32_16x16x32_bf16 v[96:99], v[178:181], v[194:197], v[96:99]
	v_mfma_f32_16x16x32_bf16 v[88:91], v[170:173], v[202:205], v[88:91]
	v_mfma_f32_16x16x32_bf16 v[80:83], v[178:181], v[202:205], v[80:83]
	v_mfma_f32_16x16x32_bf16 v[72:75], v[170:173], v[210:213], v[72:75]
	v_mfma_f32_16x16x32_bf16 v[64:67], v[178:181], v[210:213], v[64:67]
	v_mfma_f32_16x16x32_bf16 v[120:123], v[174:177], v[190:193], v[120:123]
	v_mfma_f32_16x16x32_bf16 v[112:115], v[182:185], v[190:193], v[112:115]
	v_mfma_f32_16x16x32_bf16 v[104:107], v[174:177], v[198:201], v[104:107]
	v_mfma_f32_16x16x32_bf16 v[96:99], v[182:185], v[198:201], v[96:99]
	v_mfma_f32_16x16x32_bf16 v[88:91], v[174:177], v[206:209], v[88:91]
	v_mfma_f32_16x16x32_bf16 v[80:83], v[182:185], v[206:209], v[80:83]
	v_mfma_f32_16x16x32_bf16 v[72:75], v[174:177], v[214:217], v[72:75]
	v_mfma_f32_16x16x32_bf16 v[64:67], v[182:185], v[214:217], v[64:67]
	s_barrier
	s_add_i32 s46, s46, s62
	s_mov_b32 m0, s46
	ds_read_b128 v[186:189], v147 offset:49152
	ds_read_b128 v[190:193], v147 offset:50176
	ds_read_b128 v[194:197], v147 offset:51200
	ds_read_b128 v[198:201], v147 offset:52224
	ds_read_b128 v[202:205], v147 offset:53248
	ds_read_b128 v[206:209], v147 offset:54272
	ds_read_b128 v[210:213], v147 offset:55296
	ds_read_b128 v[214:217], v147 offset:56320
	s_add_u32 s98, s24, 0x80
	s_addc_u32 s99, s25, 0
	global_load_lds_dwordx4 v160, s[98:99]
	s_add_i32 m0, s46, 0x2000
	s_add_u32 s24, s24, 0x80080
	s_addc_u32 s25, s25, 0
	s_add_i32 s46, s47, s62
	global_load_lds_dwordx4 v128, s[98:99]
	s_mov_b32 m0, s46
	s_nop 0
	global_load_lds_dwordx4 v160, s[24:25]
	s_add_i32 m0, s46, 0x2000
	s_nop 0
	global_load_lds_dwordx4 v128, s[24:25]
	s_mov_b32 m0, s63
	s_nop 0
	s_add_u32 s98, s60, 0xfff80080
	s_addc_u32 s99, s61, -1
	global_load_lds_dwordx4 v132, s[98:99]
	s_mov_b32 m0, s66
	s_nop 0
	global_load_lds_dwordx4 v130, s[98:99]
	s_waitcnt vmcnt(8) lgkmcnt(0)
	s_barrier
	v_mfma_f32_16x16x32_bf16 v[60:63], v[138:141], v[186:189], v[60:63]
	v_mfma_f32_16x16x32_bf16 v[52:55], v[152:155], v[186:189], v[52:55]
	v_mfma_f32_16x16x32_bf16 v[44:47], v[138:141], v[194:197], v[44:47]
	v_mfma_f32_16x16x32_bf16 v[36:39], v[152:155], v[194:197], v[36:39]
	v_mfma_f32_16x16x32_bf16 v[28:31], v[138:141], v[202:205], v[28:31]
	v_mfma_f32_16x16x32_bf16 v[20:23], v[152:155], v[202:205], v[20:23]
	v_mfma_f32_16x16x32_bf16 v[12:15], v[138:141], v[210:213], v[12:15]
	v_mfma_f32_16x16x32_bf16 v[4:7], v[152:155], v[210:213], v[4:7]
	v_mfma_f32_16x16x32_bf16 v[60:63], v[148:151], v[190:193], v[60:63]
	v_mfma_f32_16x16x32_bf16 v[52:55], v[156:159], v[190:193], v[52:55]
	v_mfma_f32_16x16x32_bf16 v[44:47], v[148:151], v[198:201], v[44:47]
	v_mfma_f32_16x16x32_bf16 v[36:39], v[156:159], v[198:201], v[36:39]
	v_mfma_f32_16x16x32_bf16 v[28:31], v[148:151], v[206:209], v[28:31]
	v_mfma_f32_16x16x32_bf16 v[20:23], v[156:159], v[206:209], v[20:23]
	v_mfma_f32_16x16x32_bf16 v[12:15], v[148:151], v[214:217], v[12:15]
	v_mfma_f32_16x16x32_bf16 v[4:7], v[156:159], v[214:217], v[4:7]
	v_mfma_f32_16x16x32_bf16 v[56:59], v[170:173], v[186:189], v[56:59]
	v_mfma_f32_16x16x32_bf16 v[48:51], v[178:181], v[186:189], v[48:51]
	v_mfma_f32_16x16x32_bf16 v[40:43], v[170:173], v[194:197], v[40:43]
	v_mfma_f32_16x16x32_bf16 v[32:35], v[178:181], v[194:197], v[32:35]
	v_mfma_f32_16x16x32_bf16 v[24:27], v[170:173], v[202:205], v[24:27]
	v_mfma_f32_16x16x32_bf16 v[16:19], v[178:181], v[202:205], v[16:19]
	v_mfma_f32_16x16x32_bf16 v[8:11], v[170:173], v[210:213], v[8:11]
	v_mfma_f32_16x16x32_bf16 v[0:3], v[178:181], v[210:213], v[0:3]
	v_mfma_f32_16x16x32_bf16 v[56:59], v[174:177], v[190:193], v[56:59]
	v_mfma_f32_16x16x32_bf16 v[48:51], v[182:185], v[190:193], v[48:51]
	v_mfma_f32_16x16x32_bf16 v[40:43], v[174:177], v[198:201], v[40:43]
	v_mfma_f32_16x16x32_bf16 v[32:35], v[182:185], v[198:201], v[32:35]
	v_mfma_f32_16x16x32_bf16 v[24:27], v[174:177], v[206:209], v[24:27]
	v_mfma_f32_16x16x32_bf16 v[16:19], v[182:185], v[206:209], v[16:19]
	v_mfma_f32_16x16x32_bf16 v[8:11], v[174:177], v[214:217], v[8:11]
	v_mfma_f32_16x16x32_bf16 v[0:3], v[182:185], v[214:217], v[0:3]
	s_barrier
	s_add_i32 s83, s83, 2
	s_add_u32 s54, s54, 0x100
	s_addc_u32 s55, s55, 0
	s_add_u32 s79, s79, 0x100
	s_addc_u32 s82, s82, 0
	s_cmp_gt_u32 s83, 29
	s_cbranch_scc0 .LBB0_600
	s_setprio 0
	s_and_b64 vcc, exec, s[10:11]
	s_cbranch_vccz .LBB0_603
	s_barrier
